# prune pad-row blocks from the Gate1/Gate2/SwiGLU sample-row (skinny) epilogues: only the 32 real rows are processed
# baseline (speedup 1.0000x reference)
; #define LAS __attribute__((address_space(3)))
; #define SCHED_BAR() __builtin_amdgcn_sched_barrier(0)
; template <class Epi>
; __device__ __forceinline__ void skinny_phase(LAS unsigned char* lds, const pg8::Gemm g, const Epi& E, int G, int bx) {
;     ...
;         LAS f32x4* red = (LAS f32x4*)lds;
;         __syncthreads();
; #pragma unroll
;         for (int b = 0; b < 2; ++b)
; #pragma unroll
;             for (int m = 0; m < 2; ++m)
; #pragma unroll
;                 for (int n = 0; n < 2; ++n) red[(((b * 2 + m) * 2 + n) * 8 + wid) * 64 + lane] = a8[b][m][n];
;         __syncthreads();
;         if (wid == 0) {
;             Acc acc;
; #pragma unroll
;             for (int a = 0; a < 2; ++a)
; #pragma unroll
;                 for (int b = 0; b < 2; ++b)
; #pragma unroll
;                     for (int m = 0; m < 4; ++m)
; #pragma unroll
;                         for (int n = 0; n < 2; ++n) acc[a][b][m][n] = (f32x4){0.f, 0.f, 0.f, 0.f};
; #pragma unroll
;             for (int b = 0; b < 2; ++b)
; #pragma unroll
;                 for (int m = 0; m < 2; ++m)
; #pragma unroll
;                     for (int n = 0; n < 2; ++n) { f32x4 t = {0.f, 0.f, 0.f, 0.f};
; #pragma unroll
;                         for (int w8 = 0; w8 < 8; ++w8) t += red[(((b * 2 + m) * 2 + n) * 8 + w8) * 64 + lane];
;                         acc[0][b][m][n] = t; SCHED_BAR(); }
.LBB0_471:
	s_and_b64 vcc, exec, s[10:11]
	s_barrier
	ds_write_b128 v168, v[20:23]
	ds_write_b128 v168, v[28:31] offset:8192
	ds_write_b128 v168, v[4:7] offset:16384
	ds_write_b128 v168, v[16:19] offset:24576
	ds_write_b128 v168, v[12:15] offset:32768
	ds_write_b128 v168, v[24:27] offset:40960
	ds_write_b128 v168, v[0:3] offset:49152
	ds_write_b128 v168, v[8:11] offset:57344
	s_waitcnt lgkmcnt(0)
	s_barrier
	s_cbranch_vccz .LBB0_461
	ds_read_b128 v[0:3], v167
	ds_read_b128 v[4:7], v167 offset:1024
	ds_read_b128 v[8:11], v167 offset:2048
	ds_read_b128 v[12:15], v167 offset:3072
	s_waitcnt lgkmcnt(3)
	v_pk_add_f32 v[2:3], v[2:3], 0 op_sel_hi:[1,0]
	v_pk_add_f32 v[0:1], v[0:1], 0 op_sel_hi:[1,0]
	s_waitcnt lgkmcnt(2)
	v_pk_add_f32 v[2:3], v[2:3], v[6:7]
	v_pk_add_f32 v[4:5], v[0:1], v[4:5]
	s_waitcnt lgkmcnt(1)
	v_pk_add_f32 v[6:7], v[2:3], v[10:11]
	ds_read_b128 v[0:3], v167 offset:4096
	v_pk_add_f32 v[4:5], v[4:5], v[8:9]
	s_waitcnt lgkmcnt(1)
	v_pk_add_f32 v[8:9], v[6:7], v[14:15]
	v_pk_add_f32 v[12:13], v[4:5], v[12:13]
	ds_read_b128 v[4:7], v167 offset:5120
	s_waitcnt lgkmcnt(1)
	v_pk_add_f32 v[14:15], v[8:9], v[2:3]
	ds_read_b128 v[8:11], v167 offset:6144
	v_pk_add_f32 v[12:13], v[12:13], v[0:1]
	ds_read_b128 v[0:3], v167 offset:7168
	s_waitcnt lgkmcnt(2)
	v_pk_add_f32 v[6:7], v[14:15], v[6:7]
	v_pk_add_f32 v[4:5], v[12:13], v[4:5]
	s_waitcnt lgkmcnt(1)
	v_pk_add_f32 v[6:7], v[6:7], v[10:11]
	v_pk_add_f32 v[4:5], v[4:5], v[8:9]
	s_waitcnt lgkmcnt(0)
	v_pk_add_f32 v[74:75], v[6:7], v[2:3]
	v_pk_add_f32 v[72:73], v[4:5], v[0:1]
	ds_read_b128 v[0:3], v167 offset:8192
	ds_read_b128 v[4:7], v167 offset:9216
	ds_read_b128 v[8:11], v167 offset:10240
	ds_read_b128 v[12:15], v167 offset:11264
	s_waitcnt lgkmcnt(3)
	v_pk_add_f32 v[2:3], v[2:3], 0 op_sel_hi:[1,0]
	v_pk_add_f32 v[0:1], v[0:1], 0 op_sel_hi:[1,0]
	s_waitcnt lgkmcnt(2)
	v_pk_add_f32 v[2:3], v[2:3], v[6:7]
	v_pk_add_f32 v[4:5], v[0:1], v[4:5]
	s_waitcnt lgkmcnt(1)
	v_pk_add_f32 v[6:7], v[2:3], v[10:11]
	ds_read_b128 v[0:3], v167 offset:12288
	v_pk_add_f32 v[4:5], v[4:5], v[8:9]
	s_waitcnt lgkmcnt(1)
	v_pk_add_f32 v[8:9], v[6:7], v[14:15]
	v_pk_add_f32 v[12:13], v[4:5], v[12:13]
	ds_read_b128 v[4:7], v167 offset:13312
	s_waitcnt lgkmcnt(1)
	v_pk_add_f32 v[14:15], v[8:9], v[2:3]
	ds_read_b128 v[8:11], v167 offset:14336
	v_pk_add_f32 v[12:13], v[12:13], v[0:1]
	ds_read_b128 v[0:3], v167 offset:15360
	s_waitcnt lgkmcnt(2)
	v_pk_add_f32 v[6:7], v[14:15], v[6:7]
	v_pk_add_f32 v[4:5], v[12:13], v[4:5]
	s_waitcnt lgkmcnt(1)
	v_pk_add_f32 v[6:7], v[6:7], v[10:11]
	v_pk_add_f32 v[4:5], v[4:5], v[8:9]
	s_waitcnt lgkmcnt(0)
	v_pk_add_f32 v[78:79], v[6:7], v[2:3]
	v_pk_add_f32 v[76:77], v[4:5], v[0:1]
	ds_read_b128 v[0:3], v167 offset:16384
	ds_read_b128 v[4:7], v167 offset:17408
	ds_read_b128 v[8:11], v167 offset:18432
	ds_read_b128 v[12:15], v167 offset:19456
	s_waitcnt lgkmcnt(3)
	v_pk_add_f32 v[2:3], v[2:3], 0 op_sel_hi:[1,0]
	v_pk_add_f32 v[0:1], v[0:1], 0 op_sel_hi:[1,0]
	s_waitcnt lgkmcnt(2)
	v_pk_add_f32 v[2:3], v[2:3], v[6:7]
	v_pk_add_f32 v[4:5], v[0:1], v[4:5]
	s_waitcnt lgkmcnt(1)
	v_pk_add_f32 v[6:7], v[2:3], v[10:11]
	ds_read_b128 v[0:3], v167 offset:20480
	v_pk_add_f32 v[4:5], v[4:5], v[8:9]
	s_waitcnt lgkmcnt(1)
	v_pk_add_f32 v[8:9], v[6:7], v[14:15]
	v_pk_add_f32 v[12:13], v[4:5], v[12:13]
	ds_read_b128 v[4:7], v167 offset:21504
	s_waitcnt lgkmcnt(1)
	v_pk_add_f32 v[14:15], v[8:9], v[2:3]
	ds_read_b128 v[8:11], v167 offset:22528
	v_pk_add_f32 v[12:13], v[12:13], v[0:1]
	ds_read_b128 v[0:3], v167 offset:23552
	s_waitcnt lgkmcnt(2)
	v_pk_add_f32 v[6:7], v[14:15], v[6:7]
	v_pk_add_f32 v[4:5], v[12:13], v[4:5]
	s_waitcnt lgkmcnt(1)
	v_pk_add_f32 v[6:7], v[6:7], v[10:11]
	v_pk_add_f32 v[4:5], v[4:5], v[8:9]
	s_waitcnt lgkmcnt(0)
	v_pk_add_f32 v[62:63], v[6:7], v[2:3]
	v_pk_add_f32 v[60:61], v[4:5], v[0:1]
	ds_read_b128 v[0:3], v167 offset:24576
	ds_read_b128 v[4:7], v167 offset:25600
	ds_read_b128 v[8:11], v167 offset:26624
	ds_read_b128 v[12:15], v167 offset:27648
	s_waitcnt lgkmcnt(3)
	v_pk_add_f32 v[2:3], v[2:3], 0 op_sel_hi:[1,0]
	v_pk_add_f32 v[0:1], v[0:1], 0 op_sel_hi:[1,0]
	s_waitcnt lgkmcnt(2)
	v_pk_add_f32 v[2:3], v[2:3], v[6:7]
	v_pk_add_f32 v[4:5], v[0:1], v[4:5]
	s_waitcnt lgkmcnt(1)
	v_pk_add_f32 v[6:7], v[2:3], v[10:11]
	ds_read_b128 v[0:3], v167 offset:28672
	v_pk_add_f32 v[4:5], v[4:5], v[8:9]
	s_waitcnt lgkmcnt(1)
	v_pk_add_f32 v[8:9], v[6:7], v[14:15]
	v_pk_add_f32 v[12:13], v[4:5], v[12:13]
	ds_read_b128 v[4:7], v167 offset:29696
	s_waitcnt lgkmcnt(1)
	v_pk_add_f32 v[14:15], v[8:9], v[2:3]
	ds_read_b128 v[8:11], v167 offset:30720
	v_pk_add_f32 v[12:13], v[12:13], v[0:1]
	ds_read_b128 v[0:3], v167 offset:31744
	s_waitcnt lgkmcnt(2)
	v_pk_add_f32 v[6:7], v[14:15], v[6:7]
	v_pk_add_f32 v[4:5], v[12:13], v[4:5]
	s_waitcnt lgkmcnt(1)
	v_pk_add_f32 v[6:7], v[6:7], v[10:11]
	v_pk_add_f32 v[4:5], v[4:5], v[8:9]
	s_waitcnt lgkmcnt(0)
	v_pk_add_f32 v[70:71], v[6:7], v[2:3]
	v_pk_add_f32 v[68:69], v[4:5], v[0:1]
	ds_read_b128 v[0:3], v167 offset:32768
	ds_read_b128 v[4:7], v167 offset:33792
	ds_read_b128 v[8:11], v167 offset:34816
	ds_read_b128 v[12:15], v167 offset:35840
	s_waitcnt lgkmcnt(3)
	v_pk_add_f32 v[2:3], v[2:3], 0 op_sel_hi:[1,0]
	v_pk_add_f32 v[0:1], v[0:1], 0 op_sel_hi:[1,0]
	s_waitcnt lgkmcnt(2)
	v_pk_add_f32 v[2:3], v[2:3], v[6:7]
	v_pk_add_f32 v[4:5], v[0:1], v[4:5]
	s_waitcnt lgkmcnt(1)
	v_pk_add_f32 v[6:7], v[2:3], v[10:11]
	ds_read_b128 v[0:3], v167 offset:36864
	v_pk_add_f32 v[4:5], v[4:5], v[8:9]
	s_waitcnt lgkmcnt(1)
	v_pk_add_f32 v[8:9], v[6:7], v[14:15]
	v_pk_add_f32 v[12:13], v[4:5], v[12:13]
	ds_read_b128 v[4:7], v167 offset:37888
	s_waitcnt lgkmcnt(1)
; #define SCHED_BAR() __builtin_amdgcn_sched_barrier(0)
;     __device__ __forceinline__ void operator()(const Acc& acc, const Unit& u, int wr, int wc, int fr, int fq) const {
;     ...
; #pragma unroll
;         for (int ai = 0; ai < 2; ++ai)
; #pragma unroll
;             for (int m = 0; m < 4; ++m) ssv[ai][m] = ss[u.pm * 256 + ai * 128 + wr * 64 + m * 16 + fr];
; template <class Epi>
; __device__ __forceinline__ void skinny_phase(LAS unsigned char* lds, const pg8::Gemm g, const Epi& E, int G, int bx) {
;     ...
;                         for (int n = 0; n < 2; ++n) acc[a][b][m][n] = (f32x4){0.f, 0.f, 0.f, 0.f};
; #pragma unroll
;             for (int b = 0; b < 2; ++b)
; #pragma unroll
;                 for (int m = 0; m < 2; ++m)
; #pragma unroll
;                     for (int n = 0; n < 2; ++n) { f32x4 t = {0.f, 0.f, 0.f, 0.f};
; #pragma unroll
;                         for (int w8 = 0; w8 < 8; ++w8) t += red[(((b * 2 + m) * 2 + n) * 8 + w8) * 64 + lane];
;                         acc[0][b][m][n] = t; SCHED_BAR(); }
	v_pk_add_f32 v[14:15], v[8:9], v[2:3]
	ds_read_b128 v[8:11], v167 offset:38912
	v_pk_add_f32 v[12:13], v[12:13], v[0:1]
	ds_read_b128 v[0:3], v167 offset:39936
	s_waitcnt lgkmcnt(2)
	v_pk_add_f32 v[6:7], v[14:15], v[6:7]
	v_pk_add_f32 v[4:5], v[12:13], v[4:5]
	s_waitcnt lgkmcnt(1)
	v_pk_add_f32 v[6:7], v[6:7], v[10:11]
	v_pk_add_f32 v[4:5], v[4:5], v[8:9]
	s_waitcnt lgkmcnt(0)
	v_pk_add_f32 v[122:123], v[6:7], v[2:3]
	v_pk_add_f32 v[120:121], v[4:5], v[0:1]
	ds_read_b128 v[0:3], v167 offset:40960
	ds_read_b128 v[4:7], v167 offset:41984
	ds_read_b128 v[8:11], v167 offset:43008
	ds_read_b128 v[12:15], v167 offset:44032
	s_waitcnt lgkmcnt(3)
	v_pk_add_f32 v[2:3], v[2:3], 0 op_sel_hi:[1,0]
	v_pk_add_f32 v[0:1], v[0:1], 0 op_sel_hi:[1,0]
	s_waitcnt lgkmcnt(2)
	v_pk_add_f32 v[2:3], v[2:3], v[6:7]
	v_pk_add_f32 v[4:5], v[0:1], v[4:5]
	s_waitcnt lgkmcnt(1)
	v_pk_add_f32 v[6:7], v[2:3], v[10:11]
	ds_read_b128 v[0:3], v167 offset:45056
	v_pk_add_f32 v[4:5], v[4:5], v[8:9]
	s_waitcnt lgkmcnt(1)
	v_pk_add_f32 v[8:9], v[6:7], v[14:15]
	v_pk_add_f32 v[12:13], v[4:5], v[12:13]
	ds_read_b128 v[4:7], v167 offset:46080
	s_waitcnt lgkmcnt(1)
	v_pk_add_f32 v[14:15], v[8:9], v[2:3]
	ds_read_b128 v[8:11], v167 offset:47104
	v_pk_add_f32 v[12:13], v[12:13], v[0:1]
	ds_read_b128 v[0:3], v167 offset:48128
	s_waitcnt lgkmcnt(2)
	v_pk_add_f32 v[6:7], v[14:15], v[6:7]
	v_pk_add_f32 v[4:5], v[12:13], v[4:5]
	s_waitcnt lgkmcnt(1)
	v_pk_add_f32 v[6:7], v[6:7], v[10:11]
	v_pk_add_f32 v[4:5], v[4:5], v[8:9]
	s_waitcnt lgkmcnt(0)
	v_pk_add_f32 v[126:127], v[6:7], v[2:3]
	v_pk_add_f32 v[124:125], v[4:5], v[0:1]
	ds_read_b128 v[0:3], v167 offset:49152
	ds_read_b128 v[4:7], v167 offset:50176
	ds_read_b128 v[8:11], v167 offset:51200
	ds_read_b128 v[12:15], v167 offset:52224
	s_waitcnt lgkmcnt(3)
	v_pk_add_f32 v[2:3], v[2:3], 0 op_sel_hi:[1,0]
	v_pk_add_f32 v[0:1], v[0:1], 0 op_sel_hi:[1,0]
	s_waitcnt lgkmcnt(2)
	v_pk_add_f32 v[2:3], v[2:3], v[6:7]
	v_pk_add_f32 v[4:5], v[0:1], v[4:5]
	s_waitcnt lgkmcnt(1)
	v_pk_add_f32 v[6:7], v[2:3], v[10:11]
	ds_read_b128 v[0:3], v167 offset:53248
	v_pk_add_f32 v[4:5], v[4:5], v[8:9]
	s_waitcnt lgkmcnt(1)
	v_pk_add_f32 v[8:9], v[6:7], v[14:15]
	v_pk_add_f32 v[12:13], v[4:5], v[12:13]
	ds_read_b128 v[4:7], v167 offset:54272
	s_waitcnt lgkmcnt(1)
	v_pk_add_f32 v[14:15], v[8:9], v[2:3]
	ds_read_b128 v[8:11], v167 offset:55296
	v_pk_add_f32 v[12:13], v[12:13], v[0:1]
	ds_read_b128 v[0:3], v167 offset:56320
	s_waitcnt lgkmcnt(2)
	v_pk_add_f32 v[6:7], v[14:15], v[6:7]
	v_pk_add_f32 v[4:5], v[12:13], v[4:5]
	s_waitcnt lgkmcnt(1)
	v_pk_add_f32 v[6:7], v[6:7], v[10:11]
	v_pk_add_f32 v[4:5], v[4:5], v[8:9]
	s_waitcnt lgkmcnt(0)
	v_pk_add_f32 v[110:111], v[6:7], v[2:3]
	v_pk_add_f32 v[108:109], v[4:5], v[0:1]
	ds_read_b128 v[0:3], v167 offset:57344
	ds_read_b128 v[4:7], v167 offset:58368
	ds_read_b128 v[8:11], v167 offset:59392
	ds_read_b128 v[12:15], v167 offset:60416
	s_waitcnt lgkmcnt(3)
	v_pk_add_f32 v[2:3], v[2:3], 0 op_sel_hi:[1,0]
	v_pk_add_f32 v[0:1], v[0:1], 0 op_sel_hi:[1,0]
	s_waitcnt lgkmcnt(2)
	v_pk_add_f32 v[2:3], v[2:3], v[6:7]
	v_pk_add_f32 v[4:5], v[0:1], v[4:5]
	s_waitcnt lgkmcnt(1)
	v_pk_add_f32 v[6:7], v[2:3], v[10:11]
	ds_read_b128 v[0:3], v167 offset:61440
	v_pk_add_f32 v[4:5], v[4:5], v[8:9]
	s_waitcnt lgkmcnt(1)
	v_pk_add_f32 v[8:9], v[6:7], v[14:15]
	v_pk_add_f32 v[12:13], v[4:5], v[12:13]
	ds_read_b128 v[4:7], v167 offset:62464
	s_waitcnt lgkmcnt(1)
	v_pk_add_f32 v[14:15], v[8:9], v[2:3]
	ds_read_b128 v[8:11], v167 offset:63488
	v_pk_add_f32 v[12:13], v[12:13], v[0:1]
	ds_read_b128 v[0:3], v167 offset:64512
	s_waitcnt lgkmcnt(2)
	v_pk_add_f32 v[6:7], v[14:15], v[6:7]
	v_pk_add_f32 v[4:5], v[12:13], v[4:5]
	s_waitcnt lgkmcnt(1)
	v_pk_add_f32 v[6:7], v[6:7], v[10:11]
	v_pk_add_f32 v[4:5], v[4:5], v[8:9]
	s_waitcnt lgkmcnt(0)
	v_pk_add_f32 v[114:115], v[6:7], v[2:3]
	v_pk_add_f32 v[112:113], v[4:5], v[0:1]
	s_mov_b32 s5, s4
	s_mov_b32 s6, s4
	s_mov_b32 s7, s4
	v_mov_b64_e32 v[0:1], s[4:5]
	v_mov_b64_e32 v[106:107], s[6:7]
	v_mov_b64_e32 v[98:99], s[6:7]
	v_mov_b64_e32 v[90:91], s[6:7]
	v_mov_b64_e32 v[82:83], s[6:7]
	v_mov_b64_e32 v[118:119], s[6:7]
	v_mov_b64_e32 v[102:103], s[6:7]
	v_mov_b64_e32 v[94:95], s[6:7]
	v_mov_b64_e32 v[86:87], s[6:7]
	v_mov_b64_e32 v[58:59], s[6:7]
	v_mov_b64_e32 v[50:51], s[6:7]
	v_mov_b64_e32 v[42:43], s[6:7]
	v_mov_b64_e32 v[34:35], s[6:7]
	v_mov_b64_e32 v[26:27], s[6:7]
	v_mov_b64_e32 v[18:19], s[6:7]
	v_mov_b64_e32 v[10:11], s[6:7]
	v_mov_b64_e32 v[4:5], s[4:5]
	v_mov_b64_e32 v[66:67], s[6:7]
	v_mov_b64_e32 v[54:55], s[6:7]
	v_mov_b64_e32 v[46:47], s[6:7]
	v_mov_b64_e32 v[38:39], s[6:7]
	v_mov_b64_e32 v[30:31], s[6:7]
	v_mov_b64_e32 v[22:23], s[6:7]
	v_mov_b64_e32 v[14:15], s[6:7]
	v_mov_b64_e32 v[2:3], s[6:7]
	v_mov_b64_e32 v[104:105], s[4:5]
	v_mov_b64_e32 v[96:97], s[4:5]
	v_mov_b64_e32 v[88:89], s[4:5]
	v_mov_b64_e32 v[80:81], s[4:5]
	v_mov_b64_e32 v[116:117], s[4:5]
	v_mov_b64_e32 v[100:101], s[4:5]
	v_mov_b64_e32 v[92:93], s[4:5]
	v_mov_b64_e32 v[84:85], s[4:5]
	v_mov_b64_e32 v[56:57], s[4:5]
	v_mov_b64_e32 v[48:49], s[4:5]
	v_mov_b64_e32 v[40:41], s[4:5]
	v_mov_b64_e32 v[32:33], s[4:5]
	v_mov_b64_e32 v[24:25], s[4:5]
	v_mov_b64_e32 v[16:17], s[4:5]
	v_mov_b64_e32 v[8:9], s[4:5]
	v_mov_b64_e32 v[6:7], s[6:7]
	v_mov_b64_e32 v[64:65], s[4:5]
	v_mov_b64_e32 v[52:53], s[4:5]
	v_mov_b64_e32 v[44:45], s[4:5]
	v_mov_b64_e32 v[36:37], s[4:5]
	v_mov_b64_e32 v[28:29], s[4:5]
	v_mov_b64_e32 v[20:21], s[4:5]
	v_mov_b64_e32 v[12:13], s[4:5]
	global_load_dword v174, v[130:131], off
	global_load_dword v175, v[132:133], off
	s_waitcnt vmcnt(1)
; __device__ __forceinline__ unsigned cvt_pk_bf16(float lo, float hi) { unsigned r; asm volatile("v_cvt_pk_bf16_f32 %0, %1, %2" : "=v"(r) : "v"(lo), "v"(hi)); return r; }
; __device__ __forceinline__ float fast_sigmoid(float a) { return __builtin_amdgcn_rcpf(1.0f + __expf(-a)); }
;     __device__ __forceinline__ void operator()(const Acc& acc, const Unit& u, int wr, int wc, int fr, int fq) const {
;     ...
; #pragma unroll
;         for (int ai = 0; ai < 2; ++ai)
; #pragma unroll
;             for (int m = 0; m < 4; ++m) {
;                 const int row = u.pm * 256 + ai * 128 + wr * 64 + m * 16 + fr;
;                 const float rs = rsqrtf(ssv[ai][m] * (1.0f / DM) + EPS);
;                 bf16_t* dst = act + ((size_t)((row >> 8) * (DFF / 64) + u.pn * 2 + (wc >> 1)) * 256 + (row & 255)) * 64 + (wc & 1) * 32 + fq * 8;
;                 u32x4 w;
; #pragma unroll
;                 for (int n = 0; n < 2; ++n) {
;                     const f32x4 a = acc[ai][0][m][n] * rs, b = acc[ai][1][m][n] * rs; f32x4 v;
; #pragma unroll
;                     for (int j = 0; j < 4; ++j) v[j] = a[j] * fast_sigmoid(a[j]) * b[j];
;                     if (n == 0) { w.x = cvt_pk_bf16(v[0], v[1]); w.y = cvt_pk_bf16(v[2], v[3]); } else { w.z = cvt_pk_bf16(v[0], v[1]); w.w = cvt_pk_bf16(v[2], v[3]); }
;                 }
;                 *(u32x4*)dst = w;
	v_fmamk_f32 v174, v174, 0x3a800000, v169
	v_mul_f32_e32 v176, 0x4b800000, v174
	v_cmp_gt_f32_e32 vcc, s16, v174
	v_mov_b32_e32 v178, v123
	v_mov_b32_e32 v179, v75
	v_cndmask_b32_e32 v174, v174, v176, vcc
	v_rsq_f32_e32 v174, v174
	s_lshl_b32 s0, s0, 1
	s_lshr_b32 s1, s1, 1
	v_mov_b32_e32 v123, v74
	v_mul_f32_e32 v176, 0x45800000, v174
	v_cndmask_b32_e32 v174, v174, v176, vcc
	s_waitcnt vmcnt(0)
	v_pk_mul_f32 v[178:179], v[178:179], v[174:175] op_sel_hi:[1,0]
	s_or_b32 s0, s0, s1
	v_mul_f32_e32 v75, 0xbfb8aa3b, v179
	v_exp_f32_e32 v182, v75
	v_pk_mul_f32 v[74:75], v[122:123], v[174:175] op_sel_hi:[1,0]
	s_addk_i32 s0, 0x1600
	v_mul_f32_e32 v122, 0xbfb8aa3b, v75
	s_ashr_i32 s1, s0, 31
	v_exp_f32_e32 v183, v122
	s_and_b32 s5, s29, 32
	s_lshl_b64 s[0:1], s[0:1], 15
	v_lshl_add_u64 v[176:177], v[162:163], 0, s[0:1]
	s_lshl_b32 s0, s5, 1
	s_mov_b32 s1, s4
	v_lshl_add_u64 v[122:123], v[176:177], 0, s[0:1]
	v_add_f32_e32 v176, 1.0, v182
	v_rcp_f32_e32 v182, v176
	v_add_f32_e32 v176, 1.0, v183
	v_rcp_f32_e32 v183, v176
	v_mov_b32_e32 v176, v121
	v_mov_b32_e32 v177, v73
	v_pk_mul_f32 v[176:177], v[176:177], v[174:175] op_sel_hi:[1,0]
	v_mul_f32_e32 v121, v179, v182
	v_mul_f32_e32 v73, 0xbfb8aa3b, v177
	v_exp_f32_e32 v73, v73
	v_mul_f32_e32 v178, v178, v121
	v_mov_b32_e32 v121, v72
	v_mul_f32_e32 v75, v75, v183
	v_add_f32_e32 v73, 1.0, v73
	v_rcp_f32_e32 v179, v73
	v_pk_mul_f32 v[72:73], v[120:121], v[174:175] op_sel_hi:[1,0]
	v_mul_f32_e32 v182, v74, v75
	v_mul_f32_e32 v120, 0xbfb8aa3b, v73
	v_exp_f32_e32 v120, v120
	v_mul_f32_e32 v74, v177, v179
	v_mul_f32_e32 v176, v176, v74
	v_mov_b32_e32 v75, v79
	v_add_f32_e32 v74, 1.0, v120
	v_rcp_f32_e32 v177, v74
	v_mov_b32_e32 v74, v127
	v_pk_mul_f32 v[120:121], v[74:75], v[174:175] op_sel_hi:[1,0]
	v_mov_b32_e32 v127, v78
	v_mul_f32_e32 v74, 0xbfb8aa3b, v121
	v_exp_f32_e32 v75, v74
	v_mul_f32_e32 v73, v73, v177
	v_mul_f32_e32 v72, v72, v73
	v_cvt_pk_bf16_f32 v74, v72, v176
	v_add_f32_e32 v72, 1.0, v75
	v_rcp_f32_e32 v79, v72
	v_pk_mul_f32 v[72:73], v[126:127], v[174:175] op_sel_hi:[1,0]
	v_mul_f32_e32 v79, v121, v79
	v_mul_f32_e32 v75, 0xbfb8aa3b, v73
	v_exp_f32_e32 v78, v75
	v_mul_f32_e32 v120, v120, v79
	v_mov_b32_e32 v79, v77
	v_cvt_pk_bf16_f32 v75, v182, v178
	v_add_f32_e32 v78, 1.0, v78
	v_rcp_f32_e32 v121, v78
	v_mov_b32_e32 v78, v125
	v_pk_mul_f32 v[78:79], v[78:79], v[174:175] op_sel_hi:[1,0]
	v_mov_b32_e32 v125, v76
	v_mul_f32_e32 v77, 0xbfb8aa3b, v79
	v_exp_f32_e32 v126, v77
	v_pk_mul_f32 v[76:77], v[124:125], v[174:175] op_sel_hi:[1,0]
	v_mul_f32_e32 v73, v73, v121
	v_mul_f32_e32 v124, 0xbfb8aa3b, v77
	v_exp_f32_e32 v124, v124
	v_add_f32_e32 v121, 1.0, v126
	v_rcp_f32_e32 v121, v121
	v_mul_f32_e32 v72, v72, v73
	v_add_f32_e32 v124, 1.0, v124
	v_rcp_f32_e32 v124, v124
	v_mul_f32_e32 v73, v79, v121
	v_mul_f32_e32 v73, v78, v73
	v_mov_b32_e32 v121, v63
	v_mul_f32_e32 v77, v77, v124
	v_mul_f32_e32 v76, v76, v77
	v_fmamk_f32 v77, v175, 0x3a800000, v169
	v_mul_f32_e32 v78, 0x4b800000, v77
	v_cmp_gt_f32_e32 vcc, s16, v77
	v_cvt_pk_bf16_f32 v76, v76, v73
	s_nop 1
	v_cndmask_b32_e32 v77, v77, v78, vcc
	v_rsq_f32_e32 v78, v77
	v_cvt_pk_bf16_f32 v77, v72, v120
	v_mov_b32_e32 v120, v111
	v_mov_b32_e32 v111, v62
	v_mul_f32_e32 v79, 0x45800000, v78
	v_cndmask_b32_e32 v78, v78, v79, vcc
	v_pk_mul_f32 v[120:121], v[120:121], v[78:79] op_sel_hi:[1,0]
	v_lshl_add_u64 v[72:73], v[122:123], 0, v[128:129]
	v_mul_f32_e32 v63, 0xbfb8aa3b, v121
	v_exp_f32_e32 v79, v63
	global_store_dwordx4 v[72:73], v[74:77], off
	v_pk_mul_f32 v[62:63], v[110:111], v[78:79] op_sel_hi:[1,0]
	s_nop 0
	v_mul_f32_e32 v110, 0xbfb8aa3b, v63
	v_exp_f32_e32 v110, v110
	v_add_f32_e32 v74, 1.0, v79
	v_rcp_f32_e32 v76, v74
	v_mov_b32_e32 v75, v61
	v_add_f32_e32 v74, 1.0, v110
	v_rcp_f32_e32 v77, v74
	v_mov_b32_e32 v74, v109
	v_pk_mul_f32 v[74:75], v[74:75], v[78:79] op_sel_hi:[1,0]
	v_mov_b32_e32 v109, v60
	v_mul_f32_e32 v61, 0xbfb8aa3b, v75
	v_exp_f32_e32 v61, v61
	v_mul_f32_e32 v63, v63, v77
	v_mul_f32_e32 v76, v121, v76
	v_mul_f32_e32 v76, v120, v76
	v_add_f32_e32 v61, 1.0, v61
	v_rcp_f32_e32 v77, v61
	v_pk_mul_f32 v[60:61], v[108:109], v[78:79] op_sel_hi:[1,0]
	v_mul_f32_e32 v108, v62, v63
	v_mul_f32_e32 v79, 0xbfb8aa3b, v61
	v_exp_f32_e32 v79, v79
	v_mul_f32_e32 v62, v75, v77
	v_mul_f32_e32 v74, v74, v62
	v_mov_b32_e32 v63, v71
	v_add_f32_e32 v62, 1.0, v79
	v_rcp_f32_e32 v75, v62
	v_mov_b32_e32 v62, v115
	v_pk_mul_f32 v[62:63], v[62:63], v[78:79] op_sel_hi:[1,0]
	v_mov_b32_e32 v115, v70
	v_mul_f32_e32 v71, 0xbfb8aa3b, v63
	v_exp_f32_e32 v71, v71
	v_mul_f32_e32 v61, v61, v75
	v_mul_f32_e32 v60, v60, v61
	v_cvt_pk_bf16_f32 v60, v60, v74
	v_add_f32_e32 v61, 1.0, v71
	v_pk_mul_f32 v[70:71], v[114:115], v[78:79] op_sel_hi:[1,0]
	v_rcp_f32_e32 v74, v61
	v_mul_f32_e32 v61, 0xbfb8aa3b, v71
	v_exp_f32_e32 v75, v61
	v_cvt_pk_bf16_f32 v61, v108, v76
	v_mul_f32_e32 v63, v63, v74
	v_mul_f32_e32 v74, v62, v63
	v_add_f32_e32 v62, 1.0, v75
	v_rcp_f32_e32 v75, v62
	v_mov_b32_e32 v62, v113
	v_mov_b32_e32 v63, v69
	v_pk_mul_f32 v[62:63], v[62:63], v[78:79] op_sel_hi:[1,0]
	v_mov_b32_e32 v113, v68
	v_mul_f32_e32 v69, 0xbfb8aa3b, v63
	v_exp_f32_e32 v76, v69
	v_pk_mul_f32 v[68:69], v[112:113], v[78:79] op_sel_hi:[1,0]
	v_mul_f32_e32 v71, v71, v75
	v_mul_f32_e32 v77, 0xbfb8aa3b, v69
	v_exp_f32_e32 v77, v77
	v_add_f32_e32 v75, 1.0, v76
	v_rcp_f32_e32 v75, v75
	v_mul_f32_e32 v70, v70, v71
	v_add_f32_e32 v76, 1.0, v77
	v_rcp_f32_e32 v76, v76
	v_mul_f32_e32 v63, v63, v75
	v_mul_f32_e32 v62, v62, v63
	v_mul_f32_e32 v63, v69, v76
	s_waitcnt vmcnt(6)
	v_fmamk_f32 v69, v180, 0x3a800000, v169
	v_mul_f32_e32 v71, 0x4b800000, v69
	v_cmp_gt_f32_e32 vcc, s16, v69
	v_mul_f32_e32 v63, v68, v63
	v_cvt_pk_bf16_f32 v62, v63, v62
	v_cvt_pk_bf16_f32 v63, v70, v74
	v_mov_b32_e32 v70, v119
	v_cndmask_b32_e32 v69, v69, v71, vcc
	v_rsq_f32_e32 v69, v69
	v_mov_b32_e32 v71, v107
	v_mov_b32_e32 v119, v106
	global_store_dwordx4 v[72:73], v[60:63], off offset:2048
	s_branch .LBB0_461
; __device__ __forceinline__ unsigned cvt_pk_bf16(float lo, float hi) { unsigned r; asm volatile("v_cvt_pk_bf16_f32 %0, %1, %2" : "=v"(r) : "v"(lo), "v"(hi)); return r; }
; __device__ __forceinline__ float fast_sigmoid(float a) { return __builtin_amdgcn_rcpf(1.0f + __expf(-a)); }
;     __device__ __forceinline__ void operator()(const Acc& acc, const Unit& u, int wr, int wc, int fr, int fq) const {
;     ...
; #pragma unroll
;         for (int ai = 0; ai < 2; ++ai)
; #pragma unroll
;             for (int m = 0; m < 4; ++m) {
;                 const int row = u.pm * 256 + ai * 128 + wr * 64 + m * 16 + fr;
;                 const float rs = rsqrtf(ssv[ai][m] * (1.0f / DM) + EPS);
;                 bf16_t* dst = act + ((size_t)((row >> 8) * (DFF / 64) + u.pn * 2 + (wc >> 1)) * 256 + (row & 255)) * 64 + (wc & 1) * 32 + fq * 8;
;                 u32x4 w;
; #pragma unroll
;                 for (int n = 0; n < 2; ++n) {
;                     const f32x4 a = acc[ai][0][m][n] * rs, b = acc[ai][1][m][n] * rs; f32x4 v;
; #pragma unroll
;                     for (int j = 0; j < 4; ++j) v[j] = a[j] * fast_sigmoid(a[j]) * b[j];
;                     if (n == 0) { w.x = cvt_pk_bf16(v[0], v[1]); w.y = cvt_pk_bf16(v[2], v[3]); } else { w.z = cvt_pk_bf16(v[0], v[1]); w.w = cvt_pk_bf16(v[2], v[3]); }
;                 }
;                 *(u32x4*)dst = w;
	v_mul_f32_e32 v68, 0x45800000, v69
	v_cndmask_b32_e32 v68, v69, v68, vcc
	v_pk_mul_f32 v[70:71], v[70:71], v[68:69] op_sel_hi:[1,0]
	v_mov_b32_e32 v61, v105
	v_mul_f32_e32 v69, 0xbfb8aa3b, v71
	v_exp_f32_e32 v69, v69
	s_nop 0
	v_pk_mul_f32 v[74:75], v[118:119], v[68:69] op_sel_hi:[1,0]
	s_nop 0
	v_mul_f32_e32 v76, 0xbfb8aa3b, v75
	v_exp_f32_e32 v76, v76
	v_add_f32_e32 v60, 1.0, v69
	v_rcp_f32_e32 v62, v60
	v_add_f32_e32 v60, 1.0, v76
	v_rcp_f32_e32 v63, v60
	v_mov_b32_e32 v60, v117
	v_pk_mul_f32 v[60:61], v[60:61], v[68:69] op_sel_hi:[1,0]
	v_mul_f32_e32 v62, v71, v62
	v_mul_f32_e32 v69, 0xbfb8aa3b, v61
	v_exp_f32_e32 v69, v69
	v_mul_f32_e32 v76, v70, v62
	v_mov_b32_e32 v117, v104
	v_mul_f32_e32 v70, v75, v63
	v_add_f32_e32 v62, 1.0, v69
	v_rcp_f32_e32 v69, v62
	v_mul_f32_e32 v74, v74, v70
	v_pk_mul_f32 v[62:63], v[116:117], v[68:69] op_sel_hi:[1,0]
	s_nop 0
	v_mul_f32_e32 v71, 0xbfb8aa3b, v63
	v_exp_f32_e32 v71, v71
	v_mul_f32_e32 v61, v61, v69
	v_mul_f32_e32 v69, v60, v61
	v_mov_b32_e32 v61, v99
	v_add_f32_e32 v60, 1.0, v71
	v_rcp_f32_e32 v75, v60
	v_mov_b32_e32 v60, v103
	v_pk_mul_f32 v[70:71], v[60:61], v[68:69] op_sel_hi:[1,0]
	v_mov_b32_e32 v103, v98
	v_mul_f32_e32 v60, 0xbfb8aa3b, v71
	v_exp_f32_e32 v61, v60
	v_mul_f32_e32 v60, v63, v75
	v_mul_f32_e32 v60, v62, v60
	v_cvt_pk_bf16_f32 v60, v60, v69
	v_add_f32_e32 v61, 1.0, v61
	v_rcp_f32_e32 v69, v61
	s_nop 0
	v_pk_mul_f32 v[62:63], v[102:103], v[68:69] op_sel_hi:[1,0]
	s_nop 0
	v_mul_f32_e32 v61, 0xbfb8aa3b, v63
	v_exp_f32_e32 v75, v61
	v_mul_f32_e32 v69, v71, v69
	v_cvt_pk_bf16_f32 v61, v74, v76
	v_mul_f32_e32 v74, v70, v69
	v_add_f32_e32 v69, 1.0, v75
	v_mov_b32_e32 v70, v101
	v_mov_b32_e32 v71, v97
	v_pk_mul_f32 v[70:71], v[70:71], v[68:69] op_sel_hi:[1,0]
	v_rcp_f32_e32 v75, v69
	v_mul_f32_e32 v69, 0xbfb8aa3b, v71
	v_mov_b32_e32 v101, v96
	v_exp_f32_e32 v76, v69
	v_pk_mul_f32 v[68:69], v[100:101], v[68:69] op_sel_hi:[1,0]
	v_mul_f32_e32 v63, v63, v75
	v_mul_f32_e32 v77, 0xbfb8aa3b, v69
	v_exp_f32_e32 v77, v77
	v_add_f32_e32 v75, 1.0, v76
	v_rcp_f32_e32 v75, v75
	v_mul_f32_e32 v63, v62, v63
	v_add_f32_e32 v76, 1.0, v77
	v_rcp_f32_e32 v76, v76
	v_mul_f32_e32 v62, v71, v75
	v_mul_f32_e32 v62, v70, v62
	v_mov_b32_e32 v75, v91
	v_mul_f32_e32 v69, v69, v76
	v_mul_f32_e32 v68, v68, v69
	v_cvt_pk_bf16_f32 v62, v68, v62
	s_waitcnt vmcnt(6)
	v_fmamk_f32 v68, v181, 0x3a800000, v169
	v_mul_f32_e32 v69, 0x4b800000, v68
	v_cmp_gt_f32_e32 vcc, s16, v68
	v_cvt_pk_bf16_f32 v63, v63, v74
	v_mov_b32_e32 v74, v95
	v_mov_b32_e32 v95, v90
	v_cndmask_b32_e32 v68, v68, v69, vcc
	v_rsq_f32_e32 v70, v68
	v_add_co_u32_e64 v68, s[0:1], s17, v72
	v_mul_f32_e32 v71, 0x45800000, v70
	v_cndmask_b32_e32 v70, v70, v71, vcc
	v_pk_mul_f32 v[74:75], v[74:75], v[70:71] op_sel_hi:[1,0]
	v_addc_co_u32_e64 v69, s[0:1], 0, v73, s[0:1]
	v_mul_f32_e32 v71, 0xbfb8aa3b, v75
	v_exp_f32_e32 v71, v71
	global_store_dwordx4 v[68:69], v[60:63], off
	v_pk_mul_f32 v[76:77], v[94:95], v[70:71] op_sel_hi:[1,0]
	s_nop 0
	v_mul_f32_e32 v78, 0xbfb8aa3b, v77
	v_exp_f32_e32 v78, v78
	v_add_f32_e32 v60, 1.0, v71
	v_rcp_f32_e32 v62, v60
	v_mov_b32_e32 v61, v89
	v_add_f32_e32 v60, 1.0, v78
	v_rcp_f32_e32 v63, v60
	v_mov_b32_e32 v60, v93
	v_pk_mul_f32 v[60:61], v[60:61], v[70:71] op_sel_hi:[1,0]
	v_mul_f32_e32 v62, v75, v62
	v_mul_f32_e32 v71, 0xbfb8aa3b, v61
	v_exp_f32_e32 v71, v71
	v_mul_f32_e32 v78, v74, v62
	v_mov_b32_e32 v93, v88
	v_mul_f32_e32 v74, v77, v63
	v_add_f32_e32 v62, 1.0, v71
	v_rcp_f32_e32 v71, v62
	v_mul_f32_e32 v76, v76, v74
	v_pk_mul_f32 v[62:63], v[92:93], v[70:71] op_sel_hi:[1,0]
	s_nop 0
	v_mul_f32_e32 v75, 0xbfb8aa3b, v63
	v_exp_f32_e32 v75, v75
	v_mul_f32_e32 v61, v61, v71
	v_mul_f32_e32 v71, v60, v61
	v_mov_b32_e32 v61, v83
	v_add_f32_e32 v60, 1.0, v75
	v_rcp_f32_e32 v77, v60
	v_mov_b32_e32 v60, v87
	v_pk_mul_f32 v[74:75], v[60:61], v[70:71] op_sel_hi:[1,0]
	v_mov_b32_e32 v87, v82
	v_mul_f32_e32 v60, 0xbfb8aa3b, v75
	v_exp_f32_e32 v61, v60
	v_mul_f32_e32 v60, v63, v77
	v_mul_f32_e32 v60, v62, v60
	v_cvt_pk_bf16_f32 v60, v60, v71
	v_add_f32_e32 v61, 1.0, v61
	v_rcp_f32_e32 v71, v61
	s_nop 0
	v_pk_mul_f32 v[62:63], v[86:87], v[70:71] op_sel_hi:[1,0]
	s_nop 0
	v_mul_f32_e32 v61, 0xbfb8aa3b, v63
	v_exp_f32_e32 v77, v61
	v_mul_f32_e32 v71, v75, v71
	v_cvt_pk_bf16_f32 v61, v76, v78
	v_mul_f32_e32 v76, v74, v71
	v_add_f32_e32 v71, 1.0, v77
	v_mov_b32_e32 v74, v85
	v_mov_b32_e32 v75, v81
	v_pk_mul_f32 v[74:75], v[74:75], v[70:71] op_sel_hi:[1,0]
	v_rcp_f32_e32 v77, v71
	v_mul_f32_e32 v71, 0xbfb8aa3b, v75
	v_exp_f32_e32 v78, v71
	v_mov_b32_e32 v85, v80
	v_pk_mul_f32 v[70:71], v[84:85], v[70:71] op_sel_hi:[1,0]
	v_mul_f32_e32 v63, v63, v77
	v_add_f32_e32 v77, 1.0, v78
	v_mul_f32_e32 v79, 0xbfb8aa3b, v71
	v_rcp_f32_e32 v77, v77
	v_exp_f32_e32 v79, v79
	v_mul_f32_e32 v63, v62, v63
	v_mul_f32_e32 v62, v75, v77
	v_add_f32_e32 v78, 1.0, v79
	v_mul_f32_e32 v62, v74, v62
	s_waitcnt vmcnt(6)
; __device__ __forceinline__ unsigned cvt_pk_bf16(float lo, float hi) { unsigned r; asm volatile("v_cvt_pk_bf16_f32 %0, %1, %2" : "=v"(r) : "v"(lo), "v"(hi)); return r; }
; __device__ __forceinline__ float fast_sigmoid(float a) { return __builtin_amdgcn_rcpf(1.0f + __expf(-a)); }
;     __device__ __forceinline__ void operator()(const Acc& acc, const Unit& u, int wr, int wc, int fr, int fq) const {
;     ...
; #pragma unroll
;         for (int ai = 0; ai < 2; ++ai)
; #pragma unroll
;             for (int m = 0; m < 4; ++m) {
;                 const int row = u.pm * 256 + ai * 128 + wr * 64 + m * 16 + fr;
;                 const float rs = rsqrtf(ssv[ai][m] * (1.0f / DM) + EPS);
;                 bf16_t* dst = act + ((size_t)((row >> 8) * (DFF / 64) + u.pn * 2 + (wc >> 1)) * 256 + (row & 255)) * 64 + (wc & 1) * 32 + fq * 8;
;                 u32x4 w;
; #pragma unroll
;                 for (int n = 0; n < 2; ++n) {
;                     const f32x4 a = acc[ai][0][m][n] * rs, b = acc[ai][1][m][n] * rs; f32x4 v;
; #pragma unroll
;                     for (int j = 0; j < 4; ++j) v[j] = a[j] * fast_sigmoid(a[j]) * b[j];
;                     if (n == 0) { w.x = cvt_pk_bf16(v[0], v[1]); w.y = cvt_pk_bf16(v[2], v[3]); } else { w.z = cvt_pk_bf16(v[0], v[1]); w.w = cvt_pk_bf16(v[2], v[3]); }
;                 }
;                 *(u32x4*)dst = w;
	v_fmamk_f32 v74, v173, 0x3a800000, v169
	v_rcp_f32_e32 v78, v78
	v_mul_f32_e32 v75, 0x4b800000, v74
	v_cmp_gt_f32_e32 vcc, s16, v74
	v_mul_f32_e32 v71, v71, v78
	s_nop 0
	v_cndmask_b32_e32 v74, v74, v75, vcc
	v_rsq_f32_e32 v74, v74
	v_mul_f32_e32 v70, v70, v71
	v_cvt_pk_bf16_f32 v62, v70, v62
	v_mov_b32_e32 v75, v59
	v_mul_f32_e32 v70, 0x45800000, v74
	v_cndmask_b32_e32 v70, v74, v70, vcc
	v_mov_b32_e32 v74, v67
	v_pk_mul_f32 v[74:75], v[74:75], v[70:71] op_sel_hi:[1,0]
	v_mov_b32_e32 v67, v58
	v_mul_f32_e32 v59, 0xbfb8aa3b, v75
	v_exp_f32_e32 v71, v59
	v_cvt_pk_bf16_f32 v63, v63, v76
	global_store_dwordx4 v[68:69], v[60:63], off offset:2048
	v_pk_mul_f32 v[58:59], v[66:67], v[70:71] op_sel_hi:[1,0]
	s_nop 0
	v_mul_f32_e32 v66, 0xbfb8aa3b, v59
	v_exp_f32_e32 v66, v66
	v_add_f32_e32 v60, 1.0, v71
	v_rcp_f32_e32 v62, v60
	v_mov_b32_e32 v61, v57
	v_add_f32_e32 v60, 1.0, v66
	v_rcp_f32_e32 v63, v60
	v_mov_b32_e32 v60, v65
	v_pk_mul_f32 v[60:61], v[60:61], v[70:71] op_sel_hi:[1,0]
	v_mov_b32_e32 v65, v56
	v_mul_f32_e32 v57, 0xbfb8aa3b, v61
	v_exp_f32_e32 v57, v57
	v_mul_f32_e32 v59, v59, v63
	v_mul_f32_e32 v62, v75, v62
	v_mul_f32_e32 v62, v74, v62
	v_add_f32_e32 v57, 1.0, v57
	v_rcp_f32_e32 v63, v57
	v_pk_mul_f32 v[56:57], v[64:65], v[70:71] op_sel_hi:[1,0]
	v_mul_f32_e32 v65, v58, v59
	v_mul_f32_e32 v64, 0xbfb8aa3b, v57
	v_exp_f32_e32 v64, v64
	v_mul_f32_e32 v58, v61, v63
	v_mul_f32_e32 v60, v60, v58
	v_mov_b32_e32 v59, v51
	v_add_f32_e32 v58, 1.0, v64
	v_rcp_f32_e32 v61, v58
	v_mov_b32_e32 v58, v55
	v_pk_mul_f32 v[58:59], v[58:59], v[70:71] op_sel_hi:[1,0]
	v_mul_f32_e32 v55, v57, v61
	v_mul_f32_e32 v51, 0xbfb8aa3b, v59
	v_exp_f32_e32 v51, v51
	v_mul_f32_e32 v55, v56, v55
	v_cvt_pk_bf16_f32 v56, v55, v60
	v_mov_b32_e32 v55, v50
	v_add_f32_e32 v51, 1.0, v51
	v_rcp_f32_e32 v60, v51
	v_pk_mul_f32 v[50:51], v[54:55], v[70:71] op_sel_hi:[1,0]
	v_cvt_pk_bf16_f32 v57, v65, v62
	v_mul_f32_e32 v55, v59, v60
	v_mul_f32_e32 v54, 0xbfb8aa3b, v51
	v_exp_f32_e32 v54, v54
	v_mul_f32_e32 v59, v58, v55
	v_mov_b32_e32 v55, v49
	v_add_f32_e32 v54, 1.0, v54
	v_rcp_f32_e32 v58, v54
	v_mov_b32_e32 v54, v53
	v_pk_mul_f32 v[54:55], v[54:55], v[70:71] op_sel_hi:[1,0]
	v_mov_b32_e32 v53, v48
	v_mul_f32_e32 v49, 0xbfb8aa3b, v55
	v_exp_f32_e32 v60, v49
	v_pk_mul_f32 v[48:49], v[52:53], v[70:71] op_sel_hi:[1,0]
	v_mul_f32_e32 v51, v51, v58
	v_mul_f32_e32 v52, 0xbfb8aa3b, v49
	v_exp_f32_e32 v52, v52
	v_add_f32_e32 v53, 1.0, v60
	v_rcp_f32_e32 v53, v53
	v_mul_f32_e32 v50, v50, v51
	v_add_f32_e32 v52, 1.0, v52
	v_rcp_f32_e32 v52, v52
	v_mul_f32_e32 v51, v55, v53
	v_mul_f32_e32 v51, v54, v51
	v_mov_b32_e32 v54, v47
	v_mul_f32_e32 v49, v49, v52
	v_mul_f32_e32 v48, v48, v49
	v_cvt_pk_bf16_f32 v58, v48, v51
	v_cvt_pk_bf16_f32 v59, v50, v59
	v_add_co_u32_e32 v50, vcc, s18, v72
	s_waitcnt vmcnt(6)
	v_fmamk_f32 v48, v172, 0x3a800000, v169
	v_addc_co_u32_e32 v51, vcc, 0, v73, vcc
	v_mul_f32_e32 v49, 0x4b800000, v48
	v_cmp_gt_f32_e32 vcc, s16, v48
	v_mov_b32_e32 v55, v43
	v_mov_b32_e32 v47, v42
	v_cndmask_b32_e32 v48, v48, v49, vcc
	v_rsq_f32_e32 v52, v48
	v_add_co_u32_e64 v48, s[0:1], s19, v72
	v_mul_f32_e32 v53, 0x45800000, v52
	v_cndmask_b32_e32 v52, v52, v53, vcc
	v_pk_mul_f32 v[54:55], v[54:55], v[52:53] op_sel_hi:[1,0]
	v_addc_co_u32_e64 v49, s[0:1], 0, v73, s[0:1]
	v_mul_f32_e32 v43, 0xbfb8aa3b, v55
	v_exp_f32_e32 v53, v43
	global_store_dwordx4 v[48:49], v[56:59], off offset:-4096
	v_pk_mul_f32 v[42:43], v[46:47], v[52:53] op_sel_hi:[1,0]
	s_nop 0
	v_mul_f32_e32 v46, 0xbfb8aa3b, v43
	v_exp_f32_e32 v46, v46
	v_add_f32_e32 v47, 1.0, v53
	v_rcp_f32_e32 v53, v47
	v_mov_b32_e32 v47, v41
	v_add_f32_e32 v46, 1.0, v46
	v_rcp_f32_e32 v56, v46
	v_mov_b32_e32 v46, v45
	v_pk_mul_f32 v[46:47], v[46:47], v[52:53] op_sel_hi:[1,0]
	v_mul_f32_e32 v45, v55, v53
	v_mul_f32_e32 v41, 0xbfb8aa3b, v47
	v_exp_f32_e32 v41, v41
	v_mul_f32_e32 v53, v54, v45
	v_mov_b32_e32 v45, v40
	v_mul_f32_e32 v43, v43, v56
	v_add_f32_e32 v41, 1.0, v41
	v_rcp_f32_e32 v54, v41
	v_pk_mul_f32 v[40:41], v[44:45], v[52:53] op_sel_hi:[1,0]
	v_mul_f32_e32 v45, v42, v43
	v_mul_f32_e32 v44, 0xbfb8aa3b, v41
	v_exp_f32_e32 v44, v44
	v_mul_f32_e32 v42, v47, v54
	v_mul_f32_e32 v46, v46, v42
	v_mov_b32_e32 v43, v35
	v_add_f32_e32 v42, 1.0, v44
	v_rcp_f32_e32 v44, v42
	v_mov_b32_e32 v42, v39
	v_pk_mul_f32 v[42:43], v[42:43], v[52:53] op_sel_hi:[1,0]
	v_mul_f32_e32 v39, v41, v44
	v_mul_f32_e32 v35, 0xbfb8aa3b, v43
	v_exp_f32_e32 v35, v35
	v_mul_f32_e32 v39, v40, v39
	v_cvt_pk_bf16_f32 v40, v39, v46
	v_mov_b32_e32 v39, v34
	v_add_f32_e32 v35, 1.0, v35
	v_rcp_f32_e32 v44, v35
	v_pk_mul_f32 v[34:35], v[38:39], v[52:53] op_sel_hi:[1,0]
	v_cvt_pk_bf16_f32 v41, v45, v53
	v_mul_f32_e32 v39, v43, v44
	v_mul_f32_e32 v38, 0xbfb8aa3b, v35
	v_exp_f32_e32 v38, v38
	v_mul_f32_e32 v43, v42, v39
	v_mov_b32_e32 v39, v33
	v_add_f32_e32 v38, 1.0, v38
	v_rcp_f32_e32 v42, v38
	v_mov_b32_e32 v38, v37
	v_pk_mul_f32 v[38:39], v[38:39], v[52:53] op_sel_hi:[1,0]
	v_mov_b32_e32 v37, v32
	v_mul_f32_e32 v33, 0xbfb8aa3b, v39
	v_exp_f32_e32 v44, v33
	v_pk_mul_f32 v[32:33], v[36:37], v[52:53] op_sel_hi:[1,0]
	v_mul_f32_e32 v35, v35, v42
	v_mul_f32_e32 v36, 0xbfb8aa3b, v33
	v_exp_f32_e32 v36, v36
	v_add_f32_e32 v37, 1.0, v44
	v_rcp_f32_e32 v37, v37
	v_mul_f32_e32 v34, v34, v35
	v_add_f32_e32 v36, 1.0, v36
	v_rcp_f32_e32 v36, v36
	v_mul_f32_e32 v35, v39, v37
	v_mul_f32_e32 v35, v38, v35
	v_mul_f32_e32 v33, v33, v36
	s_waitcnt vmcnt(6)
; __device__ __forceinline__ unsigned cvt_pk_bf16(float lo, float hi) { unsigned r; asm volatile("v_cvt_pk_bf16_f32 %0, %1, %2" : "=v"(r) : "v"(lo), "v"(hi)); return r; }
; __device__ __forceinline__ float fast_sigmoid(float a) { return __builtin_amdgcn_rcpf(1.0f + __expf(-a)); }
;     __device__ __forceinline__ void operator()(const Acc& acc, const Unit& u, int wr, int wc, int fr, int fq) const {
;     ...
; #pragma unroll
;         for (int ai = 0; ai < 2; ++ai)
; #pragma unroll
;             for (int m = 0; m < 4; ++m) {
;                 const int row = u.pm * 256 + ai * 128 + wr * 64 + m * 16 + fr;
;                 const float rs = rsqrtf(ssv[ai][m] * (1.0f / DM) + EPS);
;                 bf16_t* dst = act + ((size_t)((row >> 8) * (DFF / 64) + u.pn * 2 + (wc >> 1)) * 256 + (row & 255)) * 64 + (wc & 1) * 32 + fq * 8;
;                 u32x4 w;
; #pragma unroll
;                 for (int n = 0; n < 2; ++n) {
;                     const f32x4 a = acc[ai][0][m][n] * rs, b = acc[ai][1][m][n] * rs; f32x4 v;
; #pragma unroll
;                     for (int j = 0; j < 4; ++j) v[j] = a[j] * fast_sigmoid(a[j]) * b[j];
;                     if (n == 0) { w.x = cvt_pk_bf16(v[0], v[1]); w.y = cvt_pk_bf16(v[2], v[3]); } else { w.z = cvt_pk_bf16(v[0], v[1]); w.w = cvt_pk_bf16(v[2], v[3]); }
;                 }
;                 *(u32x4*)dst = w;
	v_fmamk_f32 v36, v171, 0x3a800000, v169
	v_mul_f32_e32 v37, 0x4b800000, v36
	v_cmp_gt_f32_e32 vcc, s16, v36
	v_mul_f32_e32 v32, v32, v33
	v_cvt_pk_bf16_f32 v42, v32, v35
	v_cvt_pk_bf16_f32 v43, v34, v43
	v_mov_b32_e32 v34, v31
	v_cndmask_b32_e32 v36, v36, v37, vcc
	v_rsq_f32_e32 v36, v36
	v_mov_b32_e32 v35, v27
	v_mov_b32_e32 v31, v26
	global_store_dwordx4 v[50:51], v[40:43], off offset:2048
	v_mul_f32_e32 v32, 0x45800000, v36
	v_cndmask_b32_e32 v32, v36, v32, vcc
	v_pk_mul_f32 v[34:35], v[34:35], v[32:33] op_sel_hi:[1,0]
	s_nop 0
	v_mul_f32_e32 v27, 0xbfb8aa3b, v35
	v_exp_f32_e32 v33, v27
	s_nop 0
	v_pk_mul_f32 v[26:27], v[30:31], v[32:33] op_sel_hi:[1,0]
	s_nop 0
	v_mul_f32_e32 v30, 0xbfb8aa3b, v27
	v_exp_f32_e32 v30, v30
	v_add_f32_e32 v31, 1.0, v33
	v_rcp_f32_e32 v33, v31
	v_mov_b32_e32 v31, v25
	v_add_f32_e32 v30, 1.0, v30
	v_rcp_f32_e32 v36, v30
	v_mov_b32_e32 v30, v29
	v_pk_mul_f32 v[30:31], v[30:31], v[32:33] op_sel_hi:[1,0]
	v_mul_f32_e32 v29, v35, v33
	v_mul_f32_e32 v25, 0xbfb8aa3b, v31
	v_exp_f32_e32 v25, v25
	v_mul_f32_e32 v33, v34, v29
	v_mov_b32_e32 v29, v24
	v_mul_f32_e32 v27, v27, v36
	v_add_f32_e32 v25, 1.0, v25
	v_rcp_f32_e32 v34, v25
	v_pk_mul_f32 v[24:25], v[28:29], v[32:33] op_sel_hi:[1,0]
	v_mul_f32_e32 v29, v26, v27
	v_mul_f32_e32 v28, 0xbfb8aa3b, v25
	v_exp_f32_e32 v28, v28
	v_mul_f32_e32 v26, v31, v34
	v_mul_f32_e32 v30, v30, v26
	v_mov_b32_e32 v27, v19
	v_add_f32_e32 v26, 1.0, v28
	v_rcp_f32_e32 v28, v26
	v_mov_b32_e32 v26, v23
	v_pk_mul_f32 v[26:27], v[26:27], v[32:33] op_sel_hi:[1,0]
	v_mul_f32_e32 v23, v25, v28
	v_mul_f32_e32 v19, 0xbfb8aa3b, v27
	v_exp_f32_e32 v19, v19
	v_mul_f32_e32 v23, v24, v23
	v_cvt_pk_bf16_f32 v24, v23, v30
	v_mov_b32_e32 v23, v18
	v_add_f32_e32 v19, 1.0, v19
	v_rcp_f32_e32 v28, v19
	v_pk_mul_f32 v[18:19], v[22:23], v[32:33] op_sel_hi:[1,0]
	v_cvt_pk_bf16_f32 v25, v29, v33
	v_mul_f32_e32 v23, v27, v28
	v_mul_f32_e32 v22, 0xbfb8aa3b, v19
	v_exp_f32_e32 v22, v22
	v_mul_f32_e32 v27, v26, v23
	v_mov_b32_e32 v23, v17
	v_add_f32_e32 v22, 1.0, v22
	v_rcp_f32_e32 v26, v22
	v_mov_b32_e32 v22, v21
	v_pk_mul_f32 v[22:23], v[22:23], v[32:33] op_sel_hi:[1,0]
	v_mov_b32_e32 v21, v16
	v_mul_f32_e32 v17, 0xbfb8aa3b, v23
	v_exp_f32_e32 v28, v17
	v_pk_mul_f32 v[16:17], v[20:21], v[32:33] op_sel_hi:[1,0]
	v_mul_f32_e32 v19, v19, v26
	v_mul_f32_e32 v20, 0xbfb8aa3b, v17
	v_exp_f32_e32 v20, v20
	v_add_f32_e32 v21, 1.0, v28
	v_rcp_f32_e32 v21, v21
	v_mul_f32_e32 v18, v18, v19
	v_add_f32_e32 v20, 1.0, v20
	v_rcp_f32_e32 v20, v20
	v_mul_f32_e32 v19, v23, v21
	v_mul_f32_e32 v19, v22, v19
	v_mul_f32_e32 v17, v17, v20
	s_waitcnt vmcnt(6)
	v_fmamk_f32 v20, v170, 0x3a800000, v169
	v_mul_f32_e32 v21, 0x4b800000, v20
	v_cmp_gt_f32_e32 vcc, s16, v20
	v_mul_f32_e32 v16, v16, v17
	v_cvt_pk_bf16_f32 v26, v16, v19
	v_cvt_pk_bf16_f32 v27, v18, v27
	v_mov_b32_e32 v18, v15
	v_cndmask_b32_e32 v20, v20, v21, vcc
	v_rsq_f32_e32 v20, v20
	v_mov_b32_e32 v19, v11
	v_mov_b32_e32 v15, v10
	global_store_dwordx4 v[48:49], v[24:27], off
	v_mul_f32_e32 v16, 0x45800000, v20
	v_cndmask_b32_e32 v16, v20, v16, vcc
	v_pk_mul_f32 v[18:19], v[18:19], v[16:17] op_sel_hi:[1,0]
	s_nop 0
	v_mul_f32_e32 v11, 0xbfb8aa3b, v19
	v_exp_f32_e32 v17, v11
	s_nop 0
	v_pk_mul_f32 v[10:11], v[14:15], v[16:17] op_sel_hi:[1,0]
	s_nop 0
	v_mul_f32_e32 v14, 0xbfb8aa3b, v11
	v_exp_f32_e32 v14, v14
	v_add_f32_e32 v15, 1.0, v17
	v_rcp_f32_e32 v17, v15
	v_mov_b32_e32 v15, v9
	v_add_f32_e32 v14, 1.0, v14
	v_rcp_f32_e32 v20, v14
	v_mov_b32_e32 v14, v13
	v_pk_mul_f32 v[14:15], v[14:15], v[16:17] op_sel_hi:[1,0]
	v_mul_f32_e32 v13, v19, v17
	v_mul_f32_e32 v9, 0xbfb8aa3b, v15
	v_exp_f32_e32 v9, v9
	v_mul_f32_e32 v17, v18, v13
	v_mov_b32_e32 v13, v8
	v_mul_f32_e32 v11, v11, v20
	v_add_f32_e32 v9, 1.0, v9
	v_rcp_f32_e32 v18, v9
	v_pk_mul_f32 v[8:9], v[12:13], v[16:17] op_sel_hi:[1,0]
	v_mul_f32_e32 v13, v10, v11
	v_mul_f32_e32 v12, 0xbfb8aa3b, v9
	v_exp_f32_e32 v12, v12
	v_mul_f32_e32 v10, v15, v18
	v_mul_f32_e32 v14, v14, v10
	v_mov_b32_e32 v11, v7
	v_add_f32_e32 v10, 1.0, v12
	v_rcp_f32_e32 v12, v10
	v_mov_b32_e32 v10, v3
	v_pk_mul_f32 v[10:11], v[10:11], v[16:17] op_sel_hi:[1,0]
	v_mul_f32_e32 v7, v9, v12
	v_mul_f32_e32 v3, 0xbfb8aa3b, v11
	v_exp_f32_e32 v3, v3
	v_mul_f32_e32 v7, v8, v7
	v_cvt_pk_bf16_f32 v8, v7, v14
	v_cvt_pk_bf16_f32 v9, v13, v17
	v_add_f32_e32 v3, 1.0, v3
	v_rcp_f32_e32 v7, v3
	v_mov_b32_e32 v3, v6
	v_pk_mul_f32 v[2:3], v[2:3], v[16:17] op_sel_hi:[1,0]
	v_mul_f32_e32 v7, v11, v7
	v_mul_f32_e32 v6, 0xbfb8aa3b, v3
	v_exp_f32_e32 v6, v6
	v_mul_f32_e32 v11, v10, v7
	v_mov_b32_e32 v7, v5
	v_add_f32_e32 v6, 1.0, v6
	v_rcp_f32_e32 v10, v6
	v_mov_b32_e32 v6, v1
	v_pk_mul_f32 v[6:7], v[6:7], v[16:17] op_sel_hi:[1,0]
	v_mul_f32_e32 v3, v3, v10
	v_mul_f32_e32 v1, 0xbfb8aa3b, v7
	v_exp_f32_e32 v5, v1
	v_mov_b32_e32 v1, v4
	v_pk_mul_f32 v[0:1], v[0:1], v[16:17] op_sel_hi:[1,0]
	v_mul_f32_e32 v2, v2, v3
	v_mul_f32_e32 v4, 0xbfb8aa3b, v1
	v_exp_f32_e32 v4, v4
	v_add_f32_e32 v5, 1.0, v5
	v_rcp_f32_e32 v5, v5
	v_add_f32_e32 v4, 1.0, v4
	v_rcp_f32_e32 v4, v4
	v_mul_f32_e32 v3, v7, v5
	v_mul_f32_e32 v3, v6, v3
	v_mul_f32_e32 v1, v1, v4
	v_mul_f32_e32 v0, v0, v1
	v_cvt_pk_bf16_f32 v10, v0, v3
	v_cvt_pk_bf16_f32 v11, v2, v11
	global_store_dwordx4 v[48:49], v[8:11], off offset:2048
	s_branch .LBB0_461

; #define LAS __attribute__((address_space(3)))
; #define SCHED_BAR() __builtin_amdgcn_sched_barrier(0)
; template <class Epi>
; __device__ __forceinline__ void skinny_phase(LAS unsigned char* lds, const pg8::Gemm g, const Epi& E, int G, int bx) {
;     ...
;         LAS f32x4* red = (LAS f32x4*)lds;
;         __syncthreads();
; #pragma unroll
;         for (int b = 0; b < 2; ++b)
; #pragma unroll
;             for (int m = 0; m < 2; ++m)
; #pragma unroll
;                 for (int n = 0; n < 2; ++n) red[(((b * 2 + m) * 2 + n) * 8 + wid) * 64 + lane] = a8[b][m][n];
;         __syncthreads();
;         if (wid == 0) {
;             Acc acc;
; #pragma unroll
;             for (int a = 0; a < 2; ++a)
; #pragma unroll
;                 for (int b = 0; b < 2; ++b)
; #pragma unroll
;                     for (int m = 0; m < 4; ++m)
; #pragma unroll
;                         for (int n = 0; n < 2; ++n) acc[a][b][m][n] = (f32x4){0.f, 0.f, 0.f, 0.f};
; #pragma unroll
;             for (int b = 0; b < 2; ++b)
; #pragma unroll
;                 for (int m = 0; m < 2; ++m)
; #pragma unroll
;                     for (int n = 0; n < 2; ++n) { f32x4 t = {0.f, 0.f, 0.f, 0.f};
; #pragma unroll
;                         for (int w8 = 0; w8 < 8; ++w8) t += red[(((b * 2 + m) * 2 + n) * 8 + w8) * 64 + lane];
;                         acc[0][b][m][n] = t; SCHED_BAR(); }
.LBB0_1482:
	s_and_b64 vcc, exec, s[2:3]
	s_barrier
	ds_write_b128 v204, v[28:31]
	ds_write_b128 v204, v[24:27] offset:8192
	ds_write_b128 v204, v[20:23] offset:16384
	ds_write_b128 v204, v[16:19] offset:24576
	ds_write_b128 v204, v[12:15] offset:32768
	ds_write_b128 v204, v[8:11] offset:40960
	ds_write_b128 v204, v[4:7] offset:49152
	ds_write_b128 v204, v[0:3] offset:57344
	s_waitcnt lgkmcnt(0)
	s_barrier
	s_cbranch_vccz .LBB0_1469
	ds_read_b128 v[0:3], v205
	ds_read_b128 v[4:7], v205 offset:1024
	ds_read_b128 v[8:11], v205 offset:2048
	ds_read_b128 v[12:15], v205 offset:3072
	s_waitcnt lgkmcnt(3)
	v_pk_add_f32 v[2:3], v[2:3], 0 op_sel_hi:[1,0]
	v_pk_add_f32 v[0:1], v[0:1], 0 op_sel_hi:[1,0]
	s_waitcnt lgkmcnt(2)
	v_pk_add_f32 v[2:3], v[2:3], v[6:7]
	v_pk_add_f32 v[4:5], v[0:1], v[4:5]
	s_waitcnt lgkmcnt(1)
	v_pk_add_f32 v[6:7], v[2:3], v[10:11]
	ds_read_b128 v[0:3], v205 offset:4096
	v_pk_add_f32 v[4:5], v[4:5], v[8:9]
	s_waitcnt lgkmcnt(1)
	v_pk_add_f32 v[8:9], v[6:7], v[14:15]
	v_pk_add_f32 v[12:13], v[4:5], v[12:13]
	ds_read_b128 v[4:7], v205 offset:5120
	s_waitcnt lgkmcnt(1)
	v_pk_add_f32 v[14:15], v[8:9], v[2:3]
	ds_read_b128 v[8:11], v205 offset:6144
	v_pk_add_f32 v[12:13], v[12:13], v[0:1]
	ds_read_b128 v[0:3], v205 offset:7168
	s_waitcnt lgkmcnt(2)
	v_pk_add_f32 v[6:7], v[14:15], v[6:7]
	v_pk_add_f32 v[4:5], v[12:13], v[4:5]
	s_waitcnt lgkmcnt(1)
	v_pk_add_f32 v[6:7], v[6:7], v[10:11]
	v_pk_add_f32 v[4:5], v[4:5], v[8:9]
	s_waitcnt lgkmcnt(0)
	v_pk_add_f32 v[18:19], v[6:7], v[2:3]
	v_pk_add_f32 v[16:17], v[4:5], v[0:1]
	ds_read_b128 v[0:3], v205 offset:8192
	ds_read_b128 v[4:7], v205 offset:9216
	ds_read_b128 v[8:11], v205 offset:10240
	ds_read_b128 v[12:15], v205 offset:11264
	s_waitcnt lgkmcnt(3)
	v_pk_add_f32 v[2:3], v[2:3], 0 op_sel_hi:[1,0]
	v_pk_add_f32 v[0:1], v[0:1], 0 op_sel_hi:[1,0]
	s_waitcnt lgkmcnt(2)
	v_pk_add_f32 v[2:3], v[2:3], v[6:7]
	v_pk_add_f32 v[4:5], v[0:1], v[4:5]
	s_waitcnt lgkmcnt(1)
	v_pk_add_f32 v[6:7], v[2:3], v[10:11]
	ds_read_b128 v[0:3], v205 offset:12288
	v_pk_add_f32 v[4:5], v[4:5], v[8:9]
	s_waitcnt lgkmcnt(1)
	v_pk_add_f32 v[8:9], v[6:7], v[14:15]
	v_pk_add_f32 v[12:13], v[4:5], v[12:13]
	ds_read_b128 v[4:7], v205 offset:13312
	s_waitcnt lgkmcnt(1)
	v_pk_add_f32 v[14:15], v[8:9], v[2:3]
	ds_read_b128 v[8:11], v205 offset:14336
	v_pk_add_f32 v[12:13], v[12:13], v[0:1]
	ds_read_b128 v[0:3], v205 offset:15360
	s_waitcnt lgkmcnt(2)
	v_pk_add_f32 v[6:7], v[14:15], v[6:7]
	v_pk_add_f32 v[4:5], v[12:13], v[4:5]
	s_waitcnt lgkmcnt(1)
	v_pk_add_f32 v[6:7], v[6:7], v[10:11]
	v_pk_add_f32 v[4:5], v[4:5], v[8:9]
	s_waitcnt lgkmcnt(0)
	v_pk_add_f32 v[38:39], v[6:7], v[2:3]
	v_pk_add_f32 v[36:37], v[4:5], v[0:1]
	ds_read_b128 v[0:3], v205 offset:16384
	ds_read_b128 v[4:7], v205 offset:17408
	ds_read_b128 v[8:11], v205 offset:18432
	ds_read_b128 v[12:15], v205 offset:19456
	s_waitcnt lgkmcnt(3)
	v_pk_add_f32 v[2:3], v[2:3], 0 op_sel_hi:[1,0]
	v_pk_add_f32 v[0:1], v[0:1], 0 op_sel_hi:[1,0]
	s_waitcnt lgkmcnt(2)
	v_pk_add_f32 v[2:3], v[2:3], v[6:7]
	v_pk_add_f32 v[4:5], v[0:1], v[4:5]
	s_waitcnt lgkmcnt(1)
	v_pk_add_f32 v[6:7], v[2:3], v[10:11]
	ds_read_b128 v[0:3], v205 offset:20480
	v_pk_add_f32 v[4:5], v[4:5], v[8:9]
	s_waitcnt lgkmcnt(1)
	v_pk_add_f32 v[8:9], v[6:7], v[14:15]
	v_pk_add_f32 v[12:13], v[4:5], v[12:13]
	ds_read_b128 v[4:7], v205 offset:21504
	s_waitcnt lgkmcnt(1)
	v_pk_add_f32 v[14:15], v[8:9], v[2:3]
	ds_read_b128 v[8:11], v205 offset:22528
	v_pk_add_f32 v[12:13], v[12:13], v[0:1]
	ds_read_b128 v[0:3], v205 offset:23552
	s_waitcnt lgkmcnt(2)
	v_pk_add_f32 v[6:7], v[14:15], v[6:7]
	v_pk_add_f32 v[4:5], v[12:13], v[4:5]
	s_waitcnt lgkmcnt(1)
	v_pk_add_f32 v[6:7], v[6:7], v[10:11]
	v_pk_add_f32 v[4:5], v[4:5], v[8:9]
	s_waitcnt lgkmcnt(0)
	v_pk_add_f32 v[30:31], v[6:7], v[2:3]
	v_pk_add_f32 v[28:29], v[4:5], v[0:1]
	ds_read_b128 v[0:3], v205 offset:24576
	ds_read_b128 v[4:7], v205 offset:25600
	ds_read_b128 v[8:11], v205 offset:26624
	ds_read_b128 v[12:15], v205 offset:27648
	s_waitcnt lgkmcnt(3)
	v_pk_add_f32 v[2:3], v[2:3], 0 op_sel_hi:[1,0]
	v_pk_add_f32 v[0:1], v[0:1], 0 op_sel_hi:[1,0]
	s_waitcnt lgkmcnt(2)
	v_pk_add_f32 v[2:3], v[2:3], v[6:7]
	v_pk_add_f32 v[4:5], v[0:1], v[4:5]
	s_waitcnt lgkmcnt(1)
	v_pk_add_f32 v[6:7], v[2:3], v[10:11]
	ds_read_b128 v[0:3], v205 offset:28672
	v_pk_add_f32 v[4:5], v[4:5], v[8:9]
	s_waitcnt lgkmcnt(1)
	v_pk_add_f32 v[8:9], v[6:7], v[14:15]
	v_pk_add_f32 v[12:13], v[4:5], v[12:13]
	ds_read_b128 v[4:7], v205 offset:29696
	s_waitcnt lgkmcnt(1)
	v_pk_add_f32 v[14:15], v[8:9], v[2:3]
	ds_read_b128 v[8:11], v205 offset:30720
	v_pk_add_f32 v[12:13], v[12:13], v[0:1]
	ds_read_b128 v[0:3], v205 offset:31744
	s_waitcnt lgkmcnt(2)
	v_pk_add_f32 v[6:7], v[14:15], v[6:7]
	v_pk_add_f32 v[4:5], v[12:13], v[4:5]
	s_waitcnt lgkmcnt(1)
	v_pk_add_f32 v[6:7], v[6:7], v[10:11]
	v_pk_add_f32 v[4:5], v[4:5], v[8:9]
	s_waitcnt lgkmcnt(0)
	v_pk_add_f32 v[58:59], v[6:7], v[2:3]
	v_pk_add_f32 v[56:57], v[4:5], v[0:1]
	ds_read_b128 v[0:3], v205 offset:32768
	ds_read_b128 v[4:7], v205 offset:33792
	ds_read_b128 v[8:11], v205 offset:34816
	ds_read_b128 v[12:15], v205 offset:35840
	s_waitcnt lgkmcnt(3)
	v_pk_add_f32 v[2:3], v[2:3], 0 op_sel_hi:[1,0]
	v_pk_add_f32 v[0:1], v[0:1], 0 op_sel_hi:[1,0]
	s_waitcnt lgkmcnt(2)
	v_pk_add_f32 v[2:3], v[2:3], v[6:7]
	v_pk_add_f32 v[4:5], v[0:1], v[4:5]
	s_waitcnt lgkmcnt(1)
	v_pk_add_f32 v[6:7], v[2:3], v[10:11]
	ds_read_b128 v[0:3], v205 offset:36864
	v_pk_add_f32 v[4:5], v[4:5], v[8:9]
	s_waitcnt lgkmcnt(1)
	v_pk_add_f32 v[8:9], v[6:7], v[14:15]
	v_pk_add_f32 v[12:13], v[4:5], v[12:13]
	ds_read_b128 v[4:7], v205 offset:37888
	s_waitcnt lgkmcnt(1)
; #define SCHED_BAR() __builtin_amdgcn_sched_barrier(0)
;     __device__ __forceinline__ void operator()(const Acc& acc, const Unit& u, int wr, int wc, int fr, int fq) const {
;     ...
;         u32x4 Gt[2][4][2];
; #pragma unroll
;         for (int ai = 0; ai < 2; ++ai)
; #pragma unroll
;             for (int m = 0; m < 4; ++m) { const int row = u.pm * 256 + ai * 128 + wr * 64 + m * 16 + fr; const bf16_t* gp = proj + (size_t)row * DIN + GA_OFF + colb;
; #pragma unroll
;                 for (int bj = 0; bj < 2; ++bj) Gt[ai][m][bj] = *(const u32x4*)(gp + bj * 32); }
; template <class Epi>
; __device__ __forceinline__ void skinny_phase(LAS unsigned char* lds, const pg8::Gemm g, const Epi& E, int G, int bx) {
;     ...
; #pragma unroll
;             for (int a = 0; a < 2; ++a)
; #pragma unroll
;                 for (int b = 0; b < 2; ++b)
; #pragma unroll
;                     for (int m = 0; m < 4; ++m)
; #pragma unroll
;                         for (int n = 0; n < 2; ++n) acc[a][b][m][n] = (f32x4){0.f, 0.f, 0.f, 0.f};
; #pragma unroll
;             for (int b = 0; b < 2; ++b)
; #pragma unroll
;                 for (int m = 0; m < 2; ++m)
; #pragma unroll
;                     for (int n = 0; n < 2; ++n) { f32x4 t = {0.f, 0.f, 0.f, 0.f};
; #pragma unroll
;                         for (int w8 = 0; w8 < 8; ++w8) t += red[(((b * 2 + m) * 2 + n) * 8 + w8) * 64 + lane];
;                         acc[0][b][m][n] = t; SCHED_BAR(); }
	v_pk_add_f32 v[14:15], v[8:9], v[2:3]
	ds_read_b128 v[8:11], v205 offset:38912
	v_pk_add_f32 v[12:13], v[12:13], v[0:1]
	ds_read_b128 v[0:3], v205 offset:39936
	s_waitcnt lgkmcnt(2)
	v_pk_add_f32 v[6:7], v[14:15], v[6:7]
	v_pk_add_f32 v[4:5], v[12:13], v[4:5]
	s_waitcnt lgkmcnt(1)
	v_pk_add_f32 v[6:7], v[6:7], v[10:11]
	v_pk_add_f32 v[4:5], v[4:5], v[8:9]
	s_waitcnt vmcnt(9) lgkmcnt(0)
	v_pk_add_f32 v[102:103], v[6:7], v[2:3]
	v_pk_add_f32 v[100:101], v[4:5], v[0:1]
	ds_read_b128 v[0:3], v205 offset:40960
	ds_read_b128 v[4:7], v205 offset:41984
	ds_read_b128 v[8:11], v205 offset:43008
	ds_read_b128 v[12:15], v205 offset:44032
	s_waitcnt lgkmcnt(3)
	v_pk_add_f32 v[2:3], v[2:3], 0 op_sel_hi:[1,0]
	v_pk_add_f32 v[0:1], v[0:1], 0 op_sel_hi:[1,0]
	s_waitcnt lgkmcnt(2)
	v_pk_add_f32 v[2:3], v[2:3], v[6:7]
	v_pk_add_f32 v[4:5], v[0:1], v[4:5]
	s_waitcnt lgkmcnt(1)
	v_pk_add_f32 v[6:7], v[2:3], v[10:11]
	ds_read_b128 v[0:3], v205 offset:45056
	v_pk_add_f32 v[4:5], v[4:5], v[8:9]
	s_waitcnt lgkmcnt(1)
	v_pk_add_f32 v[8:9], v[6:7], v[14:15]
	v_pk_add_f32 v[12:13], v[4:5], v[12:13]
	ds_read_b128 v[4:7], v205 offset:46080
	s_waitcnt lgkmcnt(1)
	v_pk_add_f32 v[14:15], v[8:9], v[2:3]
	ds_read_b128 v[8:11], v205 offset:47104
	v_pk_add_f32 v[12:13], v[12:13], v[0:1]
	ds_read_b128 v[0:3], v205 offset:48128
	s_waitcnt lgkmcnt(2)
	v_pk_add_f32 v[6:7], v[14:15], v[6:7]
	v_pk_add_f32 v[4:5], v[12:13], v[4:5]
	s_waitcnt lgkmcnt(1)
	v_pk_add_f32 v[6:7], v[6:7], v[10:11]
	v_pk_add_f32 v[4:5], v[4:5], v[8:9]
	s_waitcnt lgkmcnt(0)
	v_pk_add_f32 v[134:135], v[6:7], v[2:3]
	v_pk_add_f32 v[132:133], v[4:5], v[0:1]
	ds_read_b128 v[0:3], v205 offset:49152
	ds_read_b128 v[4:7], v205 offset:50176
	ds_read_b128 v[8:11], v205 offset:51200
	ds_read_b128 v[12:15], v205 offset:52224
	s_waitcnt lgkmcnt(3)
	v_pk_add_f32 v[2:3], v[2:3], 0 op_sel_hi:[1,0]
	v_pk_add_f32 v[0:1], v[0:1], 0 op_sel_hi:[1,0]
	s_waitcnt lgkmcnt(2)
	v_pk_add_f32 v[2:3], v[2:3], v[6:7]
	v_pk_add_f32 v[4:5], v[0:1], v[4:5]
	s_waitcnt lgkmcnt(1)
	v_pk_add_f32 v[6:7], v[2:3], v[10:11]
	ds_read_b128 v[0:3], v205 offset:53248
	v_pk_add_f32 v[4:5], v[4:5], v[8:9]
	s_waitcnt lgkmcnt(1)
	v_pk_add_f32 v[8:9], v[6:7], v[14:15]
	v_pk_add_f32 v[12:13], v[4:5], v[12:13]
	ds_read_b128 v[4:7], v205 offset:54272
	s_waitcnt lgkmcnt(1)
	v_pk_add_f32 v[14:15], v[8:9], v[2:3]
	ds_read_b128 v[8:11], v205 offset:55296
	v_pk_add_f32 v[12:13], v[12:13], v[0:1]
	ds_read_b128 v[0:3], v205 offset:56320
	s_waitcnt lgkmcnt(2)
	v_pk_add_f32 v[6:7], v[14:15], v[6:7]
	v_pk_add_f32 v[4:5], v[12:13], v[4:5]
	s_waitcnt lgkmcnt(1)
	v_pk_add_f32 v[6:7], v[6:7], v[10:11]
	v_pk_add_f32 v[4:5], v[4:5], v[8:9]
	s_waitcnt lgkmcnt(0)
	v_pk_add_f32 v[130:131], v[6:7], v[2:3]
	v_pk_add_f32 v[128:129], v[4:5], v[0:1]
	ds_read_b128 v[0:3], v205 offset:57344
	ds_read_b128 v[4:7], v205 offset:58368
	ds_read_b128 v[8:11], v205 offset:59392
	ds_read_b128 v[12:15], v205 offset:60416
	s_waitcnt lgkmcnt(3)
	v_pk_add_f32 v[2:3], v[2:3], 0 op_sel_hi:[1,0]
	v_pk_add_f32 v[0:1], v[0:1], 0 op_sel_hi:[1,0]
	s_waitcnt lgkmcnt(2)
	v_pk_add_f32 v[2:3], v[2:3], v[6:7]
	v_pk_add_f32 v[4:5], v[0:1], v[4:5]
	s_waitcnt lgkmcnt(1)
	v_pk_add_f32 v[6:7], v[2:3], v[10:11]
	ds_read_b128 v[0:3], v205 offset:61440
	v_pk_add_f32 v[4:5], v[4:5], v[8:9]
	s_waitcnt lgkmcnt(1)
	v_pk_add_f32 v[8:9], v[6:7], v[14:15]
	v_pk_add_f32 v[12:13], v[4:5], v[12:13]
	ds_read_b128 v[4:7], v205 offset:62464
	s_waitcnt lgkmcnt(1)
	v_pk_add_f32 v[14:15], v[8:9], v[2:3]
	ds_read_b128 v[8:11], v205 offset:63488
	v_pk_add_f32 v[12:13], v[12:13], v[0:1]
	ds_read_b128 v[0:3], v205 offset:64512
	s_waitcnt lgkmcnt(2)
	v_pk_add_f32 v[6:7], v[14:15], v[6:7]
	v_pk_add_f32 v[4:5], v[12:13], v[4:5]
	s_waitcnt lgkmcnt(1)
	v_pk_add_f32 v[6:7], v[6:7], v[10:11]
	v_pk_add_f32 v[4:5], v[4:5], v[8:9]
	s_waitcnt lgkmcnt(0)
	v_pk_add_f32 v[142:143], v[6:7], v[2:3]
	v_pk_add_f32 v[140:141], v[4:5], v[0:1]
	v_lshl_or_b32 v200, s20, 6, v203
	s_mov_b32 s9, s8
	s_mov_b32 s10, s8
	s_mov_b32 s11, s8
	v_ashrrev_i32_e32 v201, 31, v200
	v_mov_b64_e32 v[0:1], s[8:9]
	v_mov_b64_e32 v[158:159], s[10:11]
	v_mov_b64_e32 v[146:147], s[10:11]
	v_mov_b64_e32 v[122:123], s[10:11]
	v_mov_b64_e32 v[110:111], s[10:11]
	v_mov_b64_e32 v[162:163], s[10:11]
	v_mov_b64_e32 v[150:151], s[10:11]
	v_mov_b64_e32 v[126:127], s[10:11]
	v_mov_b64_e32 v[114:115], s[10:11]
	v_mov_b64_e32 v[106:107], s[10:11]
	s_waitcnt vmcnt(7)
	v_mov_b64_e32 v[94:95], s[10:11]
	s_waitcnt vmcnt(3)
	v_mov_b64_e32 v[78:79], s[10:11]
	s_waitcnt vmcnt(1)
	v_mov_b64_e32 v[70:71], s[10:11]
	v_mov_b64_e32 v[50:51], s[10:11]
	v_mov_b64_e32 v[42:43], s[10:11]
	v_mov_b64_e32 v[14:15], s[10:11]
	v_mov_b64_e32 v[8:9], s[8:9]
	v_mov_b64_e32 v[90:91], s[10:11]
	v_mov_b64_e32 v[86:87], s[10:11]
	s_waitcnt vmcnt(0)
	v_mov_b64_e32 v[66:67], s[10:11]
	v_mov_b64_e32 v[62:63], s[10:11]
	v_mov_b64_e32 v[34:35], s[10:11]
	v_mov_b64_e32 v[26:27], s[10:11]
	v_mov_b64_e32 v[4:5], s[8:9]
	v_lshlrev_b64 v[20:21], 1, v[200:201]
	v_mov_b64_e32 v[2:3], s[10:11]
	v_mov_b64_e32 v[156:157], s[8:9]
	v_mov_b64_e32 v[144:145], s[8:9]
	v_mov_b64_e32 v[120:121], s[8:9]
	v_mov_b64_e32 v[108:109], s[8:9]
	v_mov_b64_e32 v[160:161], s[8:9]
	v_mov_b64_e32 v[148:149], s[8:9]
	v_mov_b64_e32 v[124:125], s[8:9]
	v_mov_b64_e32 v[112:113], s[8:9]
	v_mov_b64_e32 v[104:105], s[8:9]
	v_mov_b64_e32 v[92:93], s[8:9]
	v_mov_b64_e32 v[76:77], s[8:9]
	v_mov_b64_e32 v[68:69], s[8:9]
	v_mov_b64_e32 v[48:49], s[8:9]
	v_mov_b64_e32 v[40:41], s[8:9]
	v_mov_b64_e32 v[12:13], s[8:9]
	v_mov_b64_e32 v[10:11], s[10:11]
	v_mov_b64_e32 v[88:89], s[8:9]
	v_mov_b64_e32 v[84:85], s[8:9]
	v_mov_b64_e32 v[64:65], s[8:9]
	v_mov_b64_e32 v[60:61], s[8:9]
	v_mov_b64_e32 v[32:33], s[8:9]
	v_mov_b64_e32 v[24:25], s[8:9]
	v_mov_b64_e32 v[6:7], s[10:11]
	v_lshl_add_u64 v[22:23], v[164:165], 0, v[20:21]
	global_load_dwordx4 v[210:213], v[22:23], off
	global_load_dwordx4 v[214:217], v[22:23], off offset:64
	v_lshl_add_u64 v[22:23], v[166:167], 0, v[20:21]
	global_load_dwordx4 v[218:221], v[22:23], off
	global_load_dwordx4 v[222:225], v[22:23], off offset:64
	v_lshl_add_u64 v[22:23], v[168:169], 0, v[20:21]
	v_lshl_add_u64 v[22:23], v[170:171], 0, v[20:21]
	v_lshl_add_u64 v[22:23], v[172:173], 0, v[20:21]
	v_lshl_add_u64 v[22:23], v[174:175], 0, v[20:21]
	v_lshl_add_u64 v[22:23], v[176:177], 0, v[20:21]
	v_lshl_add_u64 v[20:21], v[178:179], 0, v[20:21]
	s_nop 0
	v_lshlrev_b64 v[200:201], 2, v[200:201]
	s_waitcnt vmcnt(0)
; __device__ __forceinline__ float bflo(unsigned w) { return __uint_as_float(w << 16); }
; __device__ __forceinline__ float bfhi(unsigned w) { return __uint_as_float(w & 0xffff0000u); }
;     __device__ __forceinline__ void operator()(const Acc& acc, const Unit& u, int wr, int wc, int fr, int fq) const {
;     ...
; #pragma unroll
;         for (int ai = 0; ai < 2; ++ai)
; #pragma unroll
;             for (int m = 0; m < 4; ++m) { const int row = u.pm * 256 + ai * 128 + wr * 64 + m * 16 + fr; float* mp = (float*)(proj + (size_t)row * DIN + M32_COL) + colb;
; #pragma unroll
;                 for (int bj = 0; bj < 2; ++bj) { const u32x4 gw = Gt[ai][m][bj];
;                     const f32x4 g0 = {bflo(gw.x), bfhi(gw.x), bflo(gw.y), bfhi(gw.y)}, g1 = {bflo(gw.z), bfhi(gw.z), bflo(gw.w), bfhi(gw.w)};
;                     *(f32x4*)(mp + bj * 32) = acc[ai][bj][m][0] * g0; *(f32x4*)(mp + bj * 32 + 4) = acc[ai][bj][m][1] * g1; } }
	v_lshlrev_b32_e32 v240, 16, v210
	v_and_b32_e32 v241, 0xffff0000, v210
	v_lshlrev_b32_e32 v210, 16, v211
	v_and_b32_e32 v211, 0xffff0000, v211
	v_lshl_add_u64 v[206:207], v[180:181], 0, v[200:201]
	v_lshlrev_b32_e32 v242, 16, v212
	v_and_b32_e32 v243, 0xffff0000, v212
	v_lshlrev_b32_e32 v212, 16, v213
	v_and_b32_e32 v213, 0xffff0000, v213
	v_pk_mul_f32 v[18:19], v[18:19], v[210:211]
	v_pk_mul_f32 v[16:17], v[16:17], v[240:241]
	global_store_dwordx4 v[206:207], v[16:19], off
	s_nop 1
	v_pk_mul_f32 v[18:19], v[38:39], v[212:213]
	v_pk_mul_f32 v[16:17], v[36:37], v[242:243]
	global_store_dwordx4 v[206:207], v[16:19], off offset:16
	s_waitcnt vmcnt(16)
	v_lshlrev_b32_e32 v36, 16, v216
	v_and_b32_e32 v37, 0xffff0000, v216
	v_lshlrev_b32_e32 v16, 16, v214
	v_and_b32_e32 v17, 0xffff0000, v214
	v_lshlrev_b32_e32 v18, 16, v215
	v_and_b32_e32 v19, 0xffff0000, v215
	v_lshlrev_b32_e32 v38, 16, v217
	v_and_b32_e32 v39, 0xffff0000, v217
	v_pk_mul_f32 v[18:19], v[102:103], v[18:19]
	v_pk_mul_f32 v[16:17], v[100:101], v[16:17]
	global_store_dwordx4 v[206:207], v[16:19], off offset:128
	s_waitcnt vmcnt(16)
	v_lshlrev_b32_e32 v100, 16, v221
	v_and_b32_e32 v101, 0xffff0000, v221
	v_pk_mul_f32 v[18:19], v[134:135], v[38:39]
	v_pk_mul_f32 v[16:17], v[132:133], v[36:37]
	global_store_dwordx4 v[206:207], v[16:19], off offset:144
	v_lshl_add_u64 v[36:37], v[182:183], 0, v[200:201]
	v_lshlrev_b32_e32 v38, 16, v220
	v_lshlrev_b32_e32 v16, 16, v218
	v_and_b32_e32 v17, 0xffff0000, v218
	v_lshlrev_b32_e32 v18, 16, v219
	v_and_b32_e32 v19, 0xffff0000, v219
	v_and_b32_e32 v39, 0xffff0000, v220
	v_pk_mul_f32 v[18:19], v[30:31], v[18:19]
	v_pk_mul_f32 v[16:17], v[28:29], v[16:17]
	global_store_dwordx4 v[36:37], v[16:19], off
	s_waitcnt vmcnt(17)
	v_lshlrev_b32_e32 v28, 16, v224
	v_and_b32_e32 v29, 0xffff0000, v224
	v_pk_mul_f32 v[18:19], v[58:59], v[100:101]
	v_pk_mul_f32 v[16:17], v[56:57], v[38:39]
	global_store_dwordx4 v[36:37], v[16:19], off offset:16
	v_lshlrev_b32_e32 v30, 16, v225
	v_and_b32_e32 v31, 0xffff0000, v225
	v_lshlrev_b32_e32 v16, 16, v222
	v_and_b32_e32 v17, 0xffff0000, v222
	v_lshlrev_b32_e32 v18, 16, v223
	v_and_b32_e32 v19, 0xffff0000, v223
	v_pk_mul_f32 v[18:19], v[130:131], v[18:19]
	v_pk_mul_f32 v[16:17], v[128:129], v[16:17]
	global_store_dwordx4 v[36:37], v[16:19], off offset:128
	s_nop 1
	v_pk_mul_f32 v[18:19], v[142:143], v[30:31]
	v_pk_mul_f32 v[16:17], v[140:141], v[28:29]
	global_store_dwordx4 v[36:37], v[16:19], off offset:144
	s_branch .LBB0_1469
	v_lshl_add_u64 v[28:29], v[184:185], 0, v[200:201]
	s_waitcnt vmcnt(19)
	v_lshlrev_b32_e32 v30, 16, v228
	v_lshlrev_b32_e32 v16, 16, v226
	v_and_b32_e32 v17, 0xffff0000, v226
	v_lshlrev_b32_e32 v18, 16, v227
	v_and_b32_e32 v19, 0xffff0000, v227
	v_and_b32_e32 v31, 0xffff0000, v228
	v_lshlrev_b32_e32 v36, 16, v229
	v_and_b32_e32 v37, 0xffff0000, v229
	v_pk_mul_f32 v[18:19], v[158:159], v[18:19]
	v_pk_mul_f32 v[16:17], v[156:157], v[16:17]
	global_store_dwordx4 v[28:29], v[16:19], off
	s_nop 1
	v_pk_mul_f32 v[18:19], v[146:147], v[36:37]
	v_pk_mul_f32 v[16:17], v[144:145], v[30:31]
	global_store_dwordx4 v[28:29], v[16:19], off offset:16
	s_waitcnt vmcnt(20)
	v_lshlrev_b32_e32 v30, 16, v232
	v_and_b32_e32 v31, 0xffff0000, v232
	v_lshlrev_b32_e32 v16, 16, v230
	v_and_b32_e32 v17, 0xffff0000, v230
	v_lshlrev_b32_e32 v18, 16, v231
	v_and_b32_e32 v19, 0xffff0000, v231
	v_lshlrev_b32_e32 v36, 16, v233
	v_and_b32_e32 v37, 0xffff0000, v233
	v_pk_mul_f32 v[18:19], v[162:163], v[18:19]
	v_pk_mul_f32 v[16:17], v[160:161], v[16:17]
	global_store_dwordx4 v[28:29], v[16:19], off offset:128
	s_nop 1
	v_pk_mul_f32 v[18:19], v[150:151], v[36:37]
	v_pk_mul_f32 v[16:17], v[148:149], v[30:31]
	global_store_dwordx4 v[28:29], v[16:19], off offset:144
	v_lshl_add_u64 v[28:29], v[186:187], 0, v[200:201]
	s_waitcnt vmcnt(21)
	v_lshlrev_b32_e32 v30, 16, v238
	v_lshlrev_b32_e32 v16, 16, v236
	v_and_b32_e32 v17, 0xffff0000, v236
	v_lshlrev_b32_e32 v18, 16, v237
	v_and_b32_e32 v19, 0xffff0000, v237
	v_and_b32_e32 v31, 0xffff0000, v238
	v_lshlrev_b32_e32 v36, 16, v239
	v_and_b32_e32 v37, 0xffff0000, v239
	v_pk_mul_f32 v[18:19], v[122:123], v[18:19]
	v_pk_mul_f32 v[16:17], v[120:121], v[16:17]
	global_store_dwordx4 v[28:29], v[16:19], off
	s_nop 1
	v_pk_mul_f32 v[18:19], v[110:111], v[36:37]
	v_pk_mul_f32 v[16:17], v[108:109], v[30:31]
	global_store_dwordx4 v[28:29], v[16:19], off offset:16
	s_waitcnt vmcnt(22)
	v_lshlrev_b32_e32 v30, 16, v154
	v_and_b32_e32 v31, 0xffff0000, v154
	v_lshlrev_b32_e32 v16, 16, v152
	v_and_b32_e32 v17, 0xffff0000, v152
	v_lshlrev_b32_e32 v18, 16, v153
	v_and_b32_e32 v19, 0xffff0000, v153
	v_lshlrev_b32_e32 v36, 16, v155
	v_and_b32_e32 v37, 0xffff0000, v155
	v_pk_mul_f32 v[18:19], v[126:127], v[18:19]
	v_pk_mul_f32 v[16:17], v[124:125], v[16:17]
	global_store_dwordx4 v[28:29], v[16:19], off offset:128
	s_nop 1
	v_pk_mul_f32 v[18:19], v[114:115], v[36:37]
	v_pk_mul_f32 v[16:17], v[112:113], v[30:31]
	global_store_dwordx4 v[28:29], v[16:19], off offset:144
	v_lshl_add_u64 v[28:29], v[188:189], 0, v[200:201]
	s_waitcnt vmcnt(23)
; __device__ __forceinline__ float bflo(unsigned w) { return __uint_as_float(w << 16); }
; __device__ __forceinline__ float bfhi(unsigned w) { return __uint_as_float(w & 0xffff0000u); }
;     __device__ __forceinline__ void operator()(const Acc& acc, const Unit& u, int wr, int wc, int fr, int fq) const {
;     ...
; #pragma unroll
;         for (int ai = 0; ai < 2; ++ai)
; #pragma unroll
;             for (int m = 0; m < 4; ++m) { const int row = u.pm * 256 + ai * 128 + wr * 64 + m * 16 + fr; float* mp = (float*)(proj + (size_t)row * DIN + M32_COL) + colb;
; #pragma unroll
;                 for (int bj = 0; bj < 2; ++bj) { const u32x4 gw = Gt[ai][m][bj];
;                     const f32x4 g0 = {bflo(gw.x), bfhi(gw.x), bflo(gw.y), bfhi(gw.y)}, g1 = {bflo(gw.z), bfhi(gw.z), bflo(gw.w), bfhi(gw.w)};
;                     *(f32x4*)(mp + bj * 32) = acc[ai][bj][m][0] * g0; *(f32x4*)(mp + bj * 32 + 4) = acc[ai][bj][m][1] * g1; } }
	v_lshlrev_b32_e32 v30, 16, v138
	v_lshlrev_b32_e32 v16, 16, v136
	v_and_b32_e32 v17, 0xffff0000, v136
	v_lshlrev_b32_e32 v18, 16, v137
	v_and_b32_e32 v19, 0xffff0000, v137
	v_and_b32_e32 v31, 0xffff0000, v138
	v_lshlrev_b32_e32 v36, 16, v139
	v_and_b32_e32 v37, 0xffff0000, v139
	v_pk_mul_f32 v[18:19], v[106:107], v[18:19]
	v_pk_mul_f32 v[16:17], v[104:105], v[16:17]
	global_store_dwordx4 v[28:29], v[16:19], off
	s_nop 1
	v_pk_mul_f32 v[18:19], v[94:95], v[36:37]
	v_pk_mul_f32 v[16:17], v[92:93], v[30:31]
	global_store_dwordx4 v[28:29], v[16:19], off offset:16
	s_waitcnt vmcnt(24)
	v_lshlrev_b32_e32 v30, 16, v118
	v_and_b32_e32 v31, 0xffff0000, v118
	v_lshlrev_b32_e32 v16, 16, v116
	v_and_b32_e32 v17, 0xffff0000, v116
	v_lshlrev_b32_e32 v18, 16, v117
	v_and_b32_e32 v19, 0xffff0000, v117
	v_lshlrev_b32_e32 v36, 16, v119
	v_and_b32_e32 v37, 0xffff0000, v119
	v_pk_mul_f32 v[18:19], v[90:91], v[18:19]
	v_pk_mul_f32 v[16:17], v[88:89], v[16:17]
	global_store_dwordx4 v[28:29], v[16:19], off offset:128
	s_nop 1
	v_pk_mul_f32 v[18:19], v[86:87], v[36:37]
	v_pk_mul_f32 v[16:17], v[84:85], v[30:31]
	global_store_dwordx4 v[28:29], v[16:19], off offset:144
	v_lshl_add_u64 v[28:29], v[190:191], 0, v[200:201]
	s_waitcnt vmcnt(25)
	v_lshlrev_b32_e32 v30, 16, v98
	v_lshlrev_b32_e32 v16, 16, v96
	v_and_b32_e32 v17, 0xffff0000, v96
	v_lshlrev_b32_e32 v18, 16, v97
	v_and_b32_e32 v19, 0xffff0000, v97
	v_and_b32_e32 v31, 0xffff0000, v98
	v_lshlrev_b32_e32 v36, 16, v99
	v_and_b32_e32 v37, 0xffff0000, v99
	v_pk_mul_f32 v[18:19], v[78:79], v[18:19]
	v_pk_mul_f32 v[16:17], v[76:77], v[16:17]
	global_store_dwordx4 v[28:29], v[16:19], off
	s_nop 1
	v_pk_mul_f32 v[18:19], v[70:71], v[36:37]
	v_pk_mul_f32 v[16:17], v[68:69], v[30:31]
	global_store_dwordx4 v[28:29], v[16:19], off offset:16
	s_waitcnt vmcnt(26)
	v_lshlrev_b32_e32 v30, 16, v82
	v_and_b32_e32 v31, 0xffff0000, v82
	v_lshlrev_b32_e32 v16, 16, v80
	v_and_b32_e32 v17, 0xffff0000, v80
	v_lshlrev_b32_e32 v18, 16, v81
	v_and_b32_e32 v19, 0xffff0000, v81
	v_lshlrev_b32_e32 v36, 16, v83
	v_and_b32_e32 v37, 0xffff0000, v83
	v_pk_mul_f32 v[18:19], v[66:67], v[18:19]
	v_pk_mul_f32 v[16:17], v[64:65], v[16:17]
	global_store_dwordx4 v[28:29], v[16:19], off offset:128
	s_nop 1
	v_pk_mul_f32 v[18:19], v[62:63], v[36:37]
	v_pk_mul_f32 v[16:17], v[60:61], v[30:31]
	global_store_dwordx4 v[28:29], v[16:19], off offset:144
	v_lshl_add_u64 v[28:29], v[192:193], 0, v[200:201]
	s_waitcnt vmcnt(27)
	v_lshlrev_b32_e32 v30, 16, v74
	v_lshlrev_b32_e32 v16, 16, v72
	v_and_b32_e32 v17, 0xffff0000, v72
	v_lshlrev_b32_e32 v18, 16, v73
	v_and_b32_e32 v19, 0xffff0000, v73
	v_and_b32_e32 v31, 0xffff0000, v74
	v_lshlrev_b32_e32 v36, 16, v75
	v_and_b32_e32 v37, 0xffff0000, v75
	v_pk_mul_f32 v[18:19], v[50:51], v[18:19]
	v_pk_mul_f32 v[16:17], v[48:49], v[16:17]
	global_store_dwordx4 v[28:29], v[16:19], off
	s_nop 1
	v_pk_mul_f32 v[18:19], v[42:43], v[36:37]
	v_pk_mul_f32 v[16:17], v[40:41], v[30:31]
	global_store_dwordx4 v[28:29], v[16:19], off offset:16
	s_waitcnt vmcnt(28)
	v_lshlrev_b32_e32 v30, 16, v54
	v_and_b32_e32 v31, 0xffff0000, v54
	v_lshlrev_b32_e32 v16, 16, v52
	v_and_b32_e32 v17, 0xffff0000, v52
	v_lshlrev_b32_e32 v18, 16, v53
	v_and_b32_e32 v19, 0xffff0000, v53
	v_lshlrev_b32_e32 v36, 16, v55
	v_and_b32_e32 v37, 0xffff0000, v55
	v_pk_mul_f32 v[18:19], v[34:35], v[18:19]
	v_pk_mul_f32 v[16:17], v[32:33], v[16:17]
	global_store_dwordx4 v[28:29], v[16:19], off offset:128
	s_nop 1
	v_pk_mul_f32 v[18:19], v[26:27], v[36:37]
	v_pk_mul_f32 v[16:17], v[24:25], v[30:31]
	global_store_dwordx4 v[28:29], v[16:19], off offset:144
	s_waitcnt vmcnt(29)
	v_lshlrev_b32_e32 v24, 16, v45
	v_and_b32_e32 v25, 0xffff0000, v45
	v_lshlrev_b32_e32 v18, 16, v44
	v_and_b32_e32 v19, 0xffff0000, v44
	v_lshlrev_b32_e32 v26, 16, v46
	v_and_b32_e32 v27, 0xffff0000, v46
	v_lshlrev_b32_e32 v28, 16, v47
	v_and_b32_e32 v29, 0xffff0000, v47
	v_lshl_add_u64 v[16:17], v[194:195], 0, v[200:201]
	v_pk_mul_f32 v[14:15], v[14:15], v[24:25]
	v_pk_mul_f32 v[12:13], v[12:13], v[18:19]
	v_pk_mul_f32 v[10:11], v[10:11], v[28:29]
	v_pk_mul_f32 v[8:9], v[8:9], v[26:27]
	global_store_dwordx4 v[16:17], v[12:15], off
	global_store_dwordx4 v[16:17], v[8:11], off offset:16
	s_waitcnt vmcnt(30)
	v_lshlrev_b32_e32 v12, 16, v22
	v_lshlrev_b32_e32 v8, 16, v20
	v_and_b32_e32 v9, 0xffff0000, v20
	v_lshlrev_b32_e32 v10, 16, v21
	v_and_b32_e32 v11, 0xffff0000, v21
	v_and_b32_e32 v13, 0xffff0000, v22
	v_lshlrev_b32_e32 v14, 16, v23
	v_and_b32_e32 v15, 0xffff0000, v23
	v_pk_mul_f32 v[6:7], v[6:7], v[10:11]
	v_pk_mul_f32 v[4:5], v[4:5], v[8:9]
	v_pk_mul_f32 v[2:3], v[2:3], v[14:15]
	v_pk_mul_f32 v[0:1], v[0:1], v[12:13]
	global_store_dwordx4 v[16:17], v[4:7], off offset:128
	global_store_dwordx4 v[16:17], v[0:3], off offset:144
	s_branch .LBB0_1469

; #define LAS __attribute__((address_space(3)))
; #define SCHED_BAR() __builtin_amdgcn_sched_barrier(0)
; template <class Epi>
; __device__ __forceinline__ void skinny_phase(LAS unsigned char* lds, const pg8::Gemm g, const Epi& E, int G, int bx) {
;     ...
;         LAS f32x4* red = (LAS f32x4*)lds;
;         __syncthreads();
; #pragma unroll
;         for (int b = 0; b < 2; ++b)
; #pragma unroll
;             for (int m = 0; m < 2; ++m)
; #pragma unroll
;                 for (int n = 0; n < 2; ++n) red[(((b * 2 + m) * 2 + n) * 8 + wid) * 64 + lane] = a8[b][m][n];
;         __syncthreads();
;         if (wid == 0) {
;             Acc acc;
; #pragma unroll
;             for (int a = 0; a < 2; ++a)
; #pragma unroll
;                 for (int b = 0; b < 2; ++b)
; #pragma unroll
;                     for (int m = 0; m < 4; ++m)
; #pragma unroll
;                         for (int n = 0; n < 2; ++n) acc[a][b][m][n] = (f32x4){0.f, 0.f, 0.f, 0.f};
; #pragma unroll
;             for (int b = 0; b < 2; ++b)
; #pragma unroll
;                 for (int m = 0; m < 2; ++m)
; #pragma unroll
;                     for (int n = 0; n < 2; ++n) { f32x4 t = {0.f, 0.f, 0.f, 0.f};
; #pragma unroll
;                         for (int w8 = 0; w8 < 8; ++w8) t += red[(((b * 2 + m) * 2 + n) * 8 + w8) * 64 + lane];
;                         acc[0][b][m][n] = t; SCHED_BAR(); }
.LBB0_1525:
	s_and_b64 vcc, exec, s[12:13]
	s_barrier
	ds_write_b128 v187, v[28:31]
	ds_write_b128 v187, v[24:27] offset:8192
	ds_write_b128 v187, v[20:23] offset:16384
	ds_write_b128 v187, v[16:19] offset:24576
	ds_write_b128 v187, v[12:15] offset:32768
	ds_write_b128 v187, v[8:11] offset:40960
	ds_write_b128 v187, v[4:7] offset:49152
	ds_write_b128 v187, v[0:3] offset:57344
	s_waitcnt lgkmcnt(0)
	s_barrier
	s_cbranch_vccz .LBB0_1512
	ds_read_b128 v[0:3], v185
	ds_read_b128 v[4:7], v185 offset:1024
	ds_read_b128 v[8:11], v185 offset:2048
	ds_read_b128 v[12:15], v185 offset:3072
	s_waitcnt lgkmcnt(3)
	v_pk_add_f32 v[2:3], v[2:3], 0 op_sel_hi:[1,0]
	v_pk_add_f32 v[0:1], v[0:1], 0 op_sel_hi:[1,0]
	s_waitcnt lgkmcnt(2)
	v_pk_add_f32 v[2:3], v[2:3], v[6:7]
	v_pk_add_f32 v[4:5], v[0:1], v[4:5]
	s_waitcnt lgkmcnt(1)
	v_pk_add_f32 v[6:7], v[2:3], v[10:11]
	ds_read_b128 v[0:3], v185 offset:4096
	v_pk_add_f32 v[4:5], v[4:5], v[8:9]
	s_waitcnt lgkmcnt(1)
	v_pk_add_f32 v[8:9], v[6:7], v[14:15]
	v_pk_add_f32 v[12:13], v[4:5], v[12:13]
	ds_read_b128 v[4:7], v185 offset:5120
	s_waitcnt lgkmcnt(1)
	v_pk_add_f32 v[14:15], v[8:9], v[2:3]
	ds_read_b128 v[8:11], v185 offset:6144
	v_pk_add_f32 v[12:13], v[12:13], v[0:1]
	ds_read_b128 v[0:3], v185 offset:7168
	s_waitcnt lgkmcnt(2)
	v_pk_add_f32 v[6:7], v[14:15], v[6:7]
	v_pk_add_f32 v[4:5], v[12:13], v[4:5]
	s_waitcnt lgkmcnt(1)
	v_pk_add_f32 v[6:7], v[6:7], v[10:11]
	v_pk_add_f32 v[4:5], v[4:5], v[8:9]
	s_waitcnt lgkmcnt(0)
	v_pk_add_f32 v[50:51], v[6:7], v[2:3]
	v_pk_add_f32 v[48:49], v[4:5], v[0:1]
	ds_read_b128 v[0:3], v185 offset:8192
	ds_read_b128 v[4:7], v185 offset:9216
	ds_read_b128 v[8:11], v185 offset:10240
	ds_read_b128 v[12:15], v185 offset:11264
	s_waitcnt lgkmcnt(3)
	v_pk_add_f32 v[2:3], v[2:3], 0 op_sel_hi:[1,0]
	v_pk_add_f32 v[0:1], v[0:1], 0 op_sel_hi:[1,0]
	s_waitcnt lgkmcnt(2)
	v_pk_add_f32 v[2:3], v[2:3], v[6:7]
	v_pk_add_f32 v[4:5], v[0:1], v[4:5]
	s_waitcnt lgkmcnt(1)
	v_pk_add_f32 v[6:7], v[2:3], v[10:11]
	ds_read_b128 v[0:3], v185 offset:12288
	v_pk_add_f32 v[4:5], v[4:5], v[8:9]
	s_waitcnt lgkmcnt(1)
	v_pk_add_f32 v[8:9], v[6:7], v[14:15]
	v_pk_add_f32 v[12:13], v[4:5], v[12:13]
	ds_read_b128 v[4:7], v185 offset:13312
	s_waitcnt lgkmcnt(1)
	v_pk_add_f32 v[14:15], v[8:9], v[2:3]
	ds_read_b128 v[8:11], v185 offset:14336
	v_pk_add_f32 v[12:13], v[12:13], v[0:1]
	ds_read_b128 v[0:3], v185 offset:15360
	s_waitcnt lgkmcnt(2)
	v_pk_add_f32 v[6:7], v[14:15], v[6:7]
	v_pk_add_f32 v[4:5], v[12:13], v[4:5]
	s_waitcnt lgkmcnt(1)
	v_pk_add_f32 v[6:7], v[6:7], v[10:11]
	v_pk_add_f32 v[4:5], v[4:5], v[8:9]
	s_waitcnt vmcnt(0) lgkmcnt(0)
	v_pk_add_f32 v[66:67], v[6:7], v[2:3]
	v_pk_add_f32 v[64:65], v[4:5], v[0:1]
	ds_read_b128 v[0:3], v185 offset:16384
	ds_read_b128 v[4:7], v185 offset:17408
	ds_read_b128 v[8:11], v185 offset:18432
	ds_read_b128 v[12:15], v185 offset:19456
	s_waitcnt lgkmcnt(3)
	v_pk_add_f32 v[2:3], v[2:3], 0 op_sel_hi:[1,0]
	v_pk_add_f32 v[0:1], v[0:1], 0 op_sel_hi:[1,0]
	s_waitcnt lgkmcnt(2)
	v_pk_add_f32 v[2:3], v[2:3], v[6:7]
	v_pk_add_f32 v[4:5], v[0:1], v[4:5]
	s_waitcnt lgkmcnt(1)
	v_pk_add_f32 v[6:7], v[2:3], v[10:11]
	ds_read_b128 v[0:3], v185 offset:20480
	v_pk_add_f32 v[4:5], v[4:5], v[8:9]
	s_waitcnt lgkmcnt(1)
	v_pk_add_f32 v[8:9], v[6:7], v[14:15]
	v_pk_add_f32 v[12:13], v[4:5], v[12:13]
	ds_read_b128 v[4:7], v185 offset:21504
	s_waitcnt lgkmcnt(1)
	v_pk_add_f32 v[14:15], v[8:9], v[2:3]
	ds_read_b128 v[8:11], v185 offset:22528
	v_pk_add_f32 v[12:13], v[12:13], v[0:1]
	ds_read_b128 v[0:3], v185 offset:23552
	s_waitcnt lgkmcnt(2)
	v_pk_add_f32 v[6:7], v[14:15], v[6:7]
	v_pk_add_f32 v[4:5], v[12:13], v[4:5]
	s_waitcnt lgkmcnt(1)
	v_pk_add_f32 v[6:7], v[6:7], v[10:11]
	v_pk_add_f32 v[4:5], v[4:5], v[8:9]
	s_waitcnt lgkmcnt(0)
	v_pk_add_f32 v[54:55], v[6:7], v[2:3]
	v_pk_add_f32 v[52:53], v[4:5], v[0:1]
	ds_read_b128 v[0:3], v185 offset:24576
	ds_read_b128 v[4:7], v185 offset:25600
	ds_read_b128 v[8:11], v185 offset:26624
	ds_read_b128 v[12:15], v185 offset:27648
	s_waitcnt lgkmcnt(3)
	v_pk_add_f32 v[2:3], v[2:3], 0 op_sel_hi:[1,0]
	v_pk_add_f32 v[0:1], v[0:1], 0 op_sel_hi:[1,0]
	s_waitcnt lgkmcnt(2)
	v_pk_add_f32 v[2:3], v[2:3], v[6:7]
	v_pk_add_f32 v[4:5], v[0:1], v[4:5]
	s_waitcnt lgkmcnt(1)
	v_pk_add_f32 v[6:7], v[2:3], v[10:11]
	ds_read_b128 v[0:3], v185 offset:28672
	v_pk_add_f32 v[4:5], v[4:5], v[8:9]
	s_waitcnt lgkmcnt(1)
	v_pk_add_f32 v[8:9], v[6:7], v[14:15]
	v_pk_add_f32 v[12:13], v[4:5], v[12:13]
	ds_read_b128 v[4:7], v185 offset:29696
	s_waitcnt lgkmcnt(1)
	v_pk_add_f32 v[14:15], v[8:9], v[2:3]
	ds_read_b128 v[8:11], v185 offset:30720
	v_pk_add_f32 v[12:13], v[12:13], v[0:1]
	ds_read_b128 v[0:3], v185 offset:31744
	s_waitcnt lgkmcnt(2)
	v_pk_add_f32 v[6:7], v[14:15], v[6:7]
	v_pk_add_f32 v[4:5], v[12:13], v[4:5]
	s_waitcnt lgkmcnt(1)
	v_pk_add_f32 v[6:7], v[6:7], v[10:11]
	v_pk_add_f32 v[4:5], v[4:5], v[8:9]
	s_waitcnt lgkmcnt(0)
	v_pk_add_f32 v[78:79], v[6:7], v[2:3]
	v_pk_add_f32 v[76:77], v[4:5], v[0:1]
	ds_read_b128 v[0:3], v185 offset:32768
	ds_read_b128 v[4:7], v185 offset:33792
	ds_read_b128 v[8:11], v185 offset:34816
	ds_read_b128 v[12:15], v185 offset:35840
	s_waitcnt lgkmcnt(3)
	v_pk_add_f32 v[2:3], v[2:3], 0 op_sel_hi:[1,0]
	v_pk_add_f32 v[0:1], v[0:1], 0 op_sel_hi:[1,0]
	s_waitcnt lgkmcnt(2)
	v_pk_add_f32 v[2:3], v[2:3], v[6:7]
	v_pk_add_f32 v[4:5], v[0:1], v[4:5]
	s_waitcnt lgkmcnt(1)
	v_pk_add_f32 v[6:7], v[2:3], v[10:11]
	ds_read_b128 v[0:3], v185 offset:36864
	v_pk_add_f32 v[4:5], v[4:5], v[8:9]
	s_waitcnt lgkmcnt(1)
	v_pk_add_f32 v[8:9], v[6:7], v[14:15]
	v_pk_add_f32 v[12:13], v[4:5], v[12:13]
	ds_read_b128 v[4:7], v185 offset:37888
	s_waitcnt lgkmcnt(1)
; #define SCHED_BAR() __builtin_amdgcn_sched_barrier(0)
;     __device__ __forceinline__ void operator()(const Acc& acc, const Unit& u, int wr, int wc, int fr, int fq) const {
;     ...
; #pragma unroll
;         for (int ai = 0; ai < 2; ++ai)
; #pragma unroll
;             for (int mh = 0; mh < 2; ++mh) {
;                 u32x4 Gt[2][2]; f32x4 Mv[2][2][2];
; #pragma unroll
;                 for (int m2 = 0; m2 < 2; ++m2) { const int row = u.pm * 256 + ai * 128 + wr * 64 + (2 * mh + m2) * 16 + fr;
;                     const bf16_t* gp = proj + (size_t)row * DIN + GB_OFF + colb; const float* mp = (const float*)(proj + (size_t)row * DIN + M32_COL) + colb;
; #pragma unroll
;                     for (int bj = 0; bj < 2; ++bj) { Gt[m2][bj] = *(const u32x4*)(gp + bj * 32); Mv[m2][bj][0] = *(const f32x4*)(mp + bj * 32); Mv[m2][bj][1] = *(const f32x4*)(mp + bj * 32 + 4); } }
; template <class Epi>
; __device__ __forceinline__ void skinny_phase(LAS unsigned char* lds, const pg8::Gemm g, const Epi& E, int G, int bx) {
;     ...
; #pragma unroll
;             for (int a = 0; a < 2; ++a)
; #pragma unroll
;                 for (int b = 0; b < 2; ++b)
; #pragma unroll
;                     for (int m = 0; m < 4; ++m)
; #pragma unroll
;                         for (int n = 0; n < 2; ++n) acc[a][b][m][n] = (f32x4){0.f, 0.f, 0.f, 0.f};
; #pragma unroll
;             for (int b = 0; b < 2; ++b)
; #pragma unroll
;                 for (int m = 0; m < 2; ++m)
; #pragma unroll
;                     for (int n = 0; n < 2; ++n) { f32x4 t = {0.f, 0.f, 0.f, 0.f};
; #pragma unroll
;                         for (int w8 = 0; w8 < 8; ++w8) t += red[(((b * 2 + m) * 2 + n) * 8 + w8) * 64 + lane];
;                         acc[0][b][m][n] = t; SCHED_BAR(); }
	v_pk_add_f32 v[14:15], v[8:9], v[2:3]
	ds_read_b128 v[8:11], v185 offset:38912
	v_pk_add_f32 v[12:13], v[12:13], v[0:1]
	ds_read_b128 v[0:3], v185 offset:39936
	s_waitcnt lgkmcnt(2)
	v_pk_add_f32 v[6:7], v[14:15], v[6:7]
	v_pk_add_f32 v[4:5], v[12:13], v[4:5]
	s_waitcnt lgkmcnt(1)
	v_pk_add_f32 v[6:7], v[6:7], v[10:11]
	v_pk_add_f32 v[4:5], v[4:5], v[8:9]
	s_waitcnt lgkmcnt(0)
	v_pk_add_f32 v[98:99], v[6:7], v[2:3]
	v_pk_add_f32 v[96:97], v[4:5], v[0:1]
	ds_read_b128 v[0:3], v185 offset:40960
	ds_read_b128 v[4:7], v185 offset:41984
	ds_read_b128 v[8:11], v185 offset:43008
	ds_read_b128 v[12:15], v185 offset:44032
	s_waitcnt lgkmcnt(3)
	v_pk_add_f32 v[2:3], v[2:3], 0 op_sel_hi:[1,0]
	v_pk_add_f32 v[0:1], v[0:1], 0 op_sel_hi:[1,0]
	s_waitcnt lgkmcnt(2)
	v_pk_add_f32 v[2:3], v[2:3], v[6:7]
	v_pk_add_f32 v[4:5], v[0:1], v[4:5]
	s_waitcnt lgkmcnt(1)
	v_pk_add_f32 v[6:7], v[2:3], v[10:11]
	ds_read_b128 v[0:3], v185 offset:45056
	v_pk_add_f32 v[4:5], v[4:5], v[8:9]
	s_waitcnt lgkmcnt(1)
	v_pk_add_f32 v[8:9], v[6:7], v[14:15]
	v_pk_add_f32 v[12:13], v[4:5], v[12:13]
	ds_read_b128 v[4:7], v185 offset:46080
	s_waitcnt lgkmcnt(1)
	v_pk_add_f32 v[14:15], v[8:9], v[2:3]
	ds_read_b128 v[8:11], v185 offset:47104
	v_pk_add_f32 v[12:13], v[12:13], v[0:1]
	ds_read_b128 v[0:3], v185 offset:48128
	s_waitcnt lgkmcnt(2)
	v_pk_add_f32 v[6:7], v[14:15], v[6:7]
	v_pk_add_f32 v[4:5], v[12:13], v[4:5]
	s_waitcnt lgkmcnt(1)
	v_pk_add_f32 v[6:7], v[6:7], v[10:11]
	v_pk_add_f32 v[4:5], v[4:5], v[8:9]
	s_waitcnt lgkmcnt(0)
	v_pk_add_f32 v[122:123], v[6:7], v[2:3]
	v_pk_add_f32 v[120:121], v[4:5], v[0:1]
	ds_read_b128 v[0:3], v185 offset:49152
	ds_read_b128 v[4:7], v185 offset:50176
	ds_read_b128 v[8:11], v185 offset:51200
	ds_read_b128 v[12:15], v185 offset:52224
	s_waitcnt lgkmcnt(3)
	v_pk_add_f32 v[2:3], v[2:3], 0 op_sel_hi:[1,0]
	v_pk_add_f32 v[0:1], v[0:1], 0 op_sel_hi:[1,0]
	s_waitcnt lgkmcnt(2)
	v_pk_add_f32 v[2:3], v[2:3], v[6:7]
	v_pk_add_f32 v[4:5], v[0:1], v[4:5]
	s_waitcnt lgkmcnt(1)
	v_pk_add_f32 v[6:7], v[2:3], v[10:11]
	ds_read_b128 v[0:3], v185 offset:53248
	v_pk_add_f32 v[4:5], v[4:5], v[8:9]
	s_waitcnt lgkmcnt(1)
	v_pk_add_f32 v[8:9], v[6:7], v[14:15]
	v_pk_add_f32 v[12:13], v[4:5], v[12:13]
	ds_read_b128 v[4:7], v185 offset:54272
	s_waitcnt lgkmcnt(1)
	v_pk_add_f32 v[14:15], v[8:9], v[2:3]
	ds_read_b128 v[8:11], v185 offset:55296
	v_pk_add_f32 v[12:13], v[12:13], v[0:1]
	ds_read_b128 v[0:3], v185 offset:56320
	s_waitcnt lgkmcnt(2)
	v_pk_add_f32 v[6:7], v[14:15], v[6:7]
	v_pk_add_f32 v[4:5], v[12:13], v[4:5]
	s_waitcnt lgkmcnt(1)
	v_pk_add_f32 v[6:7], v[6:7], v[10:11]
	v_pk_add_f32 v[4:5], v[4:5], v[8:9]
	s_waitcnt lgkmcnt(0)
	v_pk_add_f32 v[102:103], v[6:7], v[2:3]
	v_pk_add_f32 v[100:101], v[4:5], v[0:1]
	ds_read_b128 v[0:3], v185 offset:57344
	ds_read_b128 v[4:7], v185 offset:58368
	ds_read_b128 v[8:11], v185 offset:59392
	ds_read_b128 v[12:15], v185 offset:60416
	s_waitcnt lgkmcnt(3)
	v_pk_add_f32 v[2:3], v[2:3], 0 op_sel_hi:[1,0]
	v_pk_add_f32 v[0:1], v[0:1], 0 op_sel_hi:[1,0]
	s_waitcnt lgkmcnt(2)
	v_pk_add_f32 v[2:3], v[2:3], v[6:7]
	v_pk_add_f32 v[4:5], v[0:1], v[4:5]
	s_waitcnt lgkmcnt(1)
	v_pk_add_f32 v[6:7], v[2:3], v[10:11]
	ds_read_b128 v[0:3], v185 offset:61440
	v_pk_add_f32 v[4:5], v[4:5], v[8:9]
	s_waitcnt lgkmcnt(1)
	v_pk_add_f32 v[8:9], v[6:7], v[14:15]
	v_pk_add_f32 v[12:13], v[4:5], v[12:13]
	ds_read_b128 v[4:7], v185 offset:62464
	s_waitcnt lgkmcnt(1)
	v_pk_add_f32 v[14:15], v[8:9], v[2:3]
	ds_read_b128 v[8:11], v185 offset:63488
	v_pk_add_f32 v[12:13], v[12:13], v[0:1]
	ds_read_b128 v[0:3], v185 offset:64512
	s_waitcnt lgkmcnt(2)
	v_pk_add_f32 v[6:7], v[14:15], v[6:7]
	v_pk_add_f32 v[4:5], v[12:13], v[4:5]
	s_waitcnt lgkmcnt(1)
	v_pk_add_f32 v[6:7], v[6:7], v[10:11]
	v_pk_add_f32 v[4:5], v[4:5], v[8:9]
	s_waitcnt lgkmcnt(0)
	v_pk_add_f32 v[126:127], v[6:7], v[2:3]
	v_pk_add_f32 v[124:125], v[4:5], v[0:1]
	v_lshl_or_b32 v182, s20, 6, v186
	s_mov_b32 s9, s8
	s_mov_b32 s10, s8
	s_mov_b32 s11, s8
	v_ashrrev_i32_e32 v183, 31, v182
	v_mov_b64_e32 v[0:1], s[8:9]
	v_mov_b64_e32 v[118:119], s[10:11]
	v_mov_b64_e32 v[114:115], s[10:11]
	v_mov_b64_e32 v[94:95], s[10:11]
	v_mov_b64_e32 v[90:91], s[10:11]
	v_mov_b64_e32 v[110:111], s[10:11]
	v_mov_b64_e32 v[106:107], s[10:11]
	v_mov_b64_e32 v[86:87], s[10:11]
	v_mov_b64_e32 v[82:83], s[10:11]
	v_mov_b64_e32 v[74:75], s[10:11]
	v_mov_b64_e32 v[70:71], s[10:11]
	v_mov_b64_e32 v[46:47], s[10:11]
	v_mov_b64_e32 v[42:43], s[10:11]
	v_mov_b64_e32 v[30:31], s[10:11]
	v_mov_b64_e32 v[26:27], s[10:11]
	v_mov_b64_e32 v[14:15], s[10:11]
	v_mov_b64_e32 v[8:9], s[8:9]
	v_mov_b64_e32 v[62:63], s[10:11]
	v_mov_b64_e32 v[58:59], s[10:11]
	v_mov_b64_e32 v[38:39], s[10:11]
	v_mov_b64_e32 v[34:35], s[10:11]
	v_mov_b64_e32 v[22:23], s[10:11]
	v_mov_b64_e32 v[18:19], s[10:11]
	v_mov_b64_e32 v[4:5], s[8:9]
	v_lshlrev_b64 v[180:181], 1, v[182:183]
	v_lshlrev_b64 v[182:183], 2, v[182:183]
	v_mov_b64_e32 v[2:3], s[10:11]
	v_mov_b64_e32 v[116:117], s[8:9]
	v_mov_b64_e32 v[112:113], s[8:9]
	v_mov_b64_e32 v[92:93], s[8:9]
	v_mov_b64_e32 v[88:89], s[8:9]
	v_mov_b64_e32 v[108:109], s[8:9]
	v_mov_b64_e32 v[104:105], s[8:9]
	v_mov_b64_e32 v[84:85], s[8:9]
	v_mov_b64_e32 v[80:81], s[8:9]
	v_mov_b64_e32 v[72:73], s[8:9]
	v_mov_b64_e32 v[68:69], s[8:9]
	v_mov_b64_e32 v[44:45], s[8:9]
	v_mov_b64_e32 v[40:41], s[8:9]
	v_mov_b64_e32 v[28:29], s[8:9]
	v_mov_b64_e32 v[24:25], s[8:9]
	v_mov_b64_e32 v[12:13], s[8:9]
	v_mov_b64_e32 v[10:11], s[10:11]
	v_mov_b64_e32 v[60:61], s[8:9]
	v_mov_b64_e32 v[56:57], s[8:9]
	v_mov_b64_e32 v[36:37], s[8:9]
	v_mov_b64_e32 v[32:33], s[8:9]
	v_mov_b64_e32 v[20:21], s[8:9]
	v_mov_b64_e32 v[16:17], s[8:9]
	v_mov_b64_e32 v[6:7], s[10:11]
	v_lshl_add_u64 v[200:201], v[130:131], 0, v[180:181]
	v_lshl_add_u64 v[210:211], v[128:129], 0, v[182:183]
	v_lshl_add_u64 v[226:227], v[134:135], 0, v[180:181]
	v_lshl_add_u64 v[236:237], v[132:133], 0, v[182:183]
	global_load_dwordx4 v[188:191], v[210:211], off offset:1040
	global_load_dwordx4 v[192:195], v[210:211], off offset:1024
	global_load_dwordx4 v[196:199], v[200:201], off
	s_nop 0
	global_load_dwordx4 v[200:203], v[200:201], off offset:64
	s_nop 0
	global_load_dwordx4 v[204:207], v[210:211], off offset:1168
	s_nop 0
	global_load_dwordx4 v[210:213], v[210:211], off offset:1152
	s_nop 0
	global_load_dwordx4 v[214:217], v[236:237], off offset:1040
	global_load_dwordx4 v[218:221], v[236:237], off offset:1024
	global_load_dwordx4 v[222:225], v[226:227], off
	s_nop 0
	global_load_dwordx4 v[226:229], v[226:227], off offset:64
	s_nop 0
	global_load_dwordx4 v[230:233], v[236:237], off offset:1168
	s_nop 0
	global_load_dwordx4 v[236:239], v[236:237], off offset:1152
	s_waitcnt vmcnt(9)
; __device__ __forceinline__ unsigned cvt_pk_bf16(float lo, float hi) { unsigned r; asm volatile("v_cvt_pk_bf16_f32 %0, %1, %2" : "=v"(r) : "v"(lo), "v"(hi)); return r; }
; __device__ __forceinline__ float bflo(unsigned w) { return __uint_as_float(w << 16); }
; __device__ __forceinline__ float bfhi(unsigned w) { return __uint_as_float(w & 0xffff0000u); }
; #define SCHED_BAR() __builtin_amdgcn_sched_barrier(0)
;     __device__ __forceinline__ void operator()(const Acc& acc, const Unit& u, int wr, int wc, int fr, int fq) const {
;     ...
;                 SCHED_BAR();
; #pragma unroll
;                 for (int m2 = 0; m2 < 2; ++m2) { const int m = 2 * mh + m2; const int row = u.pm * 256 + ai * 128 + wr * 64 + m * 16 + fr;
; #pragma unroll
;                     for (int bj = 0; bj < 2; ++bj) { const u32x4 gw = Gt[m2][bj];
;                         const f32x4 g0 = {bflo(gw.x), bfhi(gw.x), bflo(gw.y), bfhi(gw.y)}, g1 = {bflo(gw.z), bfhi(gw.z), bflo(gw.w), bfhi(gw.w)};
;                         const f32x4 o0 = Mv[m2][bj][0] + acc[ai][bj][m][0] * g0, o1 = Mv[m2][bj][1] + acc[ai][bj][m][1] * g1;
;                         u32x4 w; w.x = cvt_pk_bf16(o0[0], o0[1]); w.y = cvt_pk_bf16(o0[2], o0[3]); w.z = cvt_pk_bf16(o1[0], o1[1]); w.w = cvt_pk_bf16(o1[2], o1[3]);
;                         *(u32x4*)(mb + (size_t)row * DM + colb + bj * 32) = w; } }
;                 SCHED_BAR();
	v_lshlrev_b32_e32 v240, 16, v196
	v_and_b32_e32 v241, 0xffff0000, v196
	v_lshlrev_b32_e32 v196, 16, v197
	v_and_b32_e32 v197, 0xffff0000, v197
	v_lshlrev_b32_e32 v242, 16, v198
	v_and_b32_e32 v243, 0xffff0000, v198
	v_lshlrev_b32_e32 v198, 16, v199
	v_and_b32_e32 v199, 0xffff0000, v199
	v_pk_fma_f32 v[50:51], v[50:51], v[196:197], v[194:195]
	v_pk_fma_f32 v[48:49], v[48:49], v[240:241], v[192:193]
	v_pk_fma_f32 v[64:65], v[64:65], v[242:243], v[188:189]
	v_pk_fma_f32 v[66:67], v[66:67], v[198:199], v[190:191]
	v_cvt_pk_bf16_f32 v48, v48, v49
	v_cvt_pk_bf16_f32 v49, v50, v51
	v_cvt_pk_bf16_f32 v50, v64, v65
	v_lshl_add_u64 v[64:65], v[136:137], 0, v[180:181]
	v_cvt_pk_bf16_f32 v51, v66, v67
	global_store_dwordx4 v[64:65], v[48:51], off
	s_waitcnt vmcnt(9)
	v_lshlrev_b32_e32 v66, 16, v202
	v_and_b32_e32 v67, 0xffff0000, v202
	v_lshlrev_b32_e32 v48, 16, v200
	v_and_b32_e32 v49, 0xffff0000, v200
	v_lshlrev_b32_e32 v50, 16, v201
	v_and_b32_e32 v51, 0xffff0000, v201
	v_lshlrev_b32_e32 v188, 16, v203
	v_and_b32_e32 v189, 0xffff0000, v203
	s_waitcnt vmcnt(7)
	v_pk_fma_f32 v[50:51], v[98:99], v[50:51], v[212:213]
	v_pk_fma_f32 v[48:49], v[96:97], v[48:49], v[210:211]
	v_pk_fma_f32 v[96:97], v[122:123], v[188:189], v[206:207]
	v_pk_fma_f32 v[66:67], v[120:121], v[66:67], v[204:205]
	v_cvt_pk_bf16_f32 v48, v48, v49
	v_cvt_pk_bf16_f32 v49, v50, v51
	s_nop 0
	v_cvt_pk_bf16_f32 v50, v66, v67
	v_cvt_pk_bf16_f32 v51, v96, v97
	global_store_dwordx4 v[64:65], v[48:51], off offset:64
	s_waitcnt vmcnt(5)
	v_lshlrev_b32_e32 v66, 16, v225
	v_and_b32_e32 v67, 0xffff0000, v225
	v_lshlrev_b32_e32 v48, 16, v222
	v_and_b32_e32 v49, 0xffff0000, v222
	v_lshlrev_b32_e32 v50, 16, v223
	v_and_b32_e32 v51, 0xffff0000, v223
	v_lshlrev_b32_e32 v64, 16, v224
	v_and_b32_e32 v65, 0xffff0000, v224
	v_pk_fma_f32 v[50:51], v[54:55], v[50:51], v[220:221]
	v_pk_fma_f32 v[48:49], v[52:53], v[48:49], v[218:219]
	v_pk_fma_f32 v[52:53], v[78:79], v[66:67], v[216:217]
	v_pk_fma_f32 v[54:55], v[76:77], v[64:65], v[214:215]
	v_cvt_pk_bf16_f32 v48, v48, v49
	v_cvt_pk_bf16_f32 v49, v50, v51
	s_waitcnt vmcnt(4)
	v_lshlrev_b32_e32 v64, 16, v229
	v_cvt_pk_bf16_f32 v50, v54, v55
	v_cvt_pk_bf16_f32 v51, v52, v53
	v_lshl_add_u64 v[52:53], v[138:139], 0, v[180:181]
	global_store_dwordx4 v[52:53], v[48:51], off
	v_lshlrev_b32_e32 v54, 16, v228
	v_and_b32_e32 v55, 0xffff0000, v228
	v_lshlrev_b32_e32 v48, 16, v226
	v_and_b32_e32 v49, 0xffff0000, v226
	v_lshlrev_b32_e32 v50, 16, v227
	v_and_b32_e32 v51, 0xffff0000, v227
	v_and_b32_e32 v65, 0xffff0000, v229
	s_waitcnt vmcnt(3)
	v_pk_fma_f32 v[50:51], v[102:103], v[50:51], v[238:239]
	v_pk_fma_f32 v[48:49], v[100:101], v[48:49], v[236:237]
	v_pk_fma_f32 v[64:65], v[126:127], v[64:65], v[232:233]
	v_pk_fma_f32 v[54:55], v[124:125], v[54:55], v[230:231]
	v_cvt_pk_bf16_f32 v48, v48, v49
	v_cvt_pk_bf16_f32 v49, v50, v51
	s_nop 0
	v_cvt_pk_bf16_f32 v50, v54, v55
	v_cvt_pk_bf16_f32 v51, v64, v65
	global_store_dwordx4 v[52:53], v[48:51], off offset:64
	s_branch .LBB0_1512
	v_lshl_add_u64 v[76:77], v[142:143], 0, v[180:181]
	v_lshl_add_u64 v[100:101], v[140:141], 0, v[182:183]
	v_lshl_add_u64 v[192:193], v[146:147], 0, v[180:181]
	v_lshl_add_u64 v[200:201], v[144:145], 0, v[182:183]
	global_load_dwordx4 v[48:51], v[100:101], off offset:1040
	global_load_dwordx4 v[52:55], v[100:101], off offset:1024
	global_load_dwordx4 v[64:67], v[76:77], off
	s_nop 0
	global_load_dwordx4 v[76:79], v[76:77], off offset:64
	s_nop 0
	global_load_dwordx4 v[96:99], v[100:101], off offset:1168
	s_nop 0
	global_load_dwordx4 v[100:103], v[100:101], off offset:1152
	s_nop 0
	global_load_dwordx4 v[120:123], v[200:201], off offset:1040
	global_load_dwordx4 v[124:127], v[200:201], off offset:1024
	global_load_dwordx4 v[188:191], v[192:193], off
	s_nop 0
	global_load_dwordx4 v[192:195], v[192:193], off offset:64
	s_nop 0
	global_load_dwordx4 v[196:199], v[200:201], off offset:1168
	s_nop 0
	global_load_dwordx4 v[200:203], v[200:201], off offset:1152
	s_waitcnt vmcnt(9)
	v_lshlrev_b32_e32 v204, 16, v64
	v_and_b32_e32 v205, 0xffff0000, v64
	v_lshlrev_b32_e32 v64, 16, v65
	v_and_b32_e32 v65, 0xffff0000, v65
	v_lshlrev_b32_e32 v206, 16, v66
	v_and_b32_e32 v207, 0xffff0000, v66
	v_lshlrev_b32_e32 v66, 16, v67
	v_and_b32_e32 v67, 0xffff0000, v67
	v_pk_fma_f32 v[54:55], v[118:119], v[64:65], v[54:55]
	v_pk_fma_f32 v[52:53], v[116:117], v[204:205], v[52:53]
	v_pk_fma_f32 v[64:65], v[114:115], v[66:67], v[50:51]
	v_pk_fma_f32 v[50:51], v[112:113], v[206:207], v[48:49]
	v_cvt_pk_bf16_f32 v48, v52, v53
	v_cvt_pk_bf16_f32 v49, v54, v55
	v_lshl_add_u64 v[52:53], v[148:149], 0, v[180:181]
	v_cvt_pk_bf16_f32 v50, v50, v51
	v_cvt_pk_bf16_f32 v51, v64, v65
	global_store_dwordx4 v[52:53], v[48:51], off
	s_waitcnt vmcnt(9)
	v_lshlrev_b32_e32 v54, 16, v78
	v_and_b32_e32 v55, 0xffff0000, v78
	v_lshlrev_b32_e32 v48, 16, v76
	v_and_b32_e32 v49, 0xffff0000, v76
	v_lshlrev_b32_e32 v50, 16, v77
	v_and_b32_e32 v51, 0xffff0000, v77
	v_lshlrev_b32_e32 v64, 16, v79
	v_and_b32_e32 v65, 0xffff0000, v79
	s_waitcnt vmcnt(7)
	v_pk_fma_f32 v[50:51], v[110:111], v[50:51], v[102:103]
	v_pk_fma_f32 v[48:49], v[108:109], v[48:49], v[100:101]
	v_pk_fma_f32 v[64:65], v[106:107], v[64:65], v[98:99]
	v_pk_fma_f32 v[54:55], v[104:105], v[54:55], v[96:97]
	v_cvt_pk_bf16_f32 v48, v48, v49
	v_cvt_pk_bf16_f32 v49, v50, v51
	s_nop 0
	v_cvt_pk_bf16_f32 v50, v54, v55
	v_cvt_pk_bf16_f32 v51, v64, v65
	global_store_dwordx4 v[52:53], v[48:51], off offset:64
	s_waitcnt vmcnt(5)
; __device__ __forceinline__ unsigned cvt_pk_bf16(float lo, float hi) { unsigned r; asm volatile("v_cvt_pk_bf16_f32 %0, %1, %2" : "=v"(r) : "v"(lo), "v"(hi)); return r; }
; __device__ __forceinline__ float bflo(unsigned w) { return __uint_as_float(w << 16); }
; __device__ __forceinline__ float bfhi(unsigned w) { return __uint_as_float(w & 0xffff0000u); }
; #define SCHED_BAR() __builtin_amdgcn_sched_barrier(0)
;     __device__ __forceinline__ void operator()(const Acc& acc, const Unit& u, int wr, int wc, int fr, int fq) const {
;     ...
;             for (int mh = 0; mh < 2; ++mh) {
;                 u32x4 Gt[2][2]; f32x4 Mv[2][2][2];
; #pragma unroll
;                 for (int m2 = 0; m2 < 2; ++m2) { const int row = u.pm * 256 + ai * 128 + wr * 64 + (2 * mh + m2) * 16 + fr;
;                     const bf16_t* gp = proj + (size_t)row * DIN + GB_OFF + colb; const float* mp = (const float*)(proj + (size_t)row * DIN + M32_COL) + colb;
; #pragma unroll
;                     for (int bj = 0; bj < 2; ++bj) { Gt[m2][bj] = *(const u32x4*)(gp + bj * 32); Mv[m2][bj][0] = *(const f32x4*)(mp + bj * 32); Mv[m2][bj][1] = *(const f32x4*)(mp + bj * 32 + 4); } }
;                 SCHED_BAR();
; #pragma unroll
;                 for (int m2 = 0; m2 < 2; ++m2) { const int m = 2 * mh + m2; const int row = u.pm * 256 + ai * 128 + wr * 64 + m * 16 + fr;
; #pragma unroll
;                     for (int bj = 0; bj < 2; ++bj) { const u32x4 gw = Gt[m2][bj];
;                         const f32x4 g0 = {bflo(gw.x), bfhi(gw.x), bflo(gw.y), bfhi(gw.y)}, g1 = {bflo(gw.z), bfhi(gw.z), bflo(gw.w), bfhi(gw.w)};
;                         const f32x4 o0 = Mv[m2][bj][0] + acc[ai][bj][m][0] * g0, o1 = Mv[m2][bj][1] + acc[ai][bj][m][1] * g1;
;                         u32x4 w; w.x = cvt_pk_bf16(o0[0], o0[1]); w.y = cvt_pk_bf16(o0[2], o0[3]); w.z = cvt_pk_bf16(o1[0], o1[1]); w.w = cvt_pk_bf16(o1[2], o1[3]);
;                         *(u32x4*)(mb + (size_t)row * DM + colb + bj * 32) = w; } }
;                 SCHED_BAR();
	v_lshlrev_b32_e32 v52, 16, v190
	v_and_b32_e32 v53, 0xffff0000, v190
	v_lshlrev_b32_e32 v48, 16, v188
	v_and_b32_e32 v49, 0xffff0000, v188
	v_lshlrev_b32_e32 v50, 16, v189
	v_and_b32_e32 v51, 0xffff0000, v189
	v_lshlrev_b32_e32 v54, 16, v191
	v_and_b32_e32 v55, 0xffff0000, v191
	v_pk_fma_f32 v[50:51], v[94:95], v[50:51], v[126:127]
	v_pk_fma_f32 v[48:49], v[92:93], v[48:49], v[124:125]
	v_pk_fma_f32 v[52:53], v[88:89], v[52:53], v[120:121]
	v_pk_fma_f32 v[54:55], v[90:91], v[54:55], v[122:123]
	v_cvt_pk_bf16_f32 v48, v48, v49
	v_cvt_pk_bf16_f32 v49, v50, v51
	v_cvt_pk_bf16_f32 v50, v52, v53
	v_lshl_add_u64 v[52:53], v[150:151], 0, v[180:181]
	v_cvt_pk_bf16_f32 v51, v54, v55
	global_store_dwordx4 v[52:53], v[48:51], off
	s_waitcnt vmcnt(5)
	v_lshlrev_b32_e32 v54, 16, v194
	v_and_b32_e32 v55, 0xffff0000, v194
	v_lshlrev_b32_e32 v48, 16, v192
	v_and_b32_e32 v49, 0xffff0000, v192
	v_lshlrev_b32_e32 v50, 16, v193
	v_and_b32_e32 v51, 0xffff0000, v193
	v_lshlrev_b32_e32 v64, 16, v195
	v_and_b32_e32 v65, 0xffff0000, v195
	s_waitcnt vmcnt(3)
	v_pk_fma_f32 v[50:51], v[86:87], v[50:51], v[202:203]
	v_pk_fma_f32 v[48:49], v[84:85], v[48:49], v[200:201]
	v_pk_fma_f32 v[64:65], v[82:83], v[64:65], v[198:199]
	v_pk_fma_f32 v[54:55], v[80:81], v[54:55], v[196:197]
	v_cvt_pk_bf16_f32 v48, v48, v49
	v_cvt_pk_bf16_f32 v49, v50, v51
	s_nop 0
	v_cvt_pk_bf16_f32 v50, v54, v55
	v_cvt_pk_bf16_f32 v51, v64, v65
	global_store_dwordx4 v[52:53], v[48:51], off offset:64
	v_lshl_add_u64 v[76:77], v[154:155], 0, v[180:181]
	v_lshl_add_u64 v[84:85], v[152:153], 0, v[182:183]
	v_lshl_add_u64 v[100:101], v[158:159], 0, v[180:181]
	v_lshl_add_u64 v[108:109], v[156:157], 0, v[182:183]
	global_load_dwordx4 v[48:51], v[84:85], off offset:1040
	global_load_dwordx4 v[52:55], v[84:85], off offset:1024
	global_load_dwordx4 v[64:67], v[76:77], off
	s_nop 0
	global_load_dwordx4 v[76:79], v[76:77], off offset:64
	s_nop 0
	global_load_dwordx4 v[80:83], v[84:85], off offset:1168
	s_nop 0
	global_load_dwordx4 v[84:87], v[84:85], off offset:1152
	s_nop 0
	global_load_dwordx4 v[88:91], v[108:109], off offset:1040
	global_load_dwordx4 v[92:95], v[108:109], off offset:1024
	global_load_dwordx4 v[96:99], v[100:101], off
	s_nop 0
	global_load_dwordx4 v[100:103], v[100:101], off offset:64
	s_nop 0
	global_load_dwordx4 v[104:107], v[108:109], off offset:1168
	s_nop 0
	global_load_dwordx4 v[108:111], v[108:109], off offset:1152
	s_waitcnt vmcnt(9)
	v_lshlrev_b32_e32 v112, 16, v64
	v_and_b32_e32 v113, 0xffff0000, v64
	v_lshlrev_b32_e32 v64, 16, v65
	v_and_b32_e32 v65, 0xffff0000, v65
	v_lshlrev_b32_e32 v114, 16, v66
	v_and_b32_e32 v115, 0xffff0000, v66
	v_lshlrev_b32_e32 v66, 16, v67
	v_and_b32_e32 v67, 0xffff0000, v67
	v_pk_fma_f32 v[52:53], v[72:73], v[112:113], v[52:53]
	v_pk_fma_f32 v[54:55], v[74:75], v[64:65], v[54:55]
	v_pk_fma_f32 v[64:65], v[70:71], v[66:67], v[50:51]
	v_pk_fma_f32 v[50:51], v[68:69], v[114:115], v[48:49]
	v_cvt_pk_bf16_f32 v48, v52, v53
	v_cvt_pk_bf16_f32 v49, v54, v55
	v_lshl_add_u64 v[52:53], v[160:161], 0, v[180:181]
	v_cvt_pk_bf16_f32 v50, v50, v51
	v_cvt_pk_bf16_f32 v51, v64, v65
	global_store_dwordx4 v[52:53], v[48:51], off
	s_waitcnt vmcnt(9)
	v_lshlrev_b32_e32 v54, 16, v78
	v_and_b32_e32 v55, 0xffff0000, v78
	v_lshlrev_b32_e32 v48, 16, v76
	v_and_b32_e32 v49, 0xffff0000, v76
	v_lshlrev_b32_e32 v50, 16, v77
	v_and_b32_e32 v51, 0xffff0000, v77
	s_waitcnt vmcnt(7)
	v_pk_fma_f32 v[48:49], v[60:61], v[48:49], v[84:85]
	v_lshlrev_b32_e32 v64, 16, v79
	v_and_b32_e32 v65, 0xffff0000, v79
	v_pk_fma_f32 v[50:51], v[62:63], v[50:51], v[86:87]
	v_cvt_pk_bf16_f32 v48, v48, v49
	v_pk_fma_f32 v[58:59], v[58:59], v[64:65], v[82:83]
	v_cvt_pk_bf16_f32 v49, v50, v51
	v_pk_fma_f32 v[54:55], v[56:57], v[54:55], v[80:81]
	s_nop 0
	v_cvt_pk_bf16_f32 v50, v54, v55
	v_cvt_pk_bf16_f32 v51, v58, v59
	global_store_dwordx4 v[52:53], v[48:51], off offset:64
	s_waitcnt vmcnt(5)
	v_lshlrev_b32_e32 v52, 16, v98
	v_and_b32_e32 v53, 0xffff0000, v98
	v_lshlrev_b32_e32 v48, 16, v96
	v_and_b32_e32 v49, 0xffff0000, v96
	v_lshlrev_b32_e32 v50, 16, v97
	v_and_b32_e32 v51, 0xffff0000, v97
	v_lshlrev_b32_e32 v54, 16, v99
	v_and_b32_e32 v55, 0xffff0000, v99
	v_pk_fma_f32 v[44:45], v[44:45], v[48:49], v[92:93]
	v_pk_fma_f32 v[46:47], v[46:47], v[50:51], v[94:95]
	v_pk_fma_f32 v[48:49], v[42:43], v[54:55], v[90:91]
	v_pk_fma_f32 v[42:43], v[40:41], v[52:53], v[88:89]
	v_cvt_pk_bf16_f32 v40, v44, v45
	v_cvt_pk_bf16_f32 v41, v46, v47
	v_lshl_add_u64 v[44:45], v[162:163], 0, v[180:181]
	v_cvt_pk_bf16_f32 v42, v42, v43
	v_cvt_pk_bf16_f32 v43, v48, v49
	global_store_dwordx4 v[44:45], v[40:43], off
	s_waitcnt vmcnt(5)
; __device__ __forceinline__ unsigned cvt_pk_bf16(float lo, float hi) { unsigned r; asm volatile("v_cvt_pk_bf16_f32 %0, %1, %2" : "=v"(r) : "v"(lo), "v"(hi)); return r; }
; __device__ __forceinline__ float bflo(unsigned w) { return __uint_as_float(w << 16); }
; __device__ __forceinline__ float bfhi(unsigned w) { return __uint_as_float(w & 0xffff0000u); }
; #define SCHED_BAR() __builtin_amdgcn_sched_barrier(0)
;     __device__ __forceinline__ void operator()(const Acc& acc, const Unit& u, int wr, int wc, int fr, int fq) const {
;     ...
;             for (int mh = 0; mh < 2; ++mh) {
;                 u32x4 Gt[2][2]; f32x4 Mv[2][2][2];
; #pragma unroll
;                 for (int m2 = 0; m2 < 2; ++m2) { const int row = u.pm * 256 + ai * 128 + wr * 64 + (2 * mh + m2) * 16 + fr;
;                     const bf16_t* gp = proj + (size_t)row * DIN + GB_OFF + colb; const float* mp = (const float*)(proj + (size_t)row * DIN + M32_COL) + colb;
; #pragma unroll
;                     for (int bj = 0; bj < 2; ++bj) { Gt[m2][bj] = *(const u32x4*)(gp + bj * 32); Mv[m2][bj][0] = *(const f32x4*)(mp + bj * 32); Mv[m2][bj][1] = *(const f32x4*)(mp + bj * 32 + 4); } }
;                 SCHED_BAR();
; #pragma unroll
;                 for (int m2 = 0; m2 < 2; ++m2) { const int m = 2 * mh + m2; const int row = u.pm * 256 + ai * 128 + wr * 64 + m * 16 + fr;
; #pragma unroll
;                     for (int bj = 0; bj < 2; ++bj) { const u32x4 gw = Gt[m2][bj];
;                         const f32x4 g0 = {bflo(gw.x), bfhi(gw.x), bflo(gw.y), bfhi(gw.y)}, g1 = {bflo(gw.z), bfhi(gw.z), bflo(gw.w), bfhi(gw.w)};
;                         const f32x4 o0 = Mv[m2][bj][0] + acc[ai][bj][m][0] * g0, o1 = Mv[m2][bj][1] + acc[ai][bj][m][1] * g1;
;                         u32x4 w; w.x = cvt_pk_bf16(o0[0], o0[1]); w.y = cvt_pk_bf16(o0[2], o0[3]); w.z = cvt_pk_bf16(o1[0], o1[1]); w.w = cvt_pk_bf16(o1[2], o1[3]);
;                         *(u32x4*)(mb + (size_t)row * DM + colb + bj * 32) = w; } }
;                 SCHED_BAR();
	v_lshlrev_b32_e32 v46, 16, v102
	v_and_b32_e32 v47, 0xffff0000, v102
	v_lshlrev_b32_e32 v40, 16, v100
	v_and_b32_e32 v41, 0xffff0000, v100
	v_lshlrev_b32_e32 v48, 16, v103
	v_and_b32_e32 v49, 0xffff0000, v103
	v_lshlrev_b32_e32 v42, 16, v101
	v_and_b32_e32 v43, 0xffff0000, v101
	s_waitcnt vmcnt(3)
	v_pk_fma_f32 v[36:37], v[36:37], v[40:41], v[108:109]
	v_pk_fma_f32 v[40:41], v[34:35], v[48:49], v[106:107]
	v_pk_fma_f32 v[34:35], v[32:33], v[46:47], v[104:105]
	v_pk_fma_f32 v[38:39], v[38:39], v[42:43], v[110:111]
	v_cvt_pk_bf16_f32 v32, v36, v37
	s_nop 0
	v_cvt_pk_bf16_f32 v33, v38, v39
	v_cvt_pk_bf16_f32 v34, v34, v35
	v_cvt_pk_bf16_f32 v35, v40, v41
	global_store_dwordx4 v[44:45], v[32:35], off offset:64
	v_lshl_add_u64 v[56:57], v[166:167], 0, v[180:181]
	v_lshl_add_u64 v[58:59], v[164:165], 0, v[182:183]
	v_lshl_add_u64 v[68:69], v[170:171], 0, v[180:181]
	v_lshl_add_u64 v[76:77], v[168:169], 0, v[182:183]
	global_load_dwordx4 v[32:35], v[58:59], off offset:1040
	global_load_dwordx4 v[36:39], v[58:59], off offset:1024
	global_load_dwordx4 v[40:43], v[56:57], off
	global_load_dwordx4 v[44:47], v[56:57], off offset:64
	global_load_dwordx4 v[48:51], v[58:59], off offset:1168
	global_load_dwordx4 v[52:55], v[58:59], off offset:1152
	s_nop 0
	global_load_dwordx4 v[56:59], v[76:77], off offset:1040
	global_load_dwordx4 v[60:63], v[76:77], off offset:1024
	global_load_dwordx4 v[64:67], v[68:69], off
	s_nop 0
	global_load_dwordx4 v[68:71], v[68:69], off offset:64
	s_nop 0
	global_load_dwordx4 v[72:75], v[76:77], off offset:1168
	s_nop 0
	global_load_dwordx4 v[76:79], v[76:77], off offset:1152
	s_waitcnt vmcnt(9)
	v_lshlrev_b32_e32 v80, 16, v40
	v_and_b32_e32 v81, 0xffff0000, v40
	v_lshlrev_b32_e32 v82, 16, v42
	v_and_b32_e32 v83, 0xffff0000, v42
	v_lshlrev_b32_e32 v42, 16, v43
	v_and_b32_e32 v43, 0xffff0000, v43
	v_lshlrev_b32_e32 v40, 16, v41
	v_and_b32_e32 v41, 0xffff0000, v41
	v_pk_fma_f32 v[28:29], v[28:29], v[80:81], v[36:37]
	v_pk_fma_f32 v[34:35], v[26:27], v[42:43], v[34:35]
	v_pk_fma_f32 v[26:27], v[24:25], v[82:83], v[32:33]
	v_pk_fma_f32 v[30:31], v[30:31], v[40:41], v[38:39]
	v_cvt_pk_bf16_f32 v24, v28, v29
	v_lshl_add_u64 v[28:29], v[172:173], 0, v[180:181]
	v_cvt_pk_bf16_f32 v25, v30, v31
	v_cvt_pk_bf16_f32 v26, v26, v27
	v_cvt_pk_bf16_f32 v27, v34, v35
	global_store_dwordx4 v[28:29], v[24:27], off
	s_waitcnt vmcnt(9)
	v_lshlrev_b32_e32 v30, 16, v46
	v_and_b32_e32 v31, 0xffff0000, v46
	v_lshlrev_b32_e32 v24, 16, v44
	v_and_b32_e32 v25, 0xffff0000, v44
	v_lshlrev_b32_e32 v26, 16, v45
	v_and_b32_e32 v27, 0xffff0000, v45
	v_lshlrev_b32_e32 v32, 16, v47
	v_and_b32_e32 v33, 0xffff0000, v47
	s_waitcnt vmcnt(7)
	v_pk_fma_f32 v[22:23], v[22:23], v[26:27], v[54:55]
	v_pk_fma_f32 v[20:21], v[20:21], v[24:25], v[52:53]
	v_pk_fma_f32 v[24:25], v[18:19], v[32:33], v[50:51]
	v_pk_fma_f32 v[18:19], v[16:17], v[30:31], v[48:49]
	v_cvt_pk_bf16_f32 v16, v20, v21
	v_cvt_pk_bf16_f32 v17, v22, v23
	s_waitcnt vmcnt(4)
	v_lshlrev_b32_e32 v20, 16, v66
	v_cvt_pk_bf16_f32 v18, v18, v19
	v_cvt_pk_bf16_f32 v19, v24, v25
	global_store_dwordx4 v[28:29], v[16:19], off offset:64
	v_and_b32_e32 v21, 0xffff0000, v66
	v_lshlrev_b32_e32 v22, 16, v67
	v_lshlrev_b32_e32 v16, 16, v64
	v_and_b32_e32 v17, 0xffff0000, v64
	v_lshlrev_b32_e32 v18, 16, v65
	v_and_b32_e32 v19, 0xffff0000, v65
	v_and_b32_e32 v23, 0xffff0000, v67
	v_pk_fma_f32 v[12:13], v[12:13], v[16:17], v[60:61]
	v_pk_fma_f32 v[14:15], v[14:15], v[18:19], v[62:63]
	v_pk_fma_f32 v[16:17], v[10:11], v[22:23], v[58:59]
	v_pk_fma_f32 v[10:11], v[8:9], v[20:21], v[56:57]
	v_cvt_pk_bf16_f32 v8, v12, v13
	v_cvt_pk_bf16_f32 v9, v14, v15
	v_lshl_add_u64 v[12:13], v[174:175], 0, v[180:181]
	v_cvt_pk_bf16_f32 v10, v10, v11
	v_cvt_pk_bf16_f32 v11, v16, v17
	global_store_dwordx4 v[12:13], v[8:11], off
	s_waitcnt vmcnt(5)
	v_lshlrev_b32_e32 v14, 16, v70
	v_and_b32_e32 v15, 0xffff0000, v70
	v_lshlrev_b32_e32 v8, 16, v68
	v_and_b32_e32 v9, 0xffff0000, v68
	v_lshlrev_b32_e32 v16, 16, v71
	v_and_b32_e32 v17, 0xffff0000, v71
	v_lshlrev_b32_e32 v10, 16, v69
	v_and_b32_e32 v11, 0xffff0000, v69
	s_waitcnt vmcnt(3)
	v_pk_fma_f32 v[4:5], v[4:5], v[8:9], v[76:77]
	v_pk_fma_f32 v[8:9], v[2:3], v[16:17], v[74:75]
	v_pk_fma_f32 v[2:3], v[0:1], v[14:15], v[72:73]
	v_pk_fma_f32 v[6:7], v[6:7], v[10:11], v[78:79]
	v_cvt_pk_bf16_f32 v0, v4, v5
	s_nop 0
	v_cvt_pk_bf16_f32 v1, v6, v7
	v_cvt_pk_bf16_f32 v2, v2, v3
	v_cvt_pk_bf16_f32 v3, v8, v9
	global_store_dwordx4 v[12:13], v[0:3], off offset:64
	s_branch .LBB0_1512

; #define LAS __attribute__((address_space(3)))
; #define SCHED_BAR() __builtin_amdgcn_sched_barrier(0)
; template <class Epi>
; __device__ __forceinline__ void skinny_phase(LAS unsigned char* lds, const pg8::Gemm g, const Epi& E, int G, int bx) {
;     ...
;         LAS f32x4* red = (LAS f32x4*)lds;
;         __syncthreads();
; #pragma unroll
;         for (int b = 0; b < 2; ++b)
; #pragma unroll
;             for (int m = 0; m < 2; ++m)
; #pragma unroll
;                 for (int n = 0; n < 2; ++n) red[(((b * 2 + m) * 2 + n) * 8 + wid) * 64 + lane] = a8[b][m][n];
;         __syncthreads();
;         if (wid == 0) {
;             Acc acc;
; #pragma unroll
;             for (int a = 0; a < 2; ++a)
; #pragma unroll
;                 for (int b = 0; b < 2; ++b)
; #pragma unroll
;                     for (int m = 0; m < 4; ++m)
; #pragma unroll
;                         for (int n = 0; n < 2; ++n) acc[a][b][m][n] = (f32x4){0.f, 0.f, 0.f, 0.f};
; #pragma unroll
;             for (int b = 0; b < 2; ++b)
; #pragma unroll
;                 for (int m = 0; m < 2; ++m)
; #pragma unroll
;                     for (int n = 0; n < 2; ++n) { f32x4 t = {0.f, 0.f, 0.f, 0.f};
; #pragma unroll
;                         for (int w8 = 0; w8 < 8; ++w8) t += red[(((b * 2 + m) * 2 + n) * 8 + w8) * 64 + lane];
;                         acc[0][b][m][n] = t; SCHED_BAR(); }
.LBB0_1751:
	s_and_b64 vcc, exec, s[14:15]
	s_barrier
	ds_write_b128 v168, v[20:23]
	ds_write_b128 v168, v[28:31] offset:8192
	ds_write_b128 v168, v[4:7] offset:16384
	ds_write_b128 v168, v[16:19] offset:24576
	ds_write_b128 v168, v[12:15] offset:32768
	ds_write_b128 v168, v[24:27] offset:40960
	ds_write_b128 v168, v[0:3] offset:49152
	ds_write_b128 v168, v[8:11] offset:57344
	s_waitcnt lgkmcnt(0)
	s_barrier
	s_cbranch_vccz .LBB0_1741
	ds_read_b128 v[0:3], v167
	ds_read_b128 v[4:7], v167 offset:1024
	ds_read_b128 v[8:11], v167 offset:2048
	ds_read_b128 v[12:15], v167 offset:3072
	s_waitcnt lgkmcnt(3)
	v_pk_add_f32 v[2:3], v[2:3], 0 op_sel_hi:[1,0]
	v_pk_add_f32 v[0:1], v[0:1], 0 op_sel_hi:[1,0]
	s_waitcnt lgkmcnt(2)
	v_pk_add_f32 v[2:3], v[2:3], v[6:7]
	v_pk_add_f32 v[4:5], v[0:1], v[4:5]
	s_waitcnt lgkmcnt(1)
	v_pk_add_f32 v[6:7], v[2:3], v[10:11]
	ds_read_b128 v[0:3], v167 offset:4096
	v_pk_add_f32 v[4:5], v[4:5], v[8:9]
	s_waitcnt lgkmcnt(1)
	v_pk_add_f32 v[8:9], v[6:7], v[14:15]
	v_pk_add_f32 v[12:13], v[4:5], v[12:13]
	ds_read_b128 v[4:7], v167 offset:5120
	s_waitcnt lgkmcnt(1)
	v_pk_add_f32 v[14:15], v[8:9], v[2:3]
	ds_read_b128 v[8:11], v167 offset:6144
	v_pk_add_f32 v[12:13], v[12:13], v[0:1]
	ds_read_b128 v[0:3], v167 offset:7168
	s_waitcnt lgkmcnt(2)
	v_pk_add_f32 v[6:7], v[14:15], v[6:7]
	v_pk_add_f32 v[4:5], v[12:13], v[4:5]
	s_waitcnt lgkmcnt(1)
	v_pk_add_f32 v[6:7], v[6:7], v[10:11]
	v_pk_add_f32 v[4:5], v[4:5], v[8:9]
	s_waitcnt vmcnt(2) lgkmcnt(0)
	v_pk_add_f32 v[74:75], v[6:7], v[2:3]
	v_pk_add_f32 v[72:73], v[4:5], v[0:1]
	ds_read_b128 v[0:3], v167 offset:8192
	ds_read_b128 v[4:7], v167 offset:9216
	ds_read_b128 v[8:11], v167 offset:10240
	ds_read_b128 v[12:15], v167 offset:11264
	s_waitcnt lgkmcnt(3)
	v_pk_add_f32 v[2:3], v[2:3], 0 op_sel_hi:[1,0]
	v_pk_add_f32 v[0:1], v[0:1], 0 op_sel_hi:[1,0]
	s_waitcnt lgkmcnt(2)
	v_pk_add_f32 v[2:3], v[2:3], v[6:7]
	v_pk_add_f32 v[4:5], v[0:1], v[4:5]
	s_waitcnt lgkmcnt(1)
	v_pk_add_f32 v[6:7], v[2:3], v[10:11]
	ds_read_b128 v[0:3], v167 offset:12288
	v_pk_add_f32 v[4:5], v[4:5], v[8:9]
	s_waitcnt lgkmcnt(1)
	v_pk_add_f32 v[8:9], v[6:7], v[14:15]
	v_pk_add_f32 v[12:13], v[4:5], v[12:13]
	ds_read_b128 v[4:7], v167 offset:13312
	s_waitcnt lgkmcnt(1)
	v_pk_add_f32 v[14:15], v[8:9], v[2:3]
	ds_read_b128 v[8:11], v167 offset:14336
	v_pk_add_f32 v[12:13], v[12:13], v[0:1]
	ds_read_b128 v[0:3], v167 offset:15360
	s_waitcnt lgkmcnt(2)
	v_pk_add_f32 v[6:7], v[14:15], v[6:7]
	v_pk_add_f32 v[4:5], v[12:13], v[4:5]
	s_waitcnt lgkmcnt(1)
	v_pk_add_f32 v[6:7], v[6:7], v[10:11]
	v_pk_add_f32 v[4:5], v[4:5], v[8:9]
	s_waitcnt lgkmcnt(0)
	v_pk_add_f32 v[78:79], v[6:7], v[2:3]
	v_pk_add_f32 v[76:77], v[4:5], v[0:1]
	ds_read_b128 v[0:3], v167 offset:16384
	ds_read_b128 v[4:7], v167 offset:17408
	ds_read_b128 v[8:11], v167 offset:18432
	ds_read_b128 v[12:15], v167 offset:19456
	s_waitcnt lgkmcnt(3)
	v_pk_add_f32 v[2:3], v[2:3], 0 op_sel_hi:[1,0]
	v_pk_add_f32 v[0:1], v[0:1], 0 op_sel_hi:[1,0]
	s_waitcnt lgkmcnt(2)
	v_pk_add_f32 v[2:3], v[2:3], v[6:7]
	v_pk_add_f32 v[4:5], v[0:1], v[4:5]
	s_waitcnt lgkmcnt(1)
	v_pk_add_f32 v[6:7], v[2:3], v[10:11]
	ds_read_b128 v[0:3], v167 offset:20480
	v_pk_add_f32 v[4:5], v[4:5], v[8:9]
	s_waitcnt lgkmcnt(1)
	v_pk_add_f32 v[8:9], v[6:7], v[14:15]
	v_pk_add_f32 v[12:13], v[4:5], v[12:13]
	ds_read_b128 v[4:7], v167 offset:21504
	s_waitcnt lgkmcnt(1)
	v_pk_add_f32 v[14:15], v[8:9], v[2:3]
	ds_read_b128 v[8:11], v167 offset:22528
	v_pk_add_f32 v[12:13], v[12:13], v[0:1]
	ds_read_b128 v[0:3], v167 offset:23552
	s_waitcnt lgkmcnt(2)
	v_pk_add_f32 v[6:7], v[14:15], v[6:7]
	v_pk_add_f32 v[4:5], v[12:13], v[4:5]
	s_waitcnt lgkmcnt(1)
	v_pk_add_f32 v[6:7], v[6:7], v[10:11]
	v_pk_add_f32 v[4:5], v[4:5], v[8:9]
	s_waitcnt lgkmcnt(0)
	v_pk_add_f32 v[62:63], v[6:7], v[2:3]
	v_pk_add_f32 v[60:61], v[4:5], v[0:1]
	ds_read_b128 v[0:3], v167 offset:24576
	ds_read_b128 v[4:7], v167 offset:25600
	ds_read_b128 v[8:11], v167 offset:26624
	ds_read_b128 v[12:15], v167 offset:27648
	s_waitcnt lgkmcnt(3)
	v_pk_add_f32 v[2:3], v[2:3], 0 op_sel_hi:[1,0]
	v_pk_add_f32 v[0:1], v[0:1], 0 op_sel_hi:[1,0]
	s_waitcnt lgkmcnt(2)
	v_pk_add_f32 v[2:3], v[2:3], v[6:7]
	v_pk_add_f32 v[4:5], v[0:1], v[4:5]
	s_waitcnt lgkmcnt(1)
	v_pk_add_f32 v[6:7], v[2:3], v[10:11]
	ds_read_b128 v[0:3], v167 offset:28672
	v_pk_add_f32 v[4:5], v[4:5], v[8:9]
	s_waitcnt lgkmcnt(1)
	v_pk_add_f32 v[8:9], v[6:7], v[14:15]
	v_pk_add_f32 v[12:13], v[4:5], v[12:13]
	ds_read_b128 v[4:7], v167 offset:29696
	s_waitcnt lgkmcnt(1)
	v_pk_add_f32 v[14:15], v[8:9], v[2:3]
	ds_read_b128 v[8:11], v167 offset:30720
	v_pk_add_f32 v[12:13], v[12:13], v[0:1]
	ds_read_b128 v[0:3], v167 offset:31744
	s_waitcnt lgkmcnt(2)
	v_pk_add_f32 v[6:7], v[14:15], v[6:7]
	v_pk_add_f32 v[4:5], v[12:13], v[4:5]
	s_waitcnt lgkmcnt(1)
	v_pk_add_f32 v[6:7], v[6:7], v[10:11]
	v_pk_add_f32 v[4:5], v[4:5], v[8:9]
	s_waitcnt vmcnt(1) lgkmcnt(0)
	v_pk_add_f32 v[70:71], v[6:7], v[2:3]
	v_pk_add_f32 v[68:69], v[4:5], v[0:1]
	ds_read_b128 v[0:3], v167 offset:32768
	ds_read_b128 v[4:7], v167 offset:33792
	ds_read_b128 v[8:11], v167 offset:34816
	ds_read_b128 v[12:15], v167 offset:35840
	s_waitcnt lgkmcnt(3)
	v_pk_add_f32 v[2:3], v[2:3], 0 op_sel_hi:[1,0]
	v_pk_add_f32 v[0:1], v[0:1], 0 op_sel_hi:[1,0]
	s_waitcnt lgkmcnt(2)
	v_pk_add_f32 v[2:3], v[2:3], v[6:7]
	v_pk_add_f32 v[4:5], v[0:1], v[4:5]
	s_waitcnt lgkmcnt(1)
	v_pk_add_f32 v[6:7], v[2:3], v[10:11]
	ds_read_b128 v[0:3], v167 offset:36864
	v_pk_add_f32 v[4:5], v[4:5], v[8:9]
	s_waitcnt lgkmcnt(1)
	v_pk_add_f32 v[8:9], v[6:7], v[14:15]
	v_pk_add_f32 v[12:13], v[4:5], v[12:13]
	ds_read_b128 v[4:7], v167 offset:37888
	s_waitcnt lgkmcnt(1)
; #define SCHED_BAR() __builtin_amdgcn_sched_barrier(0)
;     __device__ __forceinline__ void operator()(const Acc& acc, const Unit& u, int wr, int wc, int fr, int fq) const {
;         float ssv[2][4];
; #pragma unroll
;         for (int ai = 0; ai < 2; ++ai)
; #pragma unroll
;             for (int m = 0; m < 4; ++m) ssv[ai][m] = ss[u.pm * 256 + ai * 128 + wr * 64 + m * 16 + fr];
; template <class Epi>
; __device__ __forceinline__ void skinny_phase(LAS unsigned char* lds, const pg8::Gemm g, const Epi& E, int G, int bx) {
;     ...
;             Acc acc;
; #pragma unroll
;             for (int a = 0; a < 2; ++a)
; #pragma unroll
;                 for (int b = 0; b < 2; ++b)
; #pragma unroll
;                     for (int m = 0; m < 4; ++m)
; #pragma unroll
;                         for (int n = 0; n < 2; ++n) acc[a][b][m][n] = (f32x4){0.f, 0.f, 0.f, 0.f};
; #pragma unroll
;             for (int b = 0; b < 2; ++b)
; #pragma unroll
;                 for (int m = 0; m < 2; ++m)
; #pragma unroll
;                     for (int n = 0; n < 2; ++n) { f32x4 t = {0.f, 0.f, 0.f, 0.f};
; #pragma unroll
;                         for (int w8 = 0; w8 < 8; ++w8) t += red[(((b * 2 + m) * 2 + n) * 8 + w8) * 64 + lane];
;                         acc[0][b][m][n] = t; SCHED_BAR(); }
	v_pk_add_f32 v[14:15], v[8:9], v[2:3]
	ds_read_b128 v[8:11], v167 offset:38912
	v_pk_add_f32 v[12:13], v[12:13], v[0:1]
	ds_read_b128 v[0:3], v167 offset:39936
	s_waitcnt lgkmcnt(2)
	v_pk_add_f32 v[6:7], v[14:15], v[6:7]
	v_pk_add_f32 v[4:5], v[12:13], v[4:5]
	s_waitcnt lgkmcnt(1)
	v_pk_add_f32 v[6:7], v[6:7], v[10:11]
	v_pk_add_f32 v[4:5], v[4:5], v[8:9]
	s_waitcnt lgkmcnt(0)
	v_pk_add_f32 v[122:123], v[6:7], v[2:3]
	v_pk_add_f32 v[120:121], v[4:5], v[0:1]
	ds_read_b128 v[0:3], v167 offset:40960
	ds_read_b128 v[4:7], v167 offset:41984
	ds_read_b128 v[8:11], v167 offset:43008
	ds_read_b128 v[12:15], v167 offset:44032
	s_waitcnt lgkmcnt(3)
	v_pk_add_f32 v[2:3], v[2:3], 0 op_sel_hi:[1,0]
	v_pk_add_f32 v[0:1], v[0:1], 0 op_sel_hi:[1,0]
	s_waitcnt lgkmcnt(2)
	v_pk_add_f32 v[2:3], v[2:3], v[6:7]
	v_pk_add_f32 v[4:5], v[0:1], v[4:5]
	s_waitcnt lgkmcnt(1)
	v_pk_add_f32 v[6:7], v[2:3], v[10:11]
	ds_read_b128 v[0:3], v167 offset:45056
	v_pk_add_f32 v[4:5], v[4:5], v[8:9]
	s_waitcnt lgkmcnt(1)
	v_pk_add_f32 v[8:9], v[6:7], v[14:15]
	v_pk_add_f32 v[12:13], v[4:5], v[12:13]
	ds_read_b128 v[4:7], v167 offset:46080
	s_waitcnt lgkmcnt(1)
	v_pk_add_f32 v[14:15], v[8:9], v[2:3]
	ds_read_b128 v[8:11], v167 offset:47104
	v_pk_add_f32 v[12:13], v[12:13], v[0:1]
	ds_read_b128 v[0:3], v167 offset:48128
	s_waitcnt lgkmcnt(2)
	v_pk_add_f32 v[6:7], v[14:15], v[6:7]
	v_pk_add_f32 v[4:5], v[12:13], v[4:5]
	s_waitcnt lgkmcnt(1)
	v_pk_add_f32 v[6:7], v[6:7], v[10:11]
	v_pk_add_f32 v[4:5], v[4:5], v[8:9]
	s_waitcnt lgkmcnt(0)
	v_pk_add_f32 v[126:127], v[6:7], v[2:3]
	v_pk_add_f32 v[124:125], v[4:5], v[0:1]
	ds_read_b128 v[0:3], v167 offset:49152
	ds_read_b128 v[4:7], v167 offset:50176
	ds_read_b128 v[8:11], v167 offset:51200
	ds_read_b128 v[12:15], v167 offset:52224
	s_waitcnt lgkmcnt(3)
	v_pk_add_f32 v[2:3], v[2:3], 0 op_sel_hi:[1,0]
	v_pk_add_f32 v[0:1], v[0:1], 0 op_sel_hi:[1,0]
	s_waitcnt lgkmcnt(2)
	v_pk_add_f32 v[2:3], v[2:3], v[6:7]
	v_pk_add_f32 v[4:5], v[0:1], v[4:5]
	s_waitcnt lgkmcnt(1)
	v_pk_add_f32 v[6:7], v[2:3], v[10:11]
	ds_read_b128 v[0:3], v167 offset:53248
	v_pk_add_f32 v[4:5], v[4:5], v[8:9]
	s_waitcnt lgkmcnt(1)
	v_pk_add_f32 v[8:9], v[6:7], v[14:15]
	v_pk_add_f32 v[12:13], v[4:5], v[12:13]
	ds_read_b128 v[4:7], v167 offset:54272
	s_waitcnt lgkmcnt(1)
	v_pk_add_f32 v[14:15], v[8:9], v[2:3]
	ds_read_b128 v[8:11], v167 offset:55296
	v_pk_add_f32 v[12:13], v[12:13], v[0:1]
	ds_read_b128 v[0:3], v167 offset:56320
	s_waitcnt lgkmcnt(2)
	v_pk_add_f32 v[6:7], v[14:15], v[6:7]
	v_pk_add_f32 v[4:5], v[12:13], v[4:5]
	s_waitcnt lgkmcnt(1)
	v_pk_add_f32 v[6:7], v[6:7], v[10:11]
	v_pk_add_f32 v[4:5], v[4:5], v[8:9]
	s_waitcnt lgkmcnt(0)
	v_pk_add_f32 v[110:111], v[6:7], v[2:3]
	v_pk_add_f32 v[108:109], v[4:5], v[0:1]
	ds_read_b128 v[0:3], v167 offset:57344
	ds_read_b128 v[4:7], v167 offset:58368
	ds_read_b128 v[8:11], v167 offset:59392
	ds_read_b128 v[12:15], v167 offset:60416
	s_waitcnt lgkmcnt(3)
	v_pk_add_f32 v[2:3], v[2:3], 0 op_sel_hi:[1,0]
	v_pk_add_f32 v[0:1], v[0:1], 0 op_sel_hi:[1,0]
	s_waitcnt lgkmcnt(2)
	v_pk_add_f32 v[2:3], v[2:3], v[6:7]
	v_pk_add_f32 v[4:5], v[0:1], v[4:5]
	s_waitcnt lgkmcnt(1)
	v_pk_add_f32 v[6:7], v[2:3], v[10:11]
	ds_read_b128 v[0:3], v167 offset:61440
	v_pk_add_f32 v[4:5], v[4:5], v[8:9]
	s_waitcnt lgkmcnt(1)
	v_pk_add_f32 v[8:9], v[6:7], v[14:15]
	v_pk_add_f32 v[12:13], v[4:5], v[12:13]
	ds_read_b128 v[4:7], v167 offset:62464
	s_waitcnt lgkmcnt(1)
	v_pk_add_f32 v[14:15], v[8:9], v[2:3]
	ds_read_b128 v[8:11], v167 offset:63488
	v_pk_add_f32 v[12:13], v[12:13], v[0:1]
	ds_read_b128 v[0:3], v167 offset:64512
	s_waitcnt lgkmcnt(2)
	v_pk_add_f32 v[6:7], v[14:15], v[6:7]
	v_pk_add_f32 v[4:5], v[12:13], v[4:5]
	s_waitcnt lgkmcnt(1)
	v_pk_add_f32 v[6:7], v[6:7], v[10:11]
	v_pk_add_f32 v[4:5], v[4:5], v[8:9]
	s_waitcnt lgkmcnt(0)
	v_pk_add_f32 v[114:115], v[6:7], v[2:3]
	v_pk_add_f32 v[112:113], v[4:5], v[0:1]
	s_mov_b32 s9, s8
	s_mov_b32 s10, s8
	s_mov_b32 s11, s8
	v_mov_b64_e32 v[0:1], s[8:9]
	v_mov_b64_e32 v[106:107], s[10:11]
	v_mov_b64_e32 v[98:99], s[10:11]
	v_mov_b64_e32 v[90:91], s[10:11]
	v_mov_b64_e32 v[82:83], s[10:11]
	v_mov_b64_e32 v[118:119], s[10:11]
	v_mov_b64_e32 v[102:103], s[10:11]
	v_mov_b64_e32 v[94:95], s[10:11]
	v_mov_b64_e32 v[86:87], s[10:11]
	v_mov_b64_e32 v[58:59], s[10:11]
	v_mov_b64_e32 v[50:51], s[10:11]
	v_mov_b64_e32 v[42:43], s[10:11]
	v_mov_b64_e32 v[34:35], s[10:11]
	v_mov_b64_e32 v[26:27], s[10:11]
	v_mov_b64_e32 v[18:19], s[10:11]
	v_mov_b64_e32 v[8:9], s[8:9]
	v_mov_b64_e32 v[4:5], s[8:9]
	s_waitcnt vmcnt(0)
	v_mov_b64_e32 v[66:67], s[10:11]
	v_mov_b64_e32 v[54:55], s[10:11]
	v_mov_b64_e32 v[46:47], s[10:11]
	v_mov_b64_e32 v[38:39], s[10:11]
	v_mov_b64_e32 v[30:31], s[10:11]
	v_mov_b64_e32 v[22:23], s[10:11]
	v_mov_b64_e32 v[14:15], s[10:11]
	v_mov_b64_e32 v[2:3], s[10:11]
	v_mov_b64_e32 v[104:105], s[8:9]
	v_mov_b64_e32 v[96:97], s[8:9]
	v_mov_b64_e32 v[88:89], s[8:9]
	v_mov_b64_e32 v[80:81], s[8:9]
	v_mov_b64_e32 v[116:117], s[8:9]
	v_mov_b64_e32 v[100:101], s[8:9]
	v_mov_b64_e32 v[92:93], s[8:9]
	v_mov_b64_e32 v[84:85], s[8:9]
	v_mov_b64_e32 v[56:57], s[8:9]
	v_mov_b64_e32 v[48:49], s[8:9]
	v_mov_b64_e32 v[40:41], s[8:9]
	v_mov_b64_e32 v[32:33], s[8:9]
	v_mov_b64_e32 v[24:25], s[8:9]
	v_mov_b64_e32 v[16:17], s[8:9]
	v_mov_b64_e32 v[10:11], s[10:11]
	v_mov_b64_e32 v[6:7], s[10:11]
	v_mov_b64_e32 v[64:65], s[8:9]
	v_mov_b64_e32 v[52:53], s[8:9]
	v_mov_b64_e32 v[44:45], s[8:9]
	v_mov_b64_e32 v[36:37], s[8:9]
	v_mov_b64_e32 v[28:29], s[8:9]
	v_mov_b64_e32 v[20:21], s[8:9]
	v_mov_b64_e32 v[12:13], s[8:9]
	global_load_dword v174, v[130:131], off
	global_load_dword v175, v[132:133], off
	s_waitcnt vmcnt(1)
; __device__ __forceinline__ unsigned cvt_pk_bf16(float lo, float hi) { unsigned r; asm volatile("v_cvt_pk_bf16_f32 %0, %1, %2" : "=v"(r) : "v"(lo), "v"(hi)); return r; }
; __device__ __forceinline__ float fast_sigmoid(float a) { return __builtin_amdgcn_rcpf(1.0f + __expf(-a)); }
;     __device__ __forceinline__ void operator()(const Acc& acc, const Unit& u, int wr, int wc, int fr, int fq) const {
;     ...
; #pragma unroll
;         for (int ai = 0; ai < 2; ++ai)
; #pragma unroll
;             for (int m = 0; m < 4; ++m) {
;                 const int row = u.pm * 256 + ai * 128 + wr * 64 + m * 16 + fr;
;                 const float rs = rsqrtf(ssv[ai][m] * (1.0f / DM) + EPS);
;                 bf16_t* dst = act + ((size_t)((row >> 8) * (DFF / 64) + u.pn * 2 + (wc >> 1)) * 256 + (row & 255)) * 64 + (wc & 1) * 32 + fq * 8;
;                 u32x4 w;
; #pragma unroll
;                 for (int n = 0; n < 2; ++n) {
;                     const f32x4 a = acc[ai][0][m][n] * rs, b = acc[ai][1][m][n] * rs; f32x4 v;
; #pragma unroll
;                     for (int j = 0; j < 4; ++j) v[j] = a[j] * fast_sigmoid(a[j]) * b[j];
;                     if (n == 0) { w.x = cvt_pk_bf16(v[0], v[1]); w.y = cvt_pk_bf16(v[2], v[3]); } else { w.z = cvt_pk_bf16(v[0], v[1]); w.w = cvt_pk_bf16(v[2], v[3]); }
;                 }
;                 *(u32x4*)dst = w;
;             }
	v_fmamk_f32 v174, v174, 0x3a800000, v169
	v_mul_f32_e32 v176, 0x4b800000, v174
	v_cmp_gt_f32_e32 vcc, s18, v174
	v_mov_b32_e32 v178, v123
	v_mov_b32_e32 v179, v75
	v_cndmask_b32_e32 v174, v174, v176, vcc
	v_rsq_f32_e32 v174, v174
	s_lshl_b32 s0, s0, 1
	s_lshr_b32 s1, s1, 1
	v_mov_b32_e32 v123, v74
	v_mul_f32_e32 v176, 0x45800000, v174
	v_cndmask_b32_e32 v174, v174, v176, vcc
	s_waitcnt vmcnt(0)
	v_pk_mul_f32 v[178:179], v[178:179], v[174:175] op_sel_hi:[1,0]
	s_or_b32 s0, s0, s1
	v_mul_f32_e32 v75, 0xbfb8aa3b, v179
	v_exp_f32_e32 v182, v75
	v_pk_mul_f32 v[74:75], v[122:123], v[174:175] op_sel_hi:[1,0]
	s_addk_i32 s0, 0x1600
	v_mul_f32_e32 v122, 0xbfb8aa3b, v75
	s_ashr_i32 s1, s0, 31
	v_exp_f32_e32 v183, v122
	s_and_b32 s9, s23, 32
	s_lshl_b64 s[0:1], s[0:1], 15
	v_lshl_add_u64 v[176:177], v[162:163], 0, s[0:1]
	s_lshl_b32 s0, s9, 1
	s_mov_b32 s1, s8
	v_lshl_add_u64 v[122:123], v[176:177], 0, s[0:1]
	v_add_f32_e32 v176, 1.0, v182
	v_rcp_f32_e32 v182, v176
	v_add_f32_e32 v176, 1.0, v183
	v_rcp_f32_e32 v183, v176
	v_mov_b32_e32 v176, v121
	v_mov_b32_e32 v177, v73
	v_pk_mul_f32 v[176:177], v[176:177], v[174:175] op_sel_hi:[1,0]
	v_mul_f32_e32 v121, v179, v182
	v_mul_f32_e32 v73, 0xbfb8aa3b, v177
	v_exp_f32_e32 v73, v73
	v_mul_f32_e32 v178, v178, v121
	v_mov_b32_e32 v121, v72
	v_mul_f32_e32 v75, v75, v183
	v_add_f32_e32 v73, 1.0, v73
	v_rcp_f32_e32 v179, v73
	v_pk_mul_f32 v[72:73], v[120:121], v[174:175] op_sel_hi:[1,0]
	v_mul_f32_e32 v182, v74, v75
	v_mul_f32_e32 v120, 0xbfb8aa3b, v73
	v_exp_f32_e32 v120, v120
	v_mul_f32_e32 v74, v177, v179
	v_mul_f32_e32 v176, v176, v74
	v_mov_b32_e32 v75, v79
	v_add_f32_e32 v74, 1.0, v120
	v_rcp_f32_e32 v177, v74
	v_mov_b32_e32 v74, v127
	v_pk_mul_f32 v[120:121], v[74:75], v[174:175] op_sel_hi:[1,0]
	v_mov_b32_e32 v127, v78
	v_mul_f32_e32 v74, 0xbfb8aa3b, v121
	v_exp_f32_e32 v75, v74
	v_mul_f32_e32 v73, v73, v177
	v_mul_f32_e32 v72, v72, v73
	v_cvt_pk_bf16_f32 v74, v72, v176
	v_add_f32_e32 v72, 1.0, v75
	v_rcp_f32_e32 v79, v72
	v_pk_mul_f32 v[72:73], v[126:127], v[174:175] op_sel_hi:[1,0]
	v_mul_f32_e32 v79, v121, v79
	v_mul_f32_e32 v75, 0xbfb8aa3b, v73
	v_exp_f32_e32 v78, v75
	v_mul_f32_e32 v120, v120, v79
	v_mov_b32_e32 v79, v77
	v_cvt_pk_bf16_f32 v75, v182, v178
	v_add_f32_e32 v78, 1.0, v78
	v_rcp_f32_e32 v121, v78
	v_mov_b32_e32 v78, v125
	v_pk_mul_f32 v[78:79], v[78:79], v[174:175] op_sel_hi:[1,0]
	v_mov_b32_e32 v125, v76
	v_mul_f32_e32 v77, 0xbfb8aa3b, v79
	v_exp_f32_e32 v126, v77
	v_pk_mul_f32 v[76:77], v[124:125], v[174:175] op_sel_hi:[1,0]
	v_mul_f32_e32 v73, v73, v121
	v_mul_f32_e32 v124, 0xbfb8aa3b, v77
	v_exp_f32_e32 v124, v124
	v_add_f32_e32 v121, 1.0, v126
	v_rcp_f32_e32 v121, v121
	v_mul_f32_e32 v72, v72, v73
	v_add_f32_e32 v124, 1.0, v124
	v_rcp_f32_e32 v124, v124
	v_mul_f32_e32 v73, v79, v121
	v_mul_f32_e32 v73, v78, v73
	v_mov_b32_e32 v121, v63
	v_mul_f32_e32 v77, v77, v124
	v_mul_f32_e32 v76, v76, v77
	v_fmamk_f32 v77, v175, 0x3a800000, v169
	v_mul_f32_e32 v78, 0x4b800000, v77
	v_cmp_gt_f32_e32 vcc, s18, v77
	v_cvt_pk_bf16_f32 v76, v76, v73
	s_nop 1
	v_cndmask_b32_e32 v77, v77, v78, vcc
	v_rsq_f32_e32 v78, v77
	v_cvt_pk_bf16_f32 v77, v72, v120
	v_mov_b32_e32 v120, v111
	v_mov_b32_e32 v111, v62
	v_mul_f32_e32 v79, 0x45800000, v78
	v_cndmask_b32_e32 v78, v78, v79, vcc
	v_pk_mul_f32 v[120:121], v[120:121], v[78:79] op_sel_hi:[1,0]
	v_lshl_add_u64 v[72:73], v[122:123], 0, v[128:129]
	v_mul_f32_e32 v63, 0xbfb8aa3b, v121
	v_exp_f32_e32 v79, v63
	global_store_dwordx4 v[72:73], v[74:77], off
	v_pk_mul_f32 v[62:63], v[110:111], v[78:79] op_sel_hi:[1,0]
	s_nop 0
	v_mul_f32_e32 v110, 0xbfb8aa3b, v63
	v_exp_f32_e32 v110, v110
	v_add_f32_e32 v74, 1.0, v79
	v_rcp_f32_e32 v76, v74
	v_mov_b32_e32 v75, v61
	v_add_f32_e32 v74, 1.0, v110
	v_rcp_f32_e32 v77, v74
	v_mov_b32_e32 v74, v109
	v_pk_mul_f32 v[74:75], v[74:75], v[78:79] op_sel_hi:[1,0]
	v_mov_b32_e32 v109, v60
	v_mul_f32_e32 v61, 0xbfb8aa3b, v75
	v_exp_f32_e32 v61, v61
	v_mul_f32_e32 v63, v63, v77
	v_mul_f32_e32 v76, v121, v76
	v_mul_f32_e32 v76, v120, v76
	v_add_f32_e32 v61, 1.0, v61
	v_rcp_f32_e32 v77, v61
	v_pk_mul_f32 v[60:61], v[108:109], v[78:79] op_sel_hi:[1,0]
	v_mul_f32_e32 v108, v62, v63
	v_mul_f32_e32 v79, 0xbfb8aa3b, v61
	v_exp_f32_e32 v79, v79
	v_mul_f32_e32 v62, v75, v77
	v_mul_f32_e32 v74, v74, v62
	v_mov_b32_e32 v63, v71
	v_add_f32_e32 v62, 1.0, v79
	v_rcp_f32_e32 v75, v62
	v_mov_b32_e32 v62, v115
	v_pk_mul_f32 v[62:63], v[62:63], v[78:79] op_sel_hi:[1,0]
	v_mov_b32_e32 v115, v70
	v_mul_f32_e32 v71, 0xbfb8aa3b, v63
	v_exp_f32_e32 v71, v71
	v_mul_f32_e32 v61, v61, v75
	v_mul_f32_e32 v60, v60, v61
	v_cvt_pk_bf16_f32 v60, v60, v74
	v_add_f32_e32 v61, 1.0, v71
	v_pk_mul_f32 v[70:71], v[114:115], v[78:79] op_sel_hi:[1,0]
	v_rcp_f32_e32 v74, v61
	v_mul_f32_e32 v61, 0xbfb8aa3b, v71
	v_exp_f32_e32 v75, v61
	v_cvt_pk_bf16_f32 v61, v108, v76
	v_mul_f32_e32 v63, v63, v74
	v_mul_f32_e32 v74, v62, v63
	v_add_f32_e32 v62, 1.0, v75
	v_rcp_f32_e32 v75, v62
	v_mov_b32_e32 v62, v113
	v_mov_b32_e32 v63, v69
	v_pk_mul_f32 v[62:63], v[62:63], v[78:79] op_sel_hi:[1,0]
	v_mov_b32_e32 v113, v68
	v_mul_f32_e32 v69, 0xbfb8aa3b, v63
	v_exp_f32_e32 v76, v69
	v_pk_mul_f32 v[68:69], v[112:113], v[78:79] op_sel_hi:[1,0]
	v_mul_f32_e32 v71, v71, v75
	v_mul_f32_e32 v77, 0xbfb8aa3b, v69
	v_exp_f32_e32 v77, v77
	v_add_f32_e32 v75, 1.0, v76
	v_rcp_f32_e32 v75, v75
	v_mul_f32_e32 v70, v70, v71
	v_add_f32_e32 v76, 1.0, v77
	v_rcp_f32_e32 v76, v76
	v_mul_f32_e32 v63, v63, v75
	v_mul_f32_e32 v62, v62, v63
	v_mul_f32_e32 v63, v69, v76
	s_waitcnt vmcnt(6)
	v_fmamk_f32 v69, v180, 0x3a800000, v169
	v_mul_f32_e32 v71, 0x4b800000, v69
	v_cmp_gt_f32_e32 vcc, s18, v69
	v_mul_f32_e32 v63, v68, v63
	v_cvt_pk_bf16_f32 v62, v63, v62
	v_cvt_pk_bf16_f32 v63, v70, v74
	v_mov_b32_e32 v70, v119
	v_cndmask_b32_e32 v69, v69, v71, vcc
	v_rsq_f32_e32 v69, v69
	v_mov_b32_e32 v71, v107
	v_mov_b32_e32 v119, v106
	global_store_dwordx4 v[72:73], v[60:63], off offset:2048
	s_branch .LBB0_1741
; __device__ __forceinline__ unsigned cvt_pk_bf16(float lo, float hi) { unsigned r; asm volatile("v_cvt_pk_bf16_f32 %0, %1, %2" : "=v"(r) : "v"(lo), "v"(hi)); return r; }
; __device__ __forceinline__ float fast_sigmoid(float a) { return __builtin_amdgcn_rcpf(1.0f + __expf(-a)); }
;     __device__ __forceinline__ void operator()(const Acc& acc, const Unit& u, int wr, int wc, int fr, int fq) const {
;     ...
; #pragma unroll
;         for (int ai = 0; ai < 2; ++ai)
; #pragma unroll
;             for (int m = 0; m < 4; ++m) {
;                 const int row = u.pm * 256 + ai * 128 + wr * 64 + m * 16 + fr;
;                 const float rs = rsqrtf(ssv[ai][m] * (1.0f / DM) + EPS);
;                 bf16_t* dst = act + ((size_t)((row >> 8) * (DFF / 64) + u.pn * 2 + (wc >> 1)) * 256 + (row & 255)) * 64 + (wc & 1) * 32 + fq * 8;
;                 u32x4 w;
; #pragma unroll
;                 for (int n = 0; n < 2; ++n) {
;                     const f32x4 a = acc[ai][0][m][n] * rs, b = acc[ai][1][m][n] * rs; f32x4 v;
; #pragma unroll
;                     for (int j = 0; j < 4; ++j) v[j] = a[j] * fast_sigmoid(a[j]) * b[j];
;                     if (n == 0) { w.x = cvt_pk_bf16(v[0], v[1]); w.y = cvt_pk_bf16(v[2], v[3]); } else { w.z = cvt_pk_bf16(v[0], v[1]); w.w = cvt_pk_bf16(v[2], v[3]); }
;                 }
;                 *(u32x4*)dst = w;
;             }
	v_mul_f32_e32 v68, 0x45800000, v69
	v_cndmask_b32_e32 v68, v69, v68, vcc
	v_pk_mul_f32 v[70:71], v[70:71], v[68:69] op_sel_hi:[1,0]
	v_mov_b32_e32 v61, v105
	v_mul_f32_e32 v69, 0xbfb8aa3b, v71
	v_exp_f32_e32 v69, v69
	s_nop 0
	v_pk_mul_f32 v[74:75], v[118:119], v[68:69] op_sel_hi:[1,0]
	s_nop 0
	v_mul_f32_e32 v76, 0xbfb8aa3b, v75
	v_exp_f32_e32 v76, v76
	v_add_f32_e32 v60, 1.0, v69
	v_rcp_f32_e32 v62, v60
	v_add_f32_e32 v60, 1.0, v76
	v_rcp_f32_e32 v63, v60
	v_mov_b32_e32 v60, v117
	v_pk_mul_f32 v[60:61], v[60:61], v[68:69] op_sel_hi:[1,0]
	v_mul_f32_e32 v62, v71, v62
	v_mul_f32_e32 v69, 0xbfb8aa3b, v61
	v_exp_f32_e32 v69, v69
	v_mul_f32_e32 v76, v70, v62
	v_mov_b32_e32 v117, v104
	v_mul_f32_e32 v70, v75, v63
	v_add_f32_e32 v62, 1.0, v69
	v_rcp_f32_e32 v69, v62
	v_mul_f32_e32 v74, v74, v70
	v_pk_mul_f32 v[62:63], v[116:117], v[68:69] op_sel_hi:[1,0]
	s_nop 0
	v_mul_f32_e32 v71, 0xbfb8aa3b, v63
	v_exp_f32_e32 v71, v71
	v_mul_f32_e32 v61, v61, v69
	v_mul_f32_e32 v69, v60, v61
	v_mov_b32_e32 v61, v99
	v_add_f32_e32 v60, 1.0, v71
	v_rcp_f32_e32 v75, v60
	v_mov_b32_e32 v60, v103
	v_pk_mul_f32 v[70:71], v[60:61], v[68:69] op_sel_hi:[1,0]
	v_mov_b32_e32 v103, v98
	v_mul_f32_e32 v60, 0xbfb8aa3b, v71
	v_exp_f32_e32 v61, v60
	v_mul_f32_e32 v60, v63, v75
	v_mul_f32_e32 v60, v62, v60
	v_cvt_pk_bf16_f32 v60, v60, v69
	v_add_f32_e32 v61, 1.0, v61
	v_rcp_f32_e32 v69, v61
	s_nop 0
	v_pk_mul_f32 v[62:63], v[102:103], v[68:69] op_sel_hi:[1,0]
	s_nop 0
	v_mul_f32_e32 v61, 0xbfb8aa3b, v63
	v_exp_f32_e32 v75, v61
	v_mul_f32_e32 v69, v71, v69
	v_cvt_pk_bf16_f32 v61, v74, v76
	v_mul_f32_e32 v74, v70, v69
	v_add_f32_e32 v69, 1.0, v75
	v_mov_b32_e32 v70, v101
	v_mov_b32_e32 v71, v97
	v_pk_mul_f32 v[70:71], v[70:71], v[68:69] op_sel_hi:[1,0]
	v_rcp_f32_e32 v75, v69
	v_mul_f32_e32 v69, 0xbfb8aa3b, v71
	v_mov_b32_e32 v101, v96
	v_exp_f32_e32 v76, v69
	v_pk_mul_f32 v[68:69], v[100:101], v[68:69] op_sel_hi:[1,0]
	v_mul_f32_e32 v63, v63, v75
	v_mul_f32_e32 v77, 0xbfb8aa3b, v69
	v_exp_f32_e32 v77, v77
	v_add_f32_e32 v75, 1.0, v76
	v_rcp_f32_e32 v75, v75
	v_mul_f32_e32 v63, v62, v63
	v_add_f32_e32 v76, 1.0, v77
	v_rcp_f32_e32 v76, v76
	v_mul_f32_e32 v62, v71, v75
	v_mul_f32_e32 v62, v70, v62
	v_mov_b32_e32 v75, v91
	v_mul_f32_e32 v69, v69, v76
	v_mul_f32_e32 v68, v68, v69
	v_cvt_pk_bf16_f32 v62, v68, v62
	s_waitcnt vmcnt(6)
	v_fmamk_f32 v68, v181, 0x3a800000, v169
	v_mul_f32_e32 v69, 0x4b800000, v68
	v_cmp_gt_f32_e32 vcc, s18, v68
	v_cvt_pk_bf16_f32 v63, v63, v74
	v_mov_b32_e32 v74, v95
	v_mov_b32_e32 v95, v90
	v_cndmask_b32_e32 v68, v68, v69, vcc
	v_rsq_f32_e32 v70, v68
	v_add_co_u32_e64 v68, s[0:1], s19, v72
	v_mul_f32_e32 v71, 0x45800000, v70
	v_cndmask_b32_e32 v70, v70, v71, vcc
	v_pk_mul_f32 v[74:75], v[74:75], v[70:71] op_sel_hi:[1,0]
	v_addc_co_u32_e64 v69, s[0:1], 0, v73, s[0:1]
	v_mul_f32_e32 v71, 0xbfb8aa3b, v75
	v_exp_f32_e32 v71, v71
	global_store_dwordx4 v[68:69], v[60:63], off
	v_pk_mul_f32 v[76:77], v[94:95], v[70:71] op_sel_hi:[1,0]
	s_nop 0
	v_mul_f32_e32 v78, 0xbfb8aa3b, v77
	v_exp_f32_e32 v78, v78
	v_add_f32_e32 v60, 1.0, v71
	v_rcp_f32_e32 v62, v60
	v_mov_b32_e32 v61, v89
	v_add_f32_e32 v60, 1.0, v78
	v_rcp_f32_e32 v63, v60
	v_mov_b32_e32 v60, v93
	v_pk_mul_f32 v[60:61], v[60:61], v[70:71] op_sel_hi:[1,0]
	v_mul_f32_e32 v62, v75, v62
	v_mul_f32_e32 v71, 0xbfb8aa3b, v61
	v_exp_f32_e32 v71, v71
	v_mul_f32_e32 v78, v74, v62
	v_mov_b32_e32 v93, v88
	v_mul_f32_e32 v74, v77, v63
	v_add_f32_e32 v62, 1.0, v71
	v_rcp_f32_e32 v71, v62
	v_mul_f32_e32 v76, v76, v74
	v_pk_mul_f32 v[62:63], v[92:93], v[70:71] op_sel_hi:[1,0]
	s_nop 0
	v_mul_f32_e32 v75, 0xbfb8aa3b, v63
	v_exp_f32_e32 v75, v75
	v_mul_f32_e32 v61, v61, v71
	v_mul_f32_e32 v71, v60, v61
	v_mov_b32_e32 v61, v83
	v_add_f32_e32 v60, 1.0, v75
	v_rcp_f32_e32 v77, v60
	v_mov_b32_e32 v60, v87
	v_pk_mul_f32 v[74:75], v[60:61], v[70:71] op_sel_hi:[1,0]
	v_mov_b32_e32 v87, v82
	v_mul_f32_e32 v60, 0xbfb8aa3b, v75
	v_exp_f32_e32 v61, v60
	v_mul_f32_e32 v60, v63, v77
	v_mul_f32_e32 v60, v62, v60
	v_cvt_pk_bf16_f32 v60, v60, v71
	v_add_f32_e32 v61, 1.0, v61
	v_rcp_f32_e32 v71, v61
	s_nop 0
	v_pk_mul_f32 v[62:63], v[86:87], v[70:71] op_sel_hi:[1,0]
	s_nop 0
	v_mul_f32_e32 v61, 0xbfb8aa3b, v63
	v_exp_f32_e32 v77, v61
	v_mul_f32_e32 v71, v75, v71
	v_cvt_pk_bf16_f32 v61, v76, v78
	v_mul_f32_e32 v76, v74, v71
	v_add_f32_e32 v71, 1.0, v77
	v_mov_b32_e32 v74, v85
	v_mov_b32_e32 v75, v81
	v_pk_mul_f32 v[74:75], v[74:75], v[70:71] op_sel_hi:[1,0]
	v_rcp_f32_e32 v77, v71
	v_mul_f32_e32 v71, 0xbfb8aa3b, v75
	v_exp_f32_e32 v78, v71
	v_mov_b32_e32 v85, v80
	v_pk_mul_f32 v[70:71], v[84:85], v[70:71] op_sel_hi:[1,0]
	v_mul_f32_e32 v63, v63, v77
	v_add_f32_e32 v77, 1.0, v78
	v_mul_f32_e32 v79, 0xbfb8aa3b, v71
	v_rcp_f32_e32 v77, v77
	v_exp_f32_e32 v79, v79
	v_mul_f32_e32 v63, v62, v63
	v_mul_f32_e32 v62, v75, v77
	v_add_f32_e32 v78, 1.0, v79
	v_mul_f32_e32 v62, v74, v62
	s_waitcnt vmcnt(6)
; __device__ __forceinline__ unsigned cvt_pk_bf16(float lo, float hi) { unsigned r; asm volatile("v_cvt_pk_bf16_f32 %0, %1, %2" : "=v"(r) : "v"(lo), "v"(hi)); return r; }
; __device__ __forceinline__ float fast_sigmoid(float a) { return __builtin_amdgcn_rcpf(1.0f + __expf(-a)); }
;     __device__ __forceinline__ void operator()(const Acc& acc, const Unit& u, int wr, int wc, int fr, int fq) const {
;     ...
; #pragma unroll
;         for (int ai = 0; ai < 2; ++ai)
; #pragma unroll
;             for (int m = 0; m < 4; ++m) {
;                 const int row = u.pm * 256 + ai * 128 + wr * 64 + m * 16 + fr;
;                 const float rs = rsqrtf(ssv[ai][m] * (1.0f / DM) + EPS);
;                 bf16_t* dst = act + ((size_t)((row >> 8) * (DFF / 64) + u.pn * 2 + (wc >> 1)) * 256 + (row & 255)) * 64 + (wc & 1) * 32 + fq * 8;
;                 u32x4 w;
; #pragma unroll
;                 for (int n = 0; n < 2; ++n) {
;                     const f32x4 a = acc[ai][0][m][n] * rs, b = acc[ai][1][m][n] * rs; f32x4 v;
; #pragma unroll
;                     for (int j = 0; j < 4; ++j) v[j] = a[j] * fast_sigmoid(a[j]) * b[j];
;                     if (n == 0) { w.x = cvt_pk_bf16(v[0], v[1]); w.y = cvt_pk_bf16(v[2], v[3]); } else { w.z = cvt_pk_bf16(v[0], v[1]); w.w = cvt_pk_bf16(v[2], v[3]); }
;                 }
;                 *(u32x4*)dst = w;
;             }
	v_fmamk_f32 v74, v173, 0x3a800000, v169
	v_rcp_f32_e32 v78, v78
	v_mul_f32_e32 v75, 0x4b800000, v74
	v_cmp_gt_f32_e32 vcc, s18, v74
	v_mul_f32_e32 v71, v71, v78
	s_nop 0
	v_cndmask_b32_e32 v74, v74, v75, vcc
	v_rsq_f32_e32 v74, v74
	v_mul_f32_e32 v70, v70, v71
	v_cvt_pk_bf16_f32 v62, v70, v62
	v_mov_b32_e32 v75, v59
	v_mul_f32_e32 v70, 0x45800000, v74
	v_cndmask_b32_e32 v70, v74, v70, vcc
	v_mov_b32_e32 v74, v67
	v_pk_mul_f32 v[74:75], v[74:75], v[70:71] op_sel_hi:[1,0]
	v_mov_b32_e32 v67, v58
	v_mul_f32_e32 v59, 0xbfb8aa3b, v75
	v_exp_f32_e32 v71, v59
	v_cvt_pk_bf16_f32 v63, v63, v76
	global_store_dwordx4 v[68:69], v[60:63], off offset:2048
	v_pk_mul_f32 v[58:59], v[66:67], v[70:71] op_sel_hi:[1,0]
	s_nop 0
	v_mul_f32_e32 v66, 0xbfb8aa3b, v59
	v_exp_f32_e32 v66, v66
	v_add_f32_e32 v60, 1.0, v71
	v_rcp_f32_e32 v62, v60
	v_mov_b32_e32 v61, v57
	v_add_f32_e32 v60, 1.0, v66
	v_rcp_f32_e32 v63, v60
	v_mov_b32_e32 v60, v65
	v_pk_mul_f32 v[60:61], v[60:61], v[70:71] op_sel_hi:[1,0]
	v_mov_b32_e32 v65, v56
	v_mul_f32_e32 v57, 0xbfb8aa3b, v61
	v_exp_f32_e32 v57, v57
	v_mul_f32_e32 v59, v59, v63
	v_mul_f32_e32 v62, v75, v62
	v_mul_f32_e32 v62, v74, v62
	v_add_f32_e32 v57, 1.0, v57
	v_rcp_f32_e32 v63, v57
	v_pk_mul_f32 v[56:57], v[64:65], v[70:71] op_sel_hi:[1,0]
	v_mul_f32_e32 v65, v58, v59
	v_mul_f32_e32 v64, 0xbfb8aa3b, v57
	v_exp_f32_e32 v64, v64
	v_mul_f32_e32 v58, v61, v63
	v_mul_f32_e32 v60, v60, v58
	v_mov_b32_e32 v59, v51
	v_add_f32_e32 v58, 1.0, v64
	v_rcp_f32_e32 v61, v58
	v_mov_b32_e32 v58, v55
	v_pk_mul_f32 v[58:59], v[58:59], v[70:71] op_sel_hi:[1,0]
	v_mul_f32_e32 v55, v57, v61
	v_mul_f32_e32 v51, 0xbfb8aa3b, v59
	v_exp_f32_e32 v51, v51
	v_mul_f32_e32 v55, v56, v55
	v_cvt_pk_bf16_f32 v56, v55, v60
	v_mov_b32_e32 v55, v50
	v_add_f32_e32 v51, 1.0, v51
	v_rcp_f32_e32 v60, v51
	v_pk_mul_f32 v[50:51], v[54:55], v[70:71] op_sel_hi:[1,0]
	v_cvt_pk_bf16_f32 v57, v65, v62
	v_mul_f32_e32 v55, v59, v60
	v_mul_f32_e32 v54, 0xbfb8aa3b, v51
	v_exp_f32_e32 v54, v54
	v_mul_f32_e32 v59, v58, v55
	v_mov_b32_e32 v55, v49
	v_add_f32_e32 v54, 1.0, v54
	v_rcp_f32_e32 v58, v54
	v_mov_b32_e32 v54, v53
	v_pk_mul_f32 v[54:55], v[54:55], v[70:71] op_sel_hi:[1,0]
	v_mov_b32_e32 v53, v48
	v_mul_f32_e32 v49, 0xbfb8aa3b, v55
	v_exp_f32_e32 v60, v49
	v_pk_mul_f32 v[48:49], v[52:53], v[70:71] op_sel_hi:[1,0]
	v_mul_f32_e32 v51, v51, v58
	v_mul_f32_e32 v52, 0xbfb8aa3b, v49
	v_exp_f32_e32 v52, v52
	v_add_f32_e32 v53, 1.0, v60
	v_rcp_f32_e32 v53, v53
	v_mul_f32_e32 v50, v50, v51
	v_add_f32_e32 v52, 1.0, v52
	v_rcp_f32_e32 v52, v52
	v_mul_f32_e32 v51, v55, v53
	v_mul_f32_e32 v51, v54, v51
	v_mov_b32_e32 v54, v47
	v_mul_f32_e32 v49, v49, v52
	v_mul_f32_e32 v48, v48, v49
	v_cvt_pk_bf16_f32 v58, v48, v51
	v_cvt_pk_bf16_f32 v59, v50, v59
	v_add_co_u32_e32 v50, vcc, s20, v72
	s_waitcnt vmcnt(6)
	v_fmamk_f32 v48, v172, 0x3a800000, v169
	v_addc_co_u32_e32 v51, vcc, 0, v73, vcc
	v_mul_f32_e32 v49, 0x4b800000, v48
	v_cmp_gt_f32_e32 vcc, s18, v48
	v_mov_b32_e32 v55, v43
	v_mov_b32_e32 v47, v42
	v_cndmask_b32_e32 v48, v48, v49, vcc
	v_rsq_f32_e32 v52, v48
	v_add_co_u32_e64 v48, s[0:1], s21, v72
	v_mul_f32_e32 v53, 0x45800000, v52
	v_cndmask_b32_e32 v52, v52, v53, vcc
	v_pk_mul_f32 v[54:55], v[54:55], v[52:53] op_sel_hi:[1,0]
	v_addc_co_u32_e64 v49, s[0:1], 0, v73, s[0:1]
	v_mul_f32_e32 v43, 0xbfb8aa3b, v55
	v_exp_f32_e32 v53, v43
	global_store_dwordx4 v[48:49], v[56:59], off offset:-4096
	v_pk_mul_f32 v[42:43], v[46:47], v[52:53] op_sel_hi:[1,0]
	s_nop 0
	v_mul_f32_e32 v46, 0xbfb8aa3b, v43
	v_exp_f32_e32 v46, v46
	v_add_f32_e32 v47, 1.0, v53
	v_rcp_f32_e32 v53, v47
	v_mov_b32_e32 v47, v41
	v_add_f32_e32 v46, 1.0, v46
	v_rcp_f32_e32 v56, v46
	v_mov_b32_e32 v46, v45
	v_pk_mul_f32 v[46:47], v[46:47], v[52:53] op_sel_hi:[1,0]
	v_mul_f32_e32 v45, v55, v53
	v_mul_f32_e32 v41, 0xbfb8aa3b, v47
	v_exp_f32_e32 v41, v41
	v_mul_f32_e32 v53, v54, v45
	v_mov_b32_e32 v45, v40
	v_mul_f32_e32 v43, v43, v56
	v_add_f32_e32 v41, 1.0, v41
	v_rcp_f32_e32 v54, v41
	v_pk_mul_f32 v[40:41], v[44:45], v[52:53] op_sel_hi:[1,0]
	v_mul_f32_e32 v45, v42, v43
	v_mul_f32_e32 v44, 0xbfb8aa3b, v41
	v_exp_f32_e32 v44, v44
	v_mul_f32_e32 v42, v47, v54
	v_mul_f32_e32 v46, v46, v42
	v_mov_b32_e32 v43, v35
	v_add_f32_e32 v42, 1.0, v44
	v_rcp_f32_e32 v44, v42
	v_mov_b32_e32 v42, v39
	v_pk_mul_f32 v[42:43], v[42:43], v[52:53] op_sel_hi:[1,0]
	v_mul_f32_e32 v39, v41, v44
	v_mul_f32_e32 v35, 0xbfb8aa3b, v43
	v_exp_f32_e32 v35, v35
	v_mul_f32_e32 v39, v40, v39
	v_cvt_pk_bf16_f32 v40, v39, v46
	v_mov_b32_e32 v39, v34
	v_add_f32_e32 v35, 1.0, v35
	v_rcp_f32_e32 v44, v35
	v_pk_mul_f32 v[34:35], v[38:39], v[52:53] op_sel_hi:[1,0]
	v_cvt_pk_bf16_f32 v41, v45, v53
	v_mul_f32_e32 v39, v43, v44
	v_mul_f32_e32 v38, 0xbfb8aa3b, v35
	v_exp_f32_e32 v38, v38
	v_mul_f32_e32 v43, v42, v39
	v_mov_b32_e32 v39, v33
	v_add_f32_e32 v38, 1.0, v38
	v_rcp_f32_e32 v42, v38
	v_mov_b32_e32 v38, v37
	v_pk_mul_f32 v[38:39], v[38:39], v[52:53] op_sel_hi:[1,0]
	v_mov_b32_e32 v37, v32
	v_mul_f32_e32 v33, 0xbfb8aa3b, v39
	v_exp_f32_e32 v44, v33
	v_pk_mul_f32 v[32:33], v[36:37], v[52:53] op_sel_hi:[1,0]
	v_mul_f32_e32 v35, v35, v42
	v_mul_f32_e32 v36, 0xbfb8aa3b, v33
	v_exp_f32_e32 v36, v36
	v_add_f32_e32 v37, 1.0, v44
	v_rcp_f32_e32 v37, v37
	v_mul_f32_e32 v34, v34, v35
	v_add_f32_e32 v36, 1.0, v36
	v_rcp_f32_e32 v36, v36
	v_mul_f32_e32 v35, v39, v37
	v_mul_f32_e32 v35, v38, v35
	v_mul_f32_e32 v33, v33, v36
	s_waitcnt vmcnt(6)
; __device__ __forceinline__ unsigned cvt_pk_bf16(float lo, float hi) { unsigned r; asm volatile("v_cvt_pk_bf16_f32 %0, %1, %2" : "=v"(r) : "v"(lo), "v"(hi)); return r; }
; __device__ __forceinline__ float fast_sigmoid(float a) { return __builtin_amdgcn_rcpf(1.0f + __expf(-a)); }
;     __device__ __forceinline__ void operator()(const Acc& acc, const Unit& u, int wr, int wc, int fr, int fq) const {
;     ...
; #pragma unroll
;         for (int ai = 0; ai < 2; ++ai)
; #pragma unroll
;             for (int m = 0; m < 4; ++m) {
;                 const int row = u.pm * 256 + ai * 128 + wr * 64 + m * 16 + fr;
;                 const float rs = rsqrtf(ssv[ai][m] * (1.0f / DM) + EPS);
;                 bf16_t* dst = act + ((size_t)((row >> 8) * (DFF / 64) + u.pn * 2 + (wc >> 1)) * 256 + (row & 255)) * 64 + (wc & 1) * 32 + fq * 8;
;                 u32x4 w;
; #pragma unroll
;                 for (int n = 0; n < 2; ++n) {
;                     const f32x4 a = acc[ai][0][m][n] * rs, b = acc[ai][1][m][n] * rs; f32x4 v;
; #pragma unroll
;                     for (int j = 0; j < 4; ++j) v[j] = a[j] * fast_sigmoid(a[j]) * b[j];
;                     if (n == 0) { w.x = cvt_pk_bf16(v[0], v[1]); w.y = cvt_pk_bf16(v[2], v[3]); } else { w.z = cvt_pk_bf16(v[0], v[1]); w.w = cvt_pk_bf16(v[2], v[3]); }
;                 }
;                 *(u32x4*)dst = w;
;             }
	v_fmamk_f32 v36, v171, 0x3a800000, v169
	v_mul_f32_e32 v37, 0x4b800000, v36
	v_cmp_gt_f32_e32 vcc, s18, v36
	v_mul_f32_e32 v32, v32, v33
	v_cvt_pk_bf16_f32 v42, v32, v35
	v_cvt_pk_bf16_f32 v43, v34, v43
	v_mov_b32_e32 v34, v31
	v_cndmask_b32_e32 v36, v36, v37, vcc
	v_rsq_f32_e32 v36, v36
	v_mov_b32_e32 v35, v27
	v_mov_b32_e32 v31, v26
	global_store_dwordx4 v[50:51], v[40:43], off offset:2048
	v_mul_f32_e32 v32, 0x45800000, v36
	v_cndmask_b32_e32 v32, v36, v32, vcc
	v_pk_mul_f32 v[34:35], v[34:35], v[32:33] op_sel_hi:[1,0]
	s_nop 0
	v_mul_f32_e32 v27, 0xbfb8aa3b, v35
	v_exp_f32_e32 v33, v27
	s_nop 0
	v_pk_mul_f32 v[26:27], v[30:31], v[32:33] op_sel_hi:[1,0]
	s_nop 0
	v_mul_f32_e32 v30, 0xbfb8aa3b, v27
	v_exp_f32_e32 v30, v30
	v_add_f32_e32 v31, 1.0, v33
	v_rcp_f32_e32 v33, v31
	v_mov_b32_e32 v31, v25
	v_add_f32_e32 v30, 1.0, v30
	v_rcp_f32_e32 v36, v30
	v_mov_b32_e32 v30, v29
	v_pk_mul_f32 v[30:31], v[30:31], v[32:33] op_sel_hi:[1,0]
	v_mul_f32_e32 v29, v35, v33
	v_mul_f32_e32 v25, 0xbfb8aa3b, v31
	v_exp_f32_e32 v25, v25
	v_mul_f32_e32 v33, v34, v29
	v_mov_b32_e32 v29, v24
	v_mul_f32_e32 v27, v27, v36
	v_add_f32_e32 v25, 1.0, v25
	v_rcp_f32_e32 v34, v25
	v_pk_mul_f32 v[24:25], v[28:29], v[32:33] op_sel_hi:[1,0]
	v_mul_f32_e32 v29, v26, v27
	v_mul_f32_e32 v28, 0xbfb8aa3b, v25
	v_exp_f32_e32 v28, v28
	v_mul_f32_e32 v26, v31, v34
	v_mul_f32_e32 v30, v30, v26
	v_mov_b32_e32 v27, v19
	v_add_f32_e32 v26, 1.0, v28
	v_rcp_f32_e32 v28, v26
	v_mov_b32_e32 v26, v23
	v_pk_mul_f32 v[26:27], v[26:27], v[32:33] op_sel_hi:[1,0]
	v_mul_f32_e32 v23, v25, v28
	v_mul_f32_e32 v19, 0xbfb8aa3b, v27
	v_exp_f32_e32 v19, v19
	v_mul_f32_e32 v23, v24, v23
	v_cvt_pk_bf16_f32 v24, v23, v30
	v_mov_b32_e32 v23, v18
	v_add_f32_e32 v19, 1.0, v19
	v_rcp_f32_e32 v28, v19
	v_pk_mul_f32 v[18:19], v[22:23], v[32:33] op_sel_hi:[1,0]
	v_cvt_pk_bf16_f32 v25, v29, v33
	v_mul_f32_e32 v23, v27, v28
	v_mul_f32_e32 v22, 0xbfb8aa3b, v19
	v_exp_f32_e32 v22, v22
	v_mul_f32_e32 v27, v26, v23
	v_mov_b32_e32 v23, v17
	v_add_f32_e32 v22, 1.0, v22
	v_rcp_f32_e32 v26, v22
	v_mov_b32_e32 v22, v21
	v_pk_mul_f32 v[22:23], v[22:23], v[32:33] op_sel_hi:[1,0]
	v_mov_b32_e32 v21, v16
	v_mul_f32_e32 v17, 0xbfb8aa3b, v23
	v_exp_f32_e32 v28, v17
	v_pk_mul_f32 v[16:17], v[20:21], v[32:33] op_sel_hi:[1,0]
	v_mul_f32_e32 v19, v19, v26
	v_mul_f32_e32 v20, 0xbfb8aa3b, v17
	v_exp_f32_e32 v20, v20
	v_add_f32_e32 v21, 1.0, v28
	v_rcp_f32_e32 v21, v21
	v_mul_f32_e32 v18, v18, v19
	v_add_f32_e32 v20, 1.0, v20
	v_rcp_f32_e32 v20, v20
	v_mul_f32_e32 v19, v23, v21
	v_mul_f32_e32 v19, v22, v19
	v_mul_f32_e32 v17, v17, v20
	s_waitcnt vmcnt(6)
	v_fmamk_f32 v20, v170, 0x3a800000, v169
	v_mul_f32_e32 v21, 0x4b800000, v20
	v_cmp_gt_f32_e32 vcc, s18, v20
	v_mul_f32_e32 v16, v16, v17
	v_cvt_pk_bf16_f32 v26, v16, v19
	v_cvt_pk_bf16_f32 v27, v18, v27
	v_mov_b32_e32 v18, v15
	v_cndmask_b32_e32 v20, v20, v21, vcc
	v_rsq_f32_e32 v20, v20
	v_mov_b32_e32 v19, v11
	v_mov_b32_e32 v15, v10
	global_store_dwordx4 v[48:49], v[24:27], off
	v_mul_f32_e32 v16, 0x45800000, v20
	v_cndmask_b32_e32 v16, v20, v16, vcc
	v_pk_mul_f32 v[18:19], v[18:19], v[16:17] op_sel_hi:[1,0]
	s_nop 0
	v_mul_f32_e32 v11, 0xbfb8aa3b, v19
	v_exp_f32_e32 v17, v11
	s_nop 0
	v_pk_mul_f32 v[10:11], v[14:15], v[16:17] op_sel_hi:[1,0]
	s_nop 0
	v_mul_f32_e32 v14, 0xbfb8aa3b, v11
	v_exp_f32_e32 v14, v14
	v_add_f32_e32 v15, 1.0, v17
	v_rcp_f32_e32 v17, v15
	v_mov_b32_e32 v15, v9
	v_add_f32_e32 v14, 1.0, v14
	v_rcp_f32_e32 v20, v14
	v_mov_b32_e32 v14, v13
	v_pk_mul_f32 v[14:15], v[14:15], v[16:17] op_sel_hi:[1,0]
	v_mul_f32_e32 v13, v19, v17
	v_mul_f32_e32 v9, 0xbfb8aa3b, v15
	v_exp_f32_e32 v9, v9
	v_mul_f32_e32 v17, v18, v13
	v_mov_b32_e32 v13, v8
	v_mul_f32_e32 v11, v11, v20
	v_add_f32_e32 v9, 1.0, v9
	v_rcp_f32_e32 v18, v9
	v_pk_mul_f32 v[8:9], v[12:13], v[16:17] op_sel_hi:[1,0]
	v_mul_f32_e32 v13, v10, v11
	v_mul_f32_e32 v12, 0xbfb8aa3b, v9
	v_exp_f32_e32 v12, v12
	v_mul_f32_e32 v10, v15, v18
	v_mul_f32_e32 v14, v14, v10
	v_mov_b32_e32 v11, v7
	v_add_f32_e32 v10, 1.0, v12
	v_rcp_f32_e32 v12, v10
	v_mov_b32_e32 v10, v3
	v_pk_mul_f32 v[10:11], v[10:11], v[16:17] op_sel_hi:[1,0]
	v_mul_f32_e32 v7, v9, v12
	v_mul_f32_e32 v3, 0xbfb8aa3b, v11
	v_exp_f32_e32 v3, v3
	v_mul_f32_e32 v7, v8, v7
	v_cvt_pk_bf16_f32 v8, v7, v14
	v_cvt_pk_bf16_f32 v9, v13, v17
	v_add_f32_e32 v3, 1.0, v3
	v_rcp_f32_e32 v7, v3
	v_mov_b32_e32 v3, v6
	v_pk_mul_f32 v[2:3], v[2:3], v[16:17] op_sel_hi:[1,0]
	v_mul_f32_e32 v7, v11, v7
	v_mul_f32_e32 v6, 0xbfb8aa3b, v3
	v_exp_f32_e32 v6, v6
	v_mul_f32_e32 v11, v10, v7
	v_mov_b32_e32 v7, v5
	v_add_f32_e32 v6, 1.0, v6
	v_rcp_f32_e32 v10, v6
	v_mov_b32_e32 v6, v1
	v_pk_mul_f32 v[6:7], v[6:7], v[16:17] op_sel_hi:[1,0]
	v_mul_f32_e32 v3, v3, v10
	v_mul_f32_e32 v1, 0xbfb8aa3b, v7
	v_exp_f32_e32 v5, v1
	v_mov_b32_e32 v1, v4
	v_pk_mul_f32 v[0:1], v[0:1], v[16:17] op_sel_hi:[1,0]
	v_mul_f32_e32 v2, v2, v3
	v_mul_f32_e32 v4, 0xbfb8aa3b, v1
	v_exp_f32_e32 v4, v4
	v_add_f32_e32 v5, 1.0, v5
	v_rcp_f32_e32 v5, v5
	v_add_f32_e32 v4, 1.0, v4
	v_rcp_f32_e32 v4, v4
	v_mul_f32_e32 v3, v7, v5
	v_mul_f32_e32 v3, v6, v3
	v_mul_f32_e32 v1, v1, v4
	v_mul_f32_e32 v0, v0, v1
	v_cvt_pk_bf16_f32 v10, v0, v3
	v_cvt_pk_bf16_f32 v11, v2, v11
	global_store_dwordx4 v[48:49], v[8:11], off offset:2048
	s_branch .LBB0_1741
